# v55 + removed the redundant s_waitcnt lgkmcnt(0) at the start of each GEMM compute segment (48 sites; the same wait already sits before the barrier)
# baseline (speedup 1.0000x reference)
.LBB0_153:
	ds_read_b128 v[146:149], v153
	ds_read_b128 v[156:159], v153 offset:1024
	ds_read_b128 v[160:163], v153 offset:2048
	ds_read_b128 v[164:167], v153 offset:3072
	ds_read_b128 v[168:171], v154
	ds_read_b128 v[172:175], v154 offset:1024
	ds_read_b128 v[176:179], v154 offset:2048
	ds_read_b128 v[180:183], v154 offset:3072
	s_add_u32 s42, s40, 0xfff80080
	s_addc_u32 s43, s41, -1
	s_cmp_eq_u32 s60, 28
	s_cselect_b32 s45, s2, s43
	s_cselect_b32 s44, s3, s42
	s_cselect_b32 s43, s29, s59
	s_cselect_b32 s42, s31, s58
	v_lshl_add_u64 v[218:219], s[40:41], 0, v[138:139]
	s_add_i32 m0, s39, 0xc000
	ds_read_b128 v[184:187], v155
	ds_read_b128 v[188:191], v155 offset:1024
	ds_read_b128 v[192:195], v155 offset:2048
	ds_read_b128 v[196:199], v155 offset:3072
	ds_read_b128 v[200:203], v155 offset:4096
	ds_read_b128 v[204:207], v155 offset:5120
	ds_read_b128 v[210:213], v155 offset:6144
	ds_read_b128 v[214:217], v155 offset:7168
	global_load_lds_dwordx4 v[218:219], off
	v_lshl_add_u64 v[218:219], s[40:41], 0, v[140:141]
	s_add_i32 m0, s39, 0xe000
	s_nop 0
	global_load_lds_dwordx4 v[218:219], off
	s_waitcnt vmcnt(8)
	s_waitcnt lgkmcnt(0)
	s_barrier
	s_setprio 1
	v_mfma_f32_16x16x32_bf16 v[124:127], v[146:149], v[184:187], v[124:127]
	v_mfma_f32_16x16x32_bf16 v[120:123], v[160:163], v[184:187], v[120:123]
	v_mfma_f32_16x16x32_bf16 v[116:119], v[146:149], v[192:195], v[116:119]
	v_mfma_f32_16x16x32_bf16 v[108:111], v[160:163], v[192:195], v[108:111]
	v_mfma_f32_16x16x32_bf16 v[100:103], v[146:149], v[200:203], v[100:103]
	v_mfma_f32_16x16x32_bf16 v[92:95], v[160:163], v[200:203], v[92:95]
	v_mfma_f32_16x16x32_bf16 v[84:87], v[146:149], v[210:213], v[84:87]
	v_mfma_f32_16x16x32_bf16 v[76:79], v[160:163], v[210:213], v[76:79]
	v_mfma_f32_16x16x32_bf16 v[124:127], v[156:159], v[188:191], v[124:127]
	v_mfma_f32_16x16x32_bf16 v[120:123], v[164:167], v[188:191], v[120:123]
	v_mfma_f32_16x16x32_bf16 v[116:119], v[156:159], v[196:199], v[116:119]
	v_mfma_f32_16x16x32_bf16 v[108:111], v[164:167], v[196:199], v[108:111]
	v_mfma_f32_16x16x32_bf16 v[100:103], v[156:159], v[204:207], v[100:103]
	v_mfma_f32_16x16x32_bf16 v[92:95], v[164:167], v[204:207], v[92:95]
	v_mfma_f32_16x16x32_bf16 v[84:87], v[156:159], v[214:217], v[84:87]
	v_mfma_f32_16x16x32_bf16 v[76:79], v[164:167], v[214:217], v[76:79]
	v_mfma_f32_16x16x32_bf16 v[112:115], v[168:171], v[184:187], v[112:115]
	v_mfma_f32_16x16x32_bf16 v[104:107], v[176:179], v[184:187], v[104:107]
	v_mfma_f32_16x16x32_bf16 v[96:99], v[168:171], v[192:195], v[96:99]
	v_mfma_f32_16x16x32_bf16 v[88:91], v[176:179], v[192:195], v[88:91]
	v_mfma_f32_16x16x32_bf16 v[80:83], v[168:171], v[200:203], v[80:83]
	v_mfma_f32_16x16x32_bf16 v[72:75], v[176:179], v[200:203], v[72:75]
	v_mfma_f32_16x16x32_bf16 v[68:71], v[168:171], v[210:213], v[68:71]
	v_mfma_f32_16x16x32_bf16 v[64:67], v[176:179], v[210:213], v[64:67]
	v_mfma_f32_16x16x32_bf16 v[112:115], v[172:175], v[188:191], v[112:115]
	v_mfma_f32_16x16x32_bf16 v[104:107], v[180:183], v[188:191], v[104:107]
	v_mfma_f32_16x16x32_bf16 v[96:99], v[172:175], v[196:199], v[96:99]
	v_mfma_f32_16x16x32_bf16 v[88:91], v[180:183], v[196:199], v[88:91]
	v_mfma_f32_16x16x32_bf16 v[80:83], v[172:175], v[204:207], v[80:83]
	v_mfma_f32_16x16x32_bf16 v[72:75], v[180:183], v[204:207], v[72:75]
	v_mfma_f32_16x16x32_bf16 v[68:71], v[172:175], v[214:217], v[68:71]
	v_mfma_f32_16x16x32_bf16 v[64:67], v[180:183], v[214:217], v[64:67]
	s_setprio 0
	s_barrier
	s_add_i32 s61, s54, s93
	v_lshl_add_u64 v[218:219], s[42:43], 0, v[132:133]
	s_mov_b32 m0, s61
	ds_read_b128 v[184:187], v155 offset:16384
	ds_read_b128 v[188:191], v155 offset:17408
	ds_read_b128 v[192:195], v155 offset:18432
	ds_read_b128 v[196:199], v155 offset:19456
	ds_read_b128 v[200:203], v155 offset:20480
	ds_read_b128 v[204:207], v155 offset:21504
	ds_read_b128 v[210:213], v155 offset:22528
	ds_read_b128 v[214:217], v155 offset:23552
	global_load_lds_dwordx4 v[218:219], off
	s_add_i32 m0, s61, 0x2000
	s_add_u32 s62, s42, 0x80000
	v_lshl_add_u64 v[220:221], s[42:43], 0, v[128:129]
	s_addc_u32 s63, s43, 0
	s_add_i32 s61, s55, s93
	global_load_lds_dwordx4 v[220:221], off
	v_lshl_add_u64 v[222:223], s[62:63], 0, v[132:133]
	s_mov_b32 m0, s61
	v_lshl_add_u64 v[224:225], s[44:45], 0, v[130:131]
	global_load_lds_dwordx4 v[222:223], off
	v_lshl_add_u64 v[222:223], s[62:63], 0, v[128:129]
	s_add_i32 m0, s61, 0x2000
	s_nop 0
	global_load_lds_dwordx4 v[222:223], off
	v_lshl_add_u64 v[222:223], s[44:45], 0, v[134:135]
	s_mov_b32 m0, s39
	s_nop 0
	global_load_lds_dwordx4 v[222:223], off
	s_mov_b32 m0, s47
	s_nop 0
	global_load_lds_dwordx4 v[224:225], off
	s_waitcnt vmcnt(8)
	s_waitcnt lgkmcnt(0)
	s_barrier
	s_setprio 1
	v_mfma_f32_16x16x32_bf16 v[60:63], v[146:149], v[184:187], v[60:63]
	v_mfma_f32_16x16x32_bf16 v[56:59], v[160:163], v[184:187], v[56:59]
	v_mfma_f32_16x16x32_bf16 v[52:55], v[146:149], v[192:195], v[52:55]
	v_mfma_f32_16x16x32_bf16 v[44:47], v[160:163], v[192:195], v[44:47]
	v_mfma_f32_16x16x32_bf16 v[36:39], v[146:149], v[200:203], v[36:39]
	v_mfma_f32_16x16x32_bf16 v[28:31], v[160:163], v[200:203], v[28:31]
	v_mfma_f32_16x16x32_bf16 v[20:23], v[146:149], v[210:213], v[20:23]
	v_mfma_f32_16x16x32_bf16 v[12:15], v[160:163], v[210:213], v[12:15]
	v_mfma_f32_16x16x32_bf16 v[60:63], v[156:159], v[188:191], v[60:63]
	v_mfma_f32_16x16x32_bf16 v[56:59], v[164:167], v[188:191], v[56:59]
	v_mfma_f32_16x16x32_bf16 v[52:55], v[156:159], v[196:199], v[52:55]
	v_mfma_f32_16x16x32_bf16 v[44:47], v[164:167], v[196:199], v[44:47]
	v_mfma_f32_16x16x32_bf16 v[36:39], v[156:159], v[204:207], v[36:39]
	v_mfma_f32_16x16x32_bf16 v[28:31], v[164:167], v[204:207], v[28:31]
	v_mfma_f32_16x16x32_bf16 v[20:23], v[156:159], v[214:217], v[20:23]
	v_mfma_f32_16x16x32_bf16 v[12:15], v[164:167], v[214:217], v[12:15]
	v_mfma_f32_16x16x32_bf16 v[48:51], v[168:171], v[184:187], v[48:51]
	v_mfma_f32_16x16x32_bf16 v[40:43], v[176:179], v[184:187], v[40:43]
	v_mfma_f32_16x16x32_bf16 v[32:35], v[168:171], v[192:195], v[32:35]
	v_mfma_f32_16x16x32_bf16 v[24:27], v[176:179], v[192:195], v[24:27]
	v_mfma_f32_16x16x32_bf16 v[16:19], v[168:171], v[200:203], v[16:19]
	v_mfma_f32_16x16x32_bf16 v[8:11], v[176:179], v[200:203], v[8:11]
	v_mfma_f32_16x16x32_bf16 v[4:7], v[168:171], v[210:213], v[4:7]
	v_mfma_f32_16x16x32_bf16 v[0:3], v[176:179], v[210:213], v[0:3]
	v_mfma_f32_16x16x32_bf16 v[48:51], v[172:175], v[188:191], v[48:51]
	v_mfma_f32_16x16x32_bf16 v[40:43], v[180:183], v[188:191], v[40:43]
	v_mfma_f32_16x16x32_bf16 v[32:35], v[172:175], v[196:199], v[32:35]
	v_mfma_f32_16x16x32_bf16 v[24:27], v[180:183], v[196:199], v[24:27]
	v_mfma_f32_16x16x32_bf16 v[16:19], v[172:175], v[204:207], v[16:19]
	v_mfma_f32_16x16x32_bf16 v[8:11], v[180:183], v[204:207], v[8:11]
	v_mfma_f32_16x16x32_bf16 v[4:7], v[172:175], v[214:217], v[4:7]
	v_mfma_f32_16x16x32_bf16 v[0:3], v[180:183], v[214:217], v[0:3]
	s_setprio 0
	s_barrier
	s_add_i32 s61, 0, 0x18000
	s_add_i32 s62, 0, 0x1c000
	v_add_u32_e32 v164, s61, v151
	v_add_u32_e32 v180, s62, v151
	ds_read_b128 v[146:149], v164
	ds_read_b128 v[156:159], v164 offset:1024
	ds_read_b128 v[160:163], v164 offset:2048
	ds_read_b128 v[164:167], v164 offset:3072
	ds_read_b128 v[168:171], v180
	ds_read_b128 v[172:175], v180 offset:1024
	ds_read_b128 v[176:179], v180 offset:2048
	ds_read_b128 v[180:183], v180 offset:3072
	s_add_u32 s44, s44, 0x80000
	s_addc_u32 s45, s45, 0
	s_mov_b32 m0, s48
	v_lshl_add_u64 v[226:227], s[44:45], 0, v[134:135]
	ds_read_b128 v[184:187], v155 offset:32768
	ds_read_b128 v[188:191], v155 offset:33792
	ds_read_b128 v[192:195], v155 offset:34816
	ds_read_b128 v[196:199], v155 offset:35840
	ds_read_b128 v[200:203], v155 offset:36864
	ds_read_b128 v[204:207], v155 offset:37888
	ds_read_b128 v[210:213], v155 offset:38912
	ds_read_b128 v[214:217], v155 offset:39936
	global_load_lds_dwordx4 v[226:227], off
	v_lshl_add_u64 v[226:227], s[44:45], 0, v[130:131]
	s_mov_b32 m0, s49
	s_nop 0
	global_load_lds_dwordx4 v[226:227], off
	s_waitcnt vmcnt(8)
	s_waitcnt lgkmcnt(0)
	s_barrier
	s_setprio 1
	v_mfma_f32_16x16x32_bf16 v[124:127], v[146:149], v[184:187], v[124:127]
	v_mfma_f32_16x16x32_bf16 v[120:123], v[160:163], v[184:187], v[120:123]
	v_mfma_f32_16x16x32_bf16 v[116:119], v[146:149], v[192:195], v[116:119]
	v_mfma_f32_16x16x32_bf16 v[108:111], v[160:163], v[192:195], v[108:111]
	v_mfma_f32_16x16x32_bf16 v[100:103], v[146:149], v[200:203], v[100:103]
	v_mfma_f32_16x16x32_bf16 v[92:95], v[160:163], v[200:203], v[92:95]
	v_mfma_f32_16x16x32_bf16 v[84:87], v[146:149], v[210:213], v[84:87]
	v_mfma_f32_16x16x32_bf16 v[76:79], v[160:163], v[210:213], v[76:79]
	v_mfma_f32_16x16x32_bf16 v[124:127], v[156:159], v[188:191], v[124:127]
	v_mfma_f32_16x16x32_bf16 v[120:123], v[164:167], v[188:191], v[120:123]
	v_mfma_f32_16x16x32_bf16 v[116:119], v[156:159], v[196:199], v[116:119]
	v_mfma_f32_16x16x32_bf16 v[108:111], v[164:167], v[196:199], v[108:111]
	v_mfma_f32_16x16x32_bf16 v[100:103], v[156:159], v[204:207], v[100:103]
	v_mfma_f32_16x16x32_bf16 v[92:95], v[164:167], v[204:207], v[92:95]
	v_mfma_f32_16x16x32_bf16 v[84:87], v[156:159], v[214:217], v[84:87]
	v_mfma_f32_16x16x32_bf16 v[76:79], v[164:167], v[214:217], v[76:79]
	v_mfma_f32_16x16x32_bf16 v[112:115], v[168:171], v[184:187], v[112:115]
	v_mfma_f32_16x16x32_bf16 v[104:107], v[176:179], v[184:187], v[104:107]
	v_mfma_f32_16x16x32_bf16 v[96:99], v[168:171], v[192:195], v[96:99]
	v_mfma_f32_16x16x32_bf16 v[88:91], v[176:179], v[192:195], v[88:91]
	v_mfma_f32_16x16x32_bf16 v[80:83], v[168:171], v[200:203], v[80:83]
	v_mfma_f32_16x16x32_bf16 v[72:75], v[176:179], v[200:203], v[72:75]
	v_mfma_f32_16x16x32_bf16 v[68:71], v[168:171], v[210:213], v[68:71]
	v_mfma_f32_16x16x32_bf16 v[64:67], v[176:179], v[210:213], v[64:67]
	v_mfma_f32_16x16x32_bf16 v[112:115], v[172:175], v[188:191], v[112:115]
	v_mfma_f32_16x16x32_bf16 v[104:107], v[180:183], v[188:191], v[104:107]
	v_mfma_f32_16x16x32_bf16 v[96:99], v[172:175], v[196:199], v[96:99]
	v_mfma_f32_16x16x32_bf16 v[88:91], v[180:183], v[196:199], v[88:91]
	v_mfma_f32_16x16x32_bf16 v[80:83], v[172:175], v[204:207], v[80:83]
	v_mfma_f32_16x16x32_bf16 v[72:75], v[180:183], v[204:207], v[72:75]
	v_mfma_f32_16x16x32_bf16 v[68:71], v[172:175], v[214:217], v[68:71]
	v_mfma_f32_16x16x32_bf16 v[64:67], v[180:183], v[214:217], v[64:67]
	s_setprio 0
	s_barrier
	s_add_i32 s44, s61, s93
	v_lshl_add_u64 v[218:219], v[218:219], 0, s[6:7]
	s_mov_b32 m0, s44
	ds_read_b128 v[184:187], v155 offset:49152
	ds_read_b128 v[188:191], v155 offset:50176
	ds_read_b128 v[192:195], v155 offset:51200
	ds_read_b128 v[196:199], v155 offset:52224
	ds_read_b128 v[200:203], v155 offset:53248
	ds_read_b128 v[204:207], v155 offset:54272
	ds_read_b128 v[210:213], v155 offset:55296
	ds_read_b128 v[214:217], v155 offset:56320
	global_load_lds_dwordx4 v[218:219], off
	s_add_i32 m0, s44, 0x2000
	s_add_u32 s42, s42, 0x80080
	v_lshl_add_u64 v[218:219], v[220:221], 0, s[6:7]
	s_addc_u32 s43, s43, 0
	s_add_i32 s44, s62, s93
	global_load_lds_dwordx4 v[218:219], off
	v_lshl_add_u64 v[218:219], s[42:43], 0, v[132:133]
	s_mov_b32 m0, s44
	s_nop 0
	global_load_lds_dwordx4 v[218:219], off
	v_lshl_add_u64 v[218:219], s[42:43], 0, v[128:129]
	s_add_i32 m0, s44, 0x2000
	s_nop 0
	global_load_lds_dwordx4 v[218:219], off
	v_lshl_add_u64 v[218:219], v[222:223], 0, s[6:7]
	s_mov_b32 m0, s51
	s_nop 0
	global_load_lds_dwordx4 v[218:219], off
	v_lshl_add_u64 v[218:219], v[224:225], 0, s[6:7]
	s_mov_b32 m0, s52
	s_nop 0
	global_load_lds_dwordx4 v[218:219], off
	s_waitcnt vmcnt(8)
	s_waitcnt lgkmcnt(0)
	s_barrier
	s_setprio 1
	v_mfma_f32_16x16x32_bf16 v[60:63], v[146:149], v[184:187], v[60:63]
	v_mfma_f32_16x16x32_bf16 v[56:59], v[160:163], v[184:187], v[56:59]
	v_mfma_f32_16x16x32_bf16 v[52:55], v[146:149], v[192:195], v[52:55]
	v_mfma_f32_16x16x32_bf16 v[44:47], v[160:163], v[192:195], v[44:47]
	v_mfma_f32_16x16x32_bf16 v[36:39], v[146:149], v[200:203], v[36:39]
	v_mfma_f32_16x16x32_bf16 v[28:31], v[160:163], v[200:203], v[28:31]
	v_mfma_f32_16x16x32_bf16 v[20:23], v[146:149], v[210:213], v[20:23]
	v_mfma_f32_16x16x32_bf16 v[12:15], v[160:163], v[210:213], v[12:15]
	v_mfma_f32_16x16x32_bf16 v[60:63], v[156:159], v[188:191], v[60:63]
	v_mfma_f32_16x16x32_bf16 v[56:59], v[164:167], v[188:191], v[56:59]
	v_mfma_f32_16x16x32_bf16 v[52:55], v[156:159], v[196:199], v[52:55]
	v_mfma_f32_16x16x32_bf16 v[44:47], v[164:167], v[196:199], v[44:47]
	v_mfma_f32_16x16x32_bf16 v[36:39], v[156:159], v[204:207], v[36:39]
	v_mfma_f32_16x16x32_bf16 v[28:31], v[164:167], v[204:207], v[28:31]
	v_mfma_f32_16x16x32_bf16 v[20:23], v[156:159], v[214:217], v[20:23]
	v_mfma_f32_16x16x32_bf16 v[12:15], v[164:167], v[214:217], v[12:15]
	v_mfma_f32_16x16x32_bf16 v[48:51], v[168:171], v[184:187], v[48:51]
	v_mfma_f32_16x16x32_bf16 v[40:43], v[176:179], v[184:187], v[40:43]
	v_mfma_f32_16x16x32_bf16 v[32:35], v[168:171], v[192:195], v[32:35]
	v_mfma_f32_16x16x32_bf16 v[24:27], v[176:179], v[192:195], v[24:27]
	v_mfma_f32_16x16x32_bf16 v[16:19], v[168:171], v[200:203], v[16:19]
	v_mfma_f32_16x16x32_bf16 v[8:11], v[176:179], v[200:203], v[8:11]
	v_mfma_f32_16x16x32_bf16 v[4:7], v[168:171], v[210:213], v[4:7]
	v_mfma_f32_16x16x32_bf16 v[0:3], v[176:179], v[210:213], v[0:3]
	v_mfma_f32_16x16x32_bf16 v[48:51], v[172:175], v[188:191], v[48:51]
	v_mfma_f32_16x16x32_bf16 v[40:43], v[180:183], v[188:191], v[40:43]
	v_mfma_f32_16x16x32_bf16 v[32:35], v[172:175], v[196:199], v[32:35]
	v_mfma_f32_16x16x32_bf16 v[24:27], v[180:183], v[196:199], v[24:27]
	v_mfma_f32_16x16x32_bf16 v[16:19], v[172:175], v[204:207], v[16:19]
	v_mfma_f32_16x16x32_bf16 v[8:11], v[180:183], v[204:207], v[8:11]
	v_mfma_f32_16x16x32_bf16 v[4:7], v[172:175], v[214:217], v[4:7]
	v_mfma_f32_16x16x32_bf16 v[0:3], v[180:183], v[214:217], v[0:3]
	s_setprio 0
	s_barrier
	s_add_i32 s60, s60, 2
	s_add_u32 s40, s40, 0x100
	s_addc_u32 s41, s41, 0
	s_add_u32 s58, s58, 0x100
	s_addc_u32 s59, s59, 0
	s_cmp_gt_u32 s60, 29
	s_cbranch_scc0 .LBB0_153
	s_and_b64 vcc, exec, s[14:15]
	s_cbranch_vccnz .LBB0_158
	s_cmp_gt_i32 s57, 37
	s_mov_b64 s[2:3], -1
	s_cbranch_scc1 .LBB0_159

.LBB0_376:
	ds_read_b128 v[32:35], v165
	ds_read_b128 v[36:39], v165 offset:1024
	ds_read_b128 v[48:51], v165 offset:2048
	ds_read_b128 v[52:55], v165 offset:3072
	ds_read_b128 v[156:159], v166
	ds_read_b128 v[168:171], v166 offset:1024
	ds_read_b128 v[172:175], v166 offset:2048
	ds_read_b128 v[176:179], v166 offset:3072
	s_add_u32 s46, s44, 0xfff80080
	s_addc_u32 s47, s45, -1
	s_cmp_eq_u32 s72, 60
	s_cselect_b32 s49, s2, s47
	s_cselect_b32 s48, s3, s46
	s_cselect_b32 s47, s33, s71
	s_cselect_b32 s46, s37, s39
	v_lshl_add_u64 v[160:161], s[44:45], 0, v[152:153]
	s_add_i32 m0, s61, 0xc000
	ds_read_b128 v[180:183], v167
	ds_read_b128 v[184:187], v167 offset:1024
	ds_read_b128 v[188:191], v167 offset:2048
	ds_read_b128 v[192:195], v167 offset:3072
	ds_read_b128 v[196:199], v167 offset:4096
	ds_read_b128 v[200:203], v167 offset:5120
	ds_read_b128 v[204:207], v167 offset:6144
	ds_read_b128 v[210:213], v167 offset:7168
	global_load_lds_dwordx4 v[160:161], off
	v_lshl_add_u64 v[160:161], s[44:45], 0, v[154:155]
	s_add_i32 m0, s61, 0xe000
	s_nop 0
	global_load_lds_dwordx4 v[160:161], off
	s_waitcnt vmcnt(8)
	s_waitcnt lgkmcnt(0)
	s_barrier
	s_setprio 1
	v_mfma_f32_16x16x32_bf16 v[140:143], v[32:35], v[180:183], v[140:143]
	v_mfma_f32_16x16x32_bf16 v[136:139], v[48:51], v[180:183], v[136:139]
	v_mfma_f32_16x16x32_bf16 v[124:127], v[32:35], v[188:191], v[124:127]
	v_mfma_f32_16x16x32_bf16 v[120:123], v[48:51], v[188:191], v[120:123]
	v_mfma_f32_16x16x32_bf16 v[108:111], v[32:35], v[196:199], v[108:111]
	v_mfma_f32_16x16x32_bf16 v[104:107], v[48:51], v[196:199], v[104:107]
	v_mfma_f32_16x16x32_bf16 v[92:95], v[32:35], v[204:207], v[92:95]
	v_mfma_f32_16x16x32_bf16 v[88:91], v[48:51], v[204:207], v[88:91]
	v_mfma_f32_16x16x32_bf16 v[140:143], v[36:39], v[184:187], v[140:143]
	v_mfma_f32_16x16x32_bf16 v[136:139], v[52:55], v[184:187], v[136:139]
	v_mfma_f32_16x16x32_bf16 v[124:127], v[36:39], v[192:195], v[124:127]
	v_mfma_f32_16x16x32_bf16 v[120:123], v[52:55], v[192:195], v[120:123]
	v_mfma_f32_16x16x32_bf16 v[108:111], v[36:39], v[200:203], v[108:111]
	v_mfma_f32_16x16x32_bf16 v[104:107], v[52:55], v[200:203], v[104:107]
	v_mfma_f32_16x16x32_bf16 v[92:95], v[36:39], v[210:213], v[92:95]
	v_mfma_f32_16x16x32_bf16 v[88:91], v[52:55], v[210:213], v[88:91]
	v_mfma_f32_16x16x32_bf16 v[132:135], v[156:159], v[180:183], v[132:135]
	v_mfma_f32_16x16x32_bf16 v[128:131], v[172:175], v[180:183], v[128:131]
	v_mfma_f32_16x16x32_bf16 v[116:119], v[156:159], v[188:191], v[116:119]
	v_mfma_f32_16x16x32_bf16 v[112:115], v[172:175], v[188:191], v[112:115]
	v_mfma_f32_16x16x32_bf16 v[100:103], v[156:159], v[196:199], v[100:103]
	v_mfma_f32_16x16x32_bf16 v[96:99], v[172:175], v[196:199], v[96:99]
	v_mfma_f32_16x16x32_bf16 v[84:87], v[156:159], v[204:207], v[84:87]
	v_mfma_f32_16x16x32_bf16 v[80:83], v[172:175], v[204:207], v[80:83]
	v_mfma_f32_16x16x32_bf16 v[132:135], v[168:171], v[184:187], v[132:135]
	v_mfma_f32_16x16x32_bf16 v[128:131], v[176:179], v[184:187], v[128:131]
	v_mfma_f32_16x16x32_bf16 v[116:119], v[168:171], v[192:195], v[116:119]
	v_mfma_f32_16x16x32_bf16 v[112:115], v[176:179], v[192:195], v[112:115]
	v_mfma_f32_16x16x32_bf16 v[100:103], v[168:171], v[200:203], v[100:103]
	v_mfma_f32_16x16x32_bf16 v[96:99], v[176:179], v[200:203], v[96:99]
	v_mfma_f32_16x16x32_bf16 v[84:87], v[168:171], v[210:213], v[84:87]
	v_mfma_f32_16x16x32_bf16 v[80:83], v[176:179], v[210:213], v[80:83]
	s_setprio 0
	s_barrier
	s_add_i32 s73, s68, s93
	v_lshl_add_u64 v[160:161], s[46:47], 0, v[146:147]
	s_mov_b32 m0, s73
	ds_read_b128 v[180:183], v167 offset:16384
	ds_read_b128 v[184:187], v167 offset:17408
	ds_read_b128 v[188:191], v167 offset:18432
	ds_read_b128 v[192:195], v167 offset:19456
	ds_read_b128 v[196:199], v167 offset:20480
	ds_read_b128 v[200:203], v167 offset:21504
	ds_read_b128 v[204:207], v167 offset:22528
	ds_read_b128 v[210:213], v167 offset:23552
	global_load_lds_dwordx4 v[160:161], off
	s_add_i32 m0, s73, 0x2000
	s_add_u32 s74, s46, 0x100000
	v_lshl_add_u64 v[214:215], s[46:47], 0, v[150:151]
	s_addc_u32 s75, s47, 0
	s_add_i32 s73, s69, s93
	global_load_lds_dwordx4 v[214:215], off
	v_lshl_add_u64 v[216:217], s[74:75], 0, v[146:147]
	s_mov_b32 m0, s73
	v_lshl_add_u64 v[218:219], s[48:49], 0, v[148:149]
	global_load_lds_dwordx4 v[216:217], off
	v_lshl_add_u64 v[216:217], s[74:75], 0, v[150:151]
	s_add_i32 m0, s73, 0x2000
	s_nop 0
	global_load_lds_dwordx4 v[216:217], off
	v_lshl_add_u64 v[216:217], s[48:49], 0, v[144:145]
	s_mov_b32 m0, s61
	s_nop 0
	global_load_lds_dwordx4 v[216:217], off
	s_mov_b32 m0, s62
	s_nop 0
	global_load_lds_dwordx4 v[218:219], off
	s_waitcnt vmcnt(8)
	s_waitcnt lgkmcnt(0)
	s_barrier
	s_setprio 1
	v_mfma_f32_16x16x32_bf16 v[76:79], v[32:35], v[180:183], v[76:79]
	v_mfma_f32_16x16x32_bf16 v[72:75], v[48:51], v[180:183], v[72:75]
	v_mfma_f32_16x16x32_bf16 v[60:63], v[32:35], v[188:191], v[60:63]
	v_mfma_f32_16x16x32_bf16 v[56:59], v[48:51], v[188:191], v[56:59]
	v_mfma_f32_16x16x32_bf16 v[28:31], v[32:35], v[196:199], v[28:31]
	v_mfma_f32_16x16x32_bf16 v[24:27], v[48:51], v[196:199], v[24:27]
	v_mfma_f32_16x16x32_bf16 v[12:15], v[32:35], v[204:207], v[12:15]
	v_mfma_f32_16x16x32_bf16 v[8:11], v[48:51], v[204:207], v[8:11]
	v_mfma_f32_16x16x32_bf16 v[76:79], v[36:39], v[184:187], v[76:79]
	v_mfma_f32_16x16x32_bf16 v[72:75], v[52:55], v[184:187], v[72:75]
	v_mfma_f32_16x16x32_bf16 v[60:63], v[36:39], v[192:195], v[60:63]
	v_mfma_f32_16x16x32_bf16 v[56:59], v[52:55], v[192:195], v[56:59]
	v_mfma_f32_16x16x32_bf16 v[28:31], v[36:39], v[200:203], v[28:31]
	v_mfma_f32_16x16x32_bf16 v[24:27], v[52:55], v[200:203], v[24:27]
	v_mfma_f32_16x16x32_bf16 v[12:15], v[36:39], v[210:213], v[12:15]
	v_mfma_f32_16x16x32_bf16 v[8:11], v[52:55], v[210:213], v[8:11]
	v_mfma_f32_16x16x32_bf16 v[44:47], v[156:159], v[188:191], v[44:47]
	v_mfma_f32_16x16x32_bf16 v[40:43], v[172:175], v[188:191], v[40:43]
	v_mfma_f32_16x16x32_bf16 v[20:23], v[156:159], v[196:199], v[20:23]
	v_mfma_f32_16x16x32_bf16 v[16:19], v[172:175], v[196:199], v[16:19]
	v_mfma_f32_16x16x32_bf16 v[4:7], v[156:159], v[204:207], v[4:7]
	v_mfma_f32_16x16x32_bf16 v[0:3], v[172:175], v[204:207], v[0:3]
	v_mfma_f32_16x16x32_bf16 v[32:35], v[156:159], v[180:183], v[68:71]
	v_mfma_f32_16x16x32_bf16 v[36:39], v[172:175], v[180:183], v[64:67]
	v_mfma_f32_16x16x32_bf16 v[44:47], v[168:171], v[192:195], v[44:47]
	v_mfma_f32_16x16x32_bf16 v[40:43], v[176:179], v[192:195], v[40:43]
	v_mfma_f32_16x16x32_bf16 v[20:23], v[168:171], v[200:203], v[20:23]
	v_mfma_f32_16x16x32_bf16 v[16:19], v[176:179], v[200:203], v[16:19]
	v_mfma_f32_16x16x32_bf16 v[4:7], v[168:171], v[210:213], v[4:7]
	v_mfma_f32_16x16x32_bf16 v[0:3], v[176:179], v[210:213], v[0:3]
	v_mfma_f32_16x16x32_bf16 v[32:35], v[168:171], v[184:187], v[32:35]
	v_mfma_f32_16x16x32_bf16 v[36:39], v[176:179], v[184:187], v[36:39]
	s_setprio 0
	s_barrier
	s_add_i32 s73, 0, 0x18000
	s_add_i32 s74, 0, 0x1c000
	v_add_u32_e32 v68, s73, v163
	v_add_u32_e32 v176, s74, v163
	ds_read_b128 v[48:51], v68
	ds_read_b128 v[52:55], v68 offset:1024
	ds_read_b128 v[64:67], v68 offset:2048
	ds_read_b128 v[68:71], v68 offset:3072
	ds_read_b128 v[156:159], v176
	ds_read_b128 v[168:171], v176 offset:1024
	ds_read_b128 v[172:175], v176 offset:2048
	ds_read_b128 v[176:179], v176 offset:3072
	s_add_u32 s48, s48, 0x80000
	s_addc_u32 s49, s49, 0
	s_mov_b32 m0, s63
	v_lshl_add_u64 v[220:221], s[48:49], 0, v[144:145]
	ds_read_b128 v[180:183], v167 offset:32768
	ds_read_b128 v[184:187], v167 offset:33792
	ds_read_b128 v[188:191], v167 offset:34816
	ds_read_b128 v[192:195], v167 offset:35840
	ds_read_b128 v[196:199], v167 offset:36864
	ds_read_b128 v[200:203], v167 offset:37888
	ds_read_b128 v[204:207], v167 offset:38912
	ds_read_b128 v[210:213], v167 offset:39936
	global_load_lds_dwordx4 v[220:221], off
	v_lshl_add_u64 v[220:221], s[48:49], 0, v[148:149]
	s_mov_b32 m0, s64
	s_nop 0
	global_load_lds_dwordx4 v[220:221], off
	s_waitcnt vmcnt(8)
	s_waitcnt lgkmcnt(0)
	s_barrier
	s_setprio 1
	v_mfma_f32_16x16x32_bf16 v[140:143], v[48:51], v[180:183], v[140:143]
	v_mfma_f32_16x16x32_bf16 v[136:139], v[64:67], v[180:183], v[136:139]
	v_mfma_f32_16x16x32_bf16 v[124:127], v[48:51], v[188:191], v[124:127]
	v_mfma_f32_16x16x32_bf16 v[120:123], v[64:67], v[188:191], v[120:123]
	v_mfma_f32_16x16x32_bf16 v[108:111], v[48:51], v[196:199], v[108:111]
	v_mfma_f32_16x16x32_bf16 v[104:107], v[64:67], v[196:199], v[104:107]
	v_mfma_f32_16x16x32_bf16 v[92:95], v[48:51], v[204:207], v[92:95]
	v_mfma_f32_16x16x32_bf16 v[88:91], v[64:67], v[204:207], v[88:91]
	v_mfma_f32_16x16x32_bf16 v[140:143], v[52:55], v[184:187], v[140:143]
	v_mfma_f32_16x16x32_bf16 v[136:139], v[68:71], v[184:187], v[136:139]
	v_mfma_f32_16x16x32_bf16 v[124:127], v[52:55], v[192:195], v[124:127]
	v_mfma_f32_16x16x32_bf16 v[120:123], v[68:71], v[192:195], v[120:123]
	v_mfma_f32_16x16x32_bf16 v[108:111], v[52:55], v[200:203], v[108:111]
	v_mfma_f32_16x16x32_bf16 v[104:107], v[68:71], v[200:203], v[104:107]
	v_mfma_f32_16x16x32_bf16 v[92:95], v[52:55], v[210:213], v[92:95]
	v_mfma_f32_16x16x32_bf16 v[88:91], v[68:71], v[210:213], v[88:91]
	v_mfma_f32_16x16x32_bf16 v[132:135], v[156:159], v[180:183], v[132:135]
	v_mfma_f32_16x16x32_bf16 v[128:131], v[172:175], v[180:183], v[128:131]
	v_mfma_f32_16x16x32_bf16 v[116:119], v[156:159], v[188:191], v[116:119]
	v_mfma_f32_16x16x32_bf16 v[112:115], v[172:175], v[188:191], v[112:115]
	v_mfma_f32_16x16x32_bf16 v[100:103], v[156:159], v[196:199], v[100:103]
	v_mfma_f32_16x16x32_bf16 v[96:99], v[172:175], v[196:199], v[96:99]
	v_mfma_f32_16x16x32_bf16 v[84:87], v[156:159], v[204:207], v[84:87]
	v_mfma_f32_16x16x32_bf16 v[80:83], v[172:175], v[204:207], v[80:83]
	v_mfma_f32_16x16x32_bf16 v[132:135], v[168:171], v[184:187], v[132:135]
	v_mfma_f32_16x16x32_bf16 v[128:131], v[176:179], v[184:187], v[128:131]
	v_mfma_f32_16x16x32_bf16 v[116:119], v[168:171], v[192:195], v[116:119]
	v_mfma_f32_16x16x32_bf16 v[112:115], v[176:179], v[192:195], v[112:115]
	v_mfma_f32_16x16x32_bf16 v[100:103], v[168:171], v[200:203], v[100:103]
	v_mfma_f32_16x16x32_bf16 v[96:99], v[176:179], v[200:203], v[96:99]
	v_mfma_f32_16x16x32_bf16 v[84:87], v[168:171], v[210:213], v[84:87]
	v_mfma_f32_16x16x32_bf16 v[80:83], v[176:179], v[210:213], v[80:83]
	s_setprio 0
	s_barrier
	s_add_i32 s48, s73, s93
	v_lshl_add_u64 v[160:161], v[160:161], 0, s[28:29]
	s_mov_b32 m0, s48
	ds_read_b128 v[180:183], v167 offset:49152
	ds_read_b128 v[184:187], v167 offset:50176
	ds_read_b128 v[188:191], v167 offset:51200
	ds_read_b128 v[192:195], v167 offset:52224
	ds_read_b128 v[196:199], v167 offset:53248
	ds_read_b128 v[200:203], v167 offset:54272
	ds_read_b128 v[204:207], v167 offset:55296
	ds_read_b128 v[210:213], v167 offset:56320
	global_load_lds_dwordx4 v[160:161], off
	s_add_i32 m0, s48, 0x2000
	s_add_u32 s46, s46, 0x100080
	v_lshl_add_u64 v[160:161], v[214:215], 0, s[28:29]
	s_addc_u32 s47, s47, 0
	s_add_i32 s48, s74, s93
	global_load_lds_dwordx4 v[160:161], off
	v_lshl_add_u64 v[160:161], s[46:47], 0, v[146:147]
	s_mov_b32 m0, s48
	s_nop 0
	global_load_lds_dwordx4 v[160:161], off
	v_lshl_add_u64 v[160:161], s[46:47], 0, v[150:151]
	s_add_i32 m0, s48, 0x2000
	s_nop 0
	global_load_lds_dwordx4 v[160:161], off
	v_lshl_add_u64 v[160:161], v[216:217], 0, s[28:29]
	s_mov_b32 m0, s65
	s_nop 0
	global_load_lds_dwordx4 v[160:161], off
	v_lshl_add_u64 v[160:161], v[218:219], 0, s[28:29]
	s_mov_b32 m0, s66
	s_nop 0
	global_load_lds_dwordx4 v[160:161], off
	s_waitcnt vmcnt(8)
	s_waitcnt lgkmcnt(0)
	s_barrier
	s_setprio 1
	v_mfma_f32_16x16x32_bf16 v[76:79], v[48:51], v[180:183], v[76:79]
	v_mfma_f32_16x16x32_bf16 v[72:75], v[64:67], v[180:183], v[72:75]
	v_mfma_f32_16x16x32_bf16 v[60:63], v[48:51], v[188:191], v[60:63]
	v_mfma_f32_16x16x32_bf16 v[56:59], v[64:67], v[188:191], v[56:59]
	v_mfma_f32_16x16x32_bf16 v[28:31], v[48:51], v[196:199], v[28:31]
	v_mfma_f32_16x16x32_bf16 v[24:27], v[64:67], v[196:199], v[24:27]
	v_mfma_f32_16x16x32_bf16 v[12:15], v[48:51], v[204:207], v[12:15]
	v_mfma_f32_16x16x32_bf16 v[8:11], v[64:67], v[204:207], v[8:11]
	v_mfma_f32_16x16x32_bf16 v[76:79], v[52:55], v[184:187], v[76:79]
	v_mfma_f32_16x16x32_bf16 v[72:75], v[68:71], v[184:187], v[72:75]
	v_mfma_f32_16x16x32_bf16 v[60:63], v[52:55], v[192:195], v[60:63]
	v_mfma_f32_16x16x32_bf16 v[56:59], v[68:71], v[192:195], v[56:59]
	v_mfma_f32_16x16x32_bf16 v[28:31], v[52:55], v[200:203], v[28:31]
	v_mfma_f32_16x16x32_bf16 v[24:27], v[68:71], v[200:203], v[24:27]
	v_mfma_f32_16x16x32_bf16 v[12:15], v[52:55], v[210:213], v[12:15]
	v_mfma_f32_16x16x32_bf16 v[8:11], v[68:71], v[210:213], v[8:11]
	v_mfma_f32_16x16x32_bf16 v[32:35], v[156:159], v[180:183], v[32:35]
	v_mfma_f32_16x16x32_bf16 v[68:71], v[168:171], v[184:187], v[32:35]
	v_mfma_f32_16x16x32_bf16 v[32:35], v[172:175], v[180:183], v[36:39]
	v_mfma_f32_16x16x32_bf16 v[64:67], v[176:179], v[184:187], v[32:35]
	v_mfma_f32_16x16x32_bf16 v[32:35], v[156:159], v[188:191], v[44:47]
	v_mfma_f32_16x16x32_bf16 v[44:47], v[168:171], v[192:195], v[32:35]
	v_mfma_f32_16x16x32_bf16 v[32:35], v[172:175], v[188:191], v[40:43]
	v_mfma_f32_16x16x32_bf16 v[20:23], v[156:159], v[196:199], v[20:23]
	v_mfma_f32_16x16x32_bf16 v[16:19], v[172:175], v[196:199], v[16:19]
	v_mfma_f32_16x16x32_bf16 v[4:7], v[156:159], v[204:207], v[4:7]
	v_mfma_f32_16x16x32_bf16 v[0:3], v[172:175], v[204:207], v[0:3]
	v_mfma_f32_16x16x32_bf16 v[40:43], v[176:179], v[192:195], v[32:35]
	v_mfma_f32_16x16x32_bf16 v[20:23], v[168:171], v[200:203], v[20:23]
	v_mfma_f32_16x16x32_bf16 v[16:19], v[176:179], v[200:203], v[16:19]
	v_mfma_f32_16x16x32_bf16 v[4:7], v[168:171], v[210:213], v[4:7]
	v_mfma_f32_16x16x32_bf16 v[0:3], v[176:179], v[210:213], v[0:3]
	s_setprio 0
	s_barrier
	s_add_i32 s72, s72, 2
	s_add_u32 s44, s44, 0x100
	s_addc_u32 s45, s45, 0
	s_add_u32 s39, s39, 0x100
	s_addc_u32 s71, s71, 0
	s_cmp_gt_u32 s72, 61
	s_cbranch_scc0 .LBB0_376
	v_readlane_b32 s72, v235, 62
	s_and_b64 vcc, exec, s[30:31]
	v_readlane_b32 s73, v235, 63
	v_readlane_b32 s74, v234, 0
	v_readlane_b32 s75, v234, 1
	s_cbranch_vccz .LBB0_379
	s_barrier

.LBB0_399:
	s_ashr_i32 s39, s38, 31
	s_lshl_b64 s[2:3], s[38:39], 17
	s_add_u32 s40, s6, s2
	s_addc_u32 s41, s7, s3
	ds_read_b128 v[0:3], v90
	ds_read_b128 v[4:7], v90 offset:1024
	ds_read_b128 v[8:11], v90 offset:2048
	ds_read_b128 v[12:15], v90 offset:3072
	s_and_b64 s[2:3], s[34:35], exec
	s_cselect_b32 s49, s41, s45
	s_cselect_b32 s48, s40, s44
	s_ashr_i32 s37, s36, 31
	s_lshl_b64 s[2:3], s[36:37], 17
	s_add_u32 s42, s20, s2
	s_addc_u32 s43, s21, s3
	s_and_b64 s[2:3], s[34:35], exec
	s_cselect_b32 s47, s43, s51
	s_cselect_b32 s46, s42, s50
	s_add_u32 s2, s44, 0x10080
	s_addc_u32 s3, s45, 0
	s_mov_b32 m0, s59
	v_lshl_add_u64 v[48:49], s[2:3], 0, v[64:65]
	ds_read_b128 v[16:19], v91
	ds_read_b128 v[20:23], v91 offset:1024
	ds_read_b128 v[24:27], v91 offset:2048
	ds_read_b128 v[28:31], v91 offset:3072
	ds_read_b128 v[32:35], v91 offset:4096
	ds_read_b128 v[36:39], v91 offset:5120
	ds_read_b128 v[40:43], v91 offset:6144
	ds_read_b128 v[44:47], v91 offset:7168
	global_load_lds_dwordx4 v[48:49], off
	v_lshl_add_u64 v[48:49], s[2:3], 0, v[68:69]
	s_mov_b32 m0, s68
	s_nop 0
	global_load_lds_dwordx4 v[48:49], off
	s_waitcnt vmcnt(8)
	s_waitcnt lgkmcnt(0)
	s_barrier
	s_setprio 1
	v_mfma_f32_16x16x32_bf16 v[48:51], v[0:3], v[16:19], 0
	v_mfma_f32_16x16x32_bf16 v[16:19], v[8:11], v[16:19], 0
	v_mfma_f32_16x16x32_bf16 v[48:51], v[4:7], v[20:23], v[48:51]
	v_mfma_f32_16x16x32_bf16 v[16:19], v[12:15], v[20:23], v[16:19]
	v_mfma_f32_16x16x32_bf16 v[20:23], v[0:3], v[24:27], 0
	v_mfma_f32_16x16x32_bf16 v[24:27], v[8:11], v[24:27], 0
	v_mfma_f32_16x16x32_bf16 v[20:23], v[4:7], v[28:31], v[20:23]
	v_mfma_f32_16x16x32_bf16 v[24:27], v[12:15], v[28:31], v[24:27]
	v_mfma_f32_16x16x32_bf16 v[28:31], v[0:3], v[32:35], 0
	v_mfma_f32_16x16x32_bf16 v[32:35], v[8:11], v[32:35], 0
	v_mfma_f32_16x16x32_bf16 v[28:31], v[4:7], v[36:39], v[28:31]
	v_mfma_f32_16x16x32_bf16 v[32:35], v[12:15], v[36:39], v[32:35]
	v_mfma_f32_16x16x32_bf16 v[36:39], v[0:3], v[40:43], 0
	v_mfma_f32_16x16x32_bf16 v[40:43], v[8:11], v[40:43], 0
	v_mfma_f32_16x16x32_bf16 v[36:39], v[4:7], v[44:47], v[36:39]
	v_mfma_f32_16x16x32_bf16 v[40:43], v[12:15], v[44:47], v[40:43]
	s_setprio 0
	s_barrier
	v_lshl_add_u64 v[142:143], s[50:51], 0, v[66:67]
	s_mov_b32 m0, s69
	v_lshl_add_u64 v[110:111], v[142:143], 0, s[26:27]
	v_lshl_add_u64 v[144:145], s[50:51], 0, v[70:71]
	s_add_u32 s2, s50, 0x10100
	ds_read_b128 v[44:47], v91 offset:16384
	ds_read_b128 v[52:55], v91 offset:17408
	ds_read_b128 v[56:59], v91 offset:18432
	ds_read_b128 v[60:63], v91 offset:19456
	ds_read_b128 v[94:97], v91 offset:20480
	ds_read_b128 v[98:101], v91 offset:21504
	ds_read_b128 v[102:105], v91 offset:22528
	ds_read_b128 v[106:109], v91 offset:23552
	global_load_lds_dwordx4 v[110:111], off
	v_lshl_add_u64 v[110:111], v[144:145], 0, s[26:27]
	s_mov_b32 m0, s70
	s_addc_u32 s3, s51, 0
	global_load_lds_dwordx4 v[110:111], off
	v_lshl_add_u64 v[110:111], s[2:3], 0, v[66:67]
	s_mov_b32 m0, s33
	v_lshl_add_u64 v[146:147], s[44:45], 0, v[64:65]
	global_load_lds_dwordx4 v[110:111], off
	v_lshl_add_u64 v[110:111], s[2:3], 0, v[70:71]
	s_mov_b32 m0, s60
	v_lshl_add_u64 v[148:149], s[44:45], 0, v[68:69]
	global_load_lds_dwordx4 v[110:111], off
	v_lshl_add_u64 v[110:111], v[146:147], 0, s[26:27]
	s_mov_b32 m0, s31
	s_nop 0
	global_load_lds_dwordx4 v[110:111], off
	v_lshl_add_u64 v[110:111], v[148:149], 0, s[26:27]
	s_mov_b32 m0, s61
	s_nop 0
	global_load_lds_dwordx4 v[110:111], off
	s_waitcnt vmcnt(8)
	s_waitcnt lgkmcnt(0)
	s_barrier
	s_setprio 1
	v_mfma_f32_16x16x32_bf16 v[110:113], v[0:3], v[44:47], 0
	v_mfma_f32_16x16x32_bf16 v[44:47], v[8:11], v[44:47], 0
	v_mfma_f32_16x16x32_bf16 v[110:113], v[4:7], v[52:55], v[110:113]
	v_mfma_f32_16x16x32_bf16 v[44:47], v[12:15], v[52:55], v[44:47]
	v_mfma_f32_16x16x32_bf16 v[52:55], v[0:3], v[56:59], 0
	v_mfma_f32_16x16x32_bf16 v[56:59], v[8:11], v[56:59], 0
	v_mfma_f32_16x16x32_bf16 v[52:55], v[4:7], v[60:63], v[52:55]
	v_mfma_f32_16x16x32_bf16 v[56:59], v[12:15], v[60:63], v[56:59]
	v_mfma_f32_16x16x32_bf16 v[60:63], v[0:3], v[94:97], 0
	v_mfma_f32_16x16x32_bf16 v[0:3], v[0:3], v[102:105], 0
	v_mfma_f32_16x16x32_bf16 v[60:63], v[4:7], v[98:101], v[60:63]
	v_mfma_f32_16x16x32_bf16 v[0:3], v[4:7], v[106:109], v[0:3]
	v_mfma_f32_16x16x32_bf16 v[4:7], v[8:11], v[102:105], 0
	v_mfma_f32_16x16x32_bf16 v[94:97], v[8:11], v[94:97], 0
	v_mfma_f32_16x16x32_bf16 v[4:7], v[12:15], v[106:109], v[4:7]
	v_mfma_f32_16x16x32_bf16 v[94:97], v[12:15], v[98:101], v[94:97]
	s_setprio 0
	s_barrier
	ds_read_b128 v[8:11], v92
	ds_read_b128 v[12:15], v92 offset:1024
	ds_read_b128 v[98:101], v92 offset:2048
	ds_read_b128 v[102:105], v92 offset:3072
	s_add_u32 s2, s44, 0x10100
	s_addc_u32 s3, s45, 0
	s_mov_b32 m0, s62
	v_lshl_add_u64 v[150:151], s[2:3], 0, v[64:65]
	ds_read_b128 v[106:109], v91 offset:32768
	ds_read_b128 v[114:117], v91 offset:33792
	ds_read_b128 v[118:121], v91 offset:34816
	ds_read_b128 v[122:125], v91 offset:35840
	ds_read_b128 v[126:129], v91 offset:36864
	ds_read_b128 v[130:133], v91 offset:37888
	ds_read_b128 v[134:137], v91 offset:38912
	ds_read_b128 v[138:141], v91 offset:39936
	global_load_lds_dwordx4 v[150:151], off
	v_lshl_add_u64 v[150:151], s[2:3], 0, v[68:69]
	s_mov_b32 m0, s63
	s_nop 0
	global_load_lds_dwordx4 v[150:151], off
	s_waitcnt vmcnt(8)
	s_waitcnt lgkmcnt(0)
	s_barrier
	s_setprio 1
	v_mfma_f32_16x16x32_bf16 v[48:51], v[8:11], v[106:109], v[48:51]
	v_mfma_f32_16x16x32_bf16 v[16:19], v[98:101], v[106:109], v[16:19]
	v_mfma_f32_16x16x32_bf16 v[20:23], v[8:11], v[118:121], v[20:23]
	v_mfma_f32_16x16x32_bf16 v[24:27], v[98:101], v[118:121], v[24:27]
	v_mfma_f32_16x16x32_bf16 v[28:31], v[8:11], v[126:129], v[28:31]
	v_mfma_f32_16x16x32_bf16 v[32:35], v[98:101], v[126:129], v[32:35]
	v_mfma_f32_16x16x32_bf16 v[36:39], v[8:11], v[134:137], v[36:39]
	v_mfma_f32_16x16x32_bf16 v[40:43], v[98:101], v[134:137], v[40:43]
	v_mfma_f32_16x16x32_bf16 v[48:51], v[12:15], v[114:117], v[48:51]
	v_mfma_f32_16x16x32_bf16 v[16:19], v[102:105], v[114:117], v[16:19]
	v_mfma_f32_16x16x32_bf16 v[20:23], v[12:15], v[122:125], v[20:23]
	v_mfma_f32_16x16x32_bf16 v[24:27], v[102:105], v[122:125], v[24:27]
	v_mfma_f32_16x16x32_bf16 v[28:31], v[12:15], v[130:133], v[28:31]
	v_mfma_f32_16x16x32_bf16 v[32:35], v[102:105], v[130:133], v[32:35]
	v_mfma_f32_16x16x32_bf16 v[36:39], v[12:15], v[138:141], v[36:39]
	v_mfma_f32_16x16x32_bf16 v[40:43], v[102:105], v[138:141], v[40:43]
	s_setprio 0
	s_barrier
	s_mov_b32 m0, s71
	v_lshl_add_u64 v[142:143], v[142:143], 0, s[28:29]
	s_add_u32 s2, s50, 0x10180
	ds_read_b128 v[106:109], v91 offset:49152
	ds_read_b128 v[114:117], v91 offset:50176
	ds_read_b128 v[118:121], v91 offset:51200
	ds_read_b128 v[122:125], v91 offset:52224
	ds_read_b128 v[126:129], v91 offset:53248
	ds_read_b128 v[130:133], v91 offset:54272
	ds_read_b128 v[134:137], v91 offset:55296
	ds_read_b128 v[138:141], v91 offset:56320
	global_load_lds_dwordx4 v[142:143], off
	v_lshl_add_u64 v[142:143], v[144:145], 0, s[28:29]
	s_mov_b32 m0, s72
	s_addc_u32 s3, s51, 0
	global_load_lds_dwordx4 v[142:143], off
	v_lshl_add_u64 v[142:143], s[2:3], 0, v[66:67]
	s_mov_b32 m0, s66
	s_nop 0
	global_load_lds_dwordx4 v[142:143], off
	v_lshl_add_u64 v[142:143], s[2:3], 0, v[70:71]
	s_mov_b32 m0, s67
	s_nop 0
	global_load_lds_dwordx4 v[142:143], off
	v_lshl_add_u64 v[142:143], v[146:147], 0, s[28:29]
	s_mov_b32 m0, s64
	s_nop 0
	global_load_lds_dwordx4 v[142:143], off
	v_lshl_add_u64 v[142:143], v[148:149], 0, s[28:29]
	s_mov_b32 m0, s65
	s_nop 0
	global_load_lds_dwordx4 v[142:143], off
	s_waitcnt vmcnt(8)
	s_waitcnt lgkmcnt(0)
	s_barrier
	s_setprio 1
	v_mfma_f32_16x16x32_bf16 v[44:47], v[98:101], v[106:109], v[44:47]
	v_mfma_f32_16x16x32_bf16 v[52:55], v[8:11], v[118:121], v[52:55]
	v_mfma_f32_16x16x32_bf16 v[56:59], v[98:101], v[118:121], v[56:59]
	v_mfma_f32_16x16x32_bf16 v[60:63], v[8:11], v[126:129], v[60:63]
	v_mfma_f32_16x16x32_bf16 v[0:3], v[8:11], v[134:137], v[0:3]
	v_mfma_f32_16x16x32_bf16 v[4:7], v[98:101], v[134:137], v[4:7]
	v_mfma_f32_16x16x32_bf16 v[110:113], v[8:11], v[106:109], v[110:113]
	v_mfma_f32_16x16x32_bf16 v[44:47], v[102:105], v[114:117], v[44:47]
	v_mfma_f32_16x16x32_bf16 v[52:55], v[12:15], v[122:125], v[52:55]
	v_mfma_f32_16x16x32_bf16 v[56:59], v[102:105], v[122:125], v[56:59]
	v_mfma_f32_16x16x32_bf16 v[60:63], v[12:15], v[130:133], v[60:63]
	v_mfma_f32_16x16x32_bf16 v[94:97], v[98:101], v[126:129], v[94:97]
	v_mfma_f32_16x16x32_bf16 v[0:3], v[12:15], v[138:141], v[0:3]
	v_mfma_f32_16x16x32_bf16 v[4:7], v[102:105], v[138:141], v[4:7]
	v_mfma_f32_16x16x32_bf16 v[110:113], v[12:15], v[114:117], v[110:113]
	v_mfma_f32_16x16x32_bf16 v[94:97], v[102:105], v[130:133], v[94:97]
	s_setprio 0
	s_barrier
	ds_read_b128 v[8:11], v90
	ds_read_b128 v[12:15], v90 offset:1024
	ds_read_b128 v[98:101], v90 offset:2048
	ds_read_b128 v[102:105], v90 offset:3072
	s_add_u32 s2, s44, 0x10180
	s_addc_u32 s3, s45, 0
	s_mov_b32 m0, s59
	v_lshl_add_u64 v[142:143], s[2:3], 0, v[64:65]
	ds_read_b128 v[106:109], v91
	ds_read_b128 v[114:117], v91 offset:1024
	ds_read_b128 v[118:121], v91 offset:2048
	ds_read_b128 v[122:125], v91 offset:3072
	ds_read_b128 v[126:129], v91 offset:4096
	ds_read_b128 v[130:133], v91 offset:5120
	ds_read_b128 v[134:137], v91 offset:6144
	ds_read_b128 v[138:141], v91 offset:7168
	global_load_lds_dwordx4 v[142:143], off
	v_lshl_add_u64 v[142:143], s[2:3], 0, v[68:69]
	s_mov_b32 m0, s68
	s_nop 0
	global_load_lds_dwordx4 v[142:143], off
	s_waitcnt vmcnt(8)
	s_waitcnt lgkmcnt(0)
	s_barrier
	s_setprio 1
	v_mfma_f32_16x16x32_bf16 v[36:39], v[8:11], v[134:137], v[36:39]
	v_mfma_f32_16x16x32_bf16 v[48:51], v[8:11], v[106:109], v[48:51]
	v_mfma_f32_16x16x32_bf16 v[16:19], v[98:101], v[106:109], v[16:19]
	v_mfma_f32_16x16x32_bf16 v[20:23], v[8:11], v[118:121], v[20:23]
	v_mfma_f32_16x16x32_bf16 v[24:27], v[98:101], v[118:121], v[24:27]
	v_mfma_f32_16x16x32_bf16 v[28:31], v[8:11], v[126:129], v[28:31]
	v_mfma_f32_16x16x32_bf16 v[32:35], v[98:101], v[126:129], v[32:35]
	v_mfma_f32_16x16x32_bf16 v[106:109], v[12:15], v[138:141], v[36:39]
	v_mfma_f32_16x16x32_bf16 v[36:39], v[98:101], v[134:137], v[40:43]
	v_mfma_f32_16x16x32_bf16 v[48:51], v[12:15], v[114:117], v[48:51]
	v_mfma_f32_16x16x32_bf16 v[16:19], v[102:105], v[114:117], v[16:19]
	v_mfma_f32_16x16x32_bf16 v[20:23], v[12:15], v[122:125], v[20:23]
	v_mfma_f32_16x16x32_bf16 v[24:27], v[102:105], v[122:125], v[24:27]
	v_mfma_f32_16x16x32_bf16 v[28:31], v[12:15], v[130:133], v[28:31]
	v_mfma_f32_16x16x32_bf16 v[32:35], v[102:105], v[130:133], v[32:35]
	v_mfma_f32_16x16x32_bf16 v[40:43], v[102:105], v[138:141], v[36:39]
	s_setprio 0
	s_barrier
	s_mov_b32 m0, s69
	v_lshl_add_u64 v[154:155], s[46:47], 0, v[66:67]
	s_add_u32 s2, s46, 0x10000
	ds_read_b128 v[36:39], v91 offset:16384
	ds_read_b128 v[114:117], v91 offset:17408
	ds_read_b128 v[118:121], v91 offset:18432
	ds_read_b128 v[122:125], v91 offset:19456
	ds_read_b128 v[126:129], v91 offset:20480
	ds_read_b128 v[130:133], v91 offset:21504
	ds_read_b128 v[134:137], v91 offset:22528
	ds_read_b128 v[138:141], v91 offset:23552
	global_load_lds_dwordx4 v[154:155], off
	v_lshl_add_u64 v[156:157], s[46:47], 0, v[70:71]
	s_mov_b32 m0, s70
	s_addc_u32 s3, s47, 0
	global_load_lds_dwordx4 v[156:157], off
	v_lshl_add_u64 v[142:143], s[2:3], 0, v[66:67]
	s_mov_b32 m0, s33
	v_lshl_add_u64 v[158:159], s[48:49], 0, v[64:65]
	global_load_lds_dwordx4 v[142:143], off
	v_lshl_add_u64 v[142:143], s[2:3], 0, v[70:71]
	s_mov_b32 m0, s60
	v_lshl_add_u64 v[160:161], s[48:49], 0, v[68:69]
	global_load_lds_dwordx4 v[142:143], off
	s_mov_b32 m0, s31
	s_nop 0
	global_load_lds_dwordx4 v[158:159], off
	s_mov_b32 m0, s61
	s_nop 0
	global_load_lds_dwordx4 v[160:161], off
	s_waitcnt vmcnt(8)
	s_waitcnt lgkmcnt(0)
	s_barrier
	s_setprio 1
	v_mfma_f32_16x16x32_bf16 v[110:113], v[8:11], v[36:39], v[110:113]
	v_mfma_f32_16x16x32_bf16 v[36:39], v[98:101], v[36:39], v[44:47]
	v_mfma_f32_16x16x32_bf16 v[110:113], v[12:15], v[114:117], v[110:113]
	v_mfma_f32_16x16x32_bf16 v[114:117], v[102:105], v[114:117], v[36:39]
	v_mfma_f32_16x16x32_bf16 v[36:39], v[8:11], v[118:121], v[52:55]
	v_mfma_f32_16x16x32_bf16 v[142:145], v[12:15], v[122:125], v[36:39]
	v_mfma_f32_16x16x32_bf16 v[36:39], v[98:101], v[118:121], v[56:59]
	v_mfma_f32_16x16x32_bf16 v[118:121], v[102:105], v[122:125], v[36:39]
	v_mfma_f32_16x16x32_bf16 v[36:39], v[8:11], v[126:129], v[60:63]
	v_mfma_f32_16x16x32_bf16 v[0:3], v[8:11], v[134:137], v[0:3]
	v_mfma_f32_16x16x32_bf16 v[122:125], v[12:15], v[130:133], v[36:39]
	v_mfma_f32_16x16x32_bf16 v[36:39], v[98:101], v[126:129], v[94:97]
	v_mfma_f32_16x16x32_bf16 v[0:3], v[12:15], v[138:141], v[0:3]
	v_mfma_f32_16x16x32_bf16 v[4:7], v[98:101], v[134:137], v[4:7]
	v_mfma_f32_16x16x32_bf16 v[94:97], v[102:105], v[130:133], v[36:39]
	v_mfma_f32_16x16x32_bf16 v[98:101], v[102:105], v[138:141], v[4:7]
	s_setprio 0
	s_barrier
	s_nop 1
	ds_read_b128 v[4:7], v92
	ds_read_b128 v[102:105], v92 offset:1024
	ds_read_b128 v[126:129], v92 offset:2048
	ds_read_b128 v[130:133], v92 offset:3072
	s_add_u32 s2, s48, 0x10000
	s_addc_u32 s3, s49, 0
	s_mov_b32 m0, s62
	v_lshl_add_u64 v[52:53], s[2:3], 0, v[64:65]
	ds_read_b128 v[8:11], v91 offset:32768
	ds_read_b128 v[12:15], v91 offset:33792
	ds_read_b128 v[36:39], v91 offset:34816
	ds_read_b128 v[44:47], v91 offset:35840
	ds_read_b128 v[134:137], v91 offset:36864
	ds_read_b128 v[138:141], v91 offset:37888
	ds_read_b128 v[146:149], v91 offset:38912
	ds_read_b128 v[150:153], v91 offset:39936
	global_load_lds_dwordx4 v[52:53], off
	v_lshl_add_u64 v[52:53], s[2:3], 0, v[68:69]
	s_mov_b32 m0, s63
	s_nop 0
	global_load_lds_dwordx4 v[52:53], off
	s_waitcnt vmcnt(8)
	s_waitcnt lgkmcnt(0)
	s_barrier
	s_setprio 1
	v_mfma_f32_16x16x32_bf16 v[48:51], v[4:7], v[8:11], v[48:51]
	v_mfma_f32_16x16x32_bf16 v[8:11], v[126:129], v[8:11], v[16:19]
	v_mfma_f32_16x16x32_bf16 v[56:59], v[130:133], v[12:15], v[8:11]
	v_mfma_f32_16x16x32_bf16 v[8:11], v[4:7], v[36:39], v[20:23]
	v_mfma_f32_16x16x32_bf16 v[52:55], v[102:105], v[44:47], v[8:11]
	v_mfma_f32_16x16x32_bf16 v[8:11], v[126:129], v[36:39], v[24:27]
	v_mfma_f32_16x16x32_bf16 v[60:63], v[102:105], v[12:15], v[48:51]
	v_mfma_f32_16x16x32_bf16 v[48:51], v[130:133], v[44:47], v[8:11]
	v_mfma_f32_16x16x32_bf16 v[8:11], v[4:7], v[134:137], v[28:31]
	v_mfma_f32_16x16x32_bf16 v[44:47], v[102:105], v[138:141], v[8:11]
	v_mfma_f32_16x16x32_bf16 v[8:11], v[126:129], v[134:137], v[32:35]
	v_mfma_f32_16x16x32_bf16 v[36:39], v[130:133], v[138:141], v[8:11]
	v_mfma_f32_16x16x32_bf16 v[8:11], v[4:7], v[146:149], v[106:109]
	v_mfma_f32_16x16x32_bf16 v[32:35], v[102:105], v[150:153], v[8:11]
	v_mfma_f32_16x16x32_bf16 v[8:11], v[126:129], v[146:149], v[40:43]
	v_mfma_f32_16x16x32_bf16 v[24:27], v[130:133], v[150:153], v[8:11]
	s_setprio 0
	s_barrier
	s_mov_b32 m0, s71
	v_lshl_add_u64 v[20:21], v[154:155], 0, s[22:23]
	s_add_u32 s2, s46, 0x10080
	ds_read_b128 v[8:11], v91 offset:49152
	ds_read_b128 v[12:15], v91 offset:50176
	ds_read_b128 v[16:19], v91 offset:51200
	ds_read_b128 v[106:109], v91 offset:52224
	ds_read_b128 v[134:137], v91 offset:53248
	ds_read_b128 v[138:141], v91 offset:54272
	ds_read_b128 v[146:149], v91 offset:55296
	ds_read_b128 v[150:153], v91 offset:56320
	global_load_lds_dwordx4 v[20:21], off
	v_lshl_add_u64 v[20:21], v[156:157], 0, s[22:23]
	s_mov_b32 m0, s72
	s_addc_u32 s3, s47, 0
	global_load_lds_dwordx4 v[20:21], off
	v_lshl_add_u64 v[20:21], s[2:3], 0, v[66:67]
	s_mov_b32 m0, s66
	s_nop 0
	global_load_lds_dwordx4 v[20:21], off
	v_lshl_add_u64 v[20:21], s[2:3], 0, v[70:71]
	s_mov_b32 m0, s67
	s_nop 0
	global_load_lds_dwordx4 v[20:21], off
	v_lshl_add_u64 v[20:21], v[158:159], 0, s[22:23]
	s_mov_b32 m0, s64
	s_nop 0
	global_load_lds_dwordx4 v[20:21], off
	v_lshl_add_u64 v[20:21], v[160:161], 0, s[22:23]
	s_mov_b32 m0, s65
	s_nop 0
	global_load_lds_dwordx4 v[20:21], off
	s_waitcnt vmcnt(8)
	s_waitcnt lgkmcnt(0)
	s_barrier
	s_setprio 1
	v_mfma_f32_16x16x32_bf16 v[20:23], v[4:7], v[8:11], v[110:113]
	v_mfma_f32_16x16x32_bf16 v[8:11], v[126:129], v[8:11], v[114:117]
	v_mfma_f32_16x16x32_bf16 v[28:31], v[130:133], v[12:15], v[8:11]
	v_mfma_f32_16x16x32_bf16 v[8:11], v[4:7], v[16:19], v[142:145]
	v_mfma_f32_16x16x32_bf16 v[40:43], v[102:105], v[12:15], v[20:23]
	v_mfma_f32_16x16x32_bf16 v[20:23], v[102:105], v[106:109], v[8:11]
	v_mfma_f32_16x16x32_bf16 v[8:11], v[126:129], v[16:19], v[118:121]
	v_mfma_f32_16x16x32_bf16 v[16:19], v[130:133], v[106:109], v[8:11]
	v_mfma_f32_16x16x32_bf16 v[8:11], v[4:7], v[134:137], v[122:125]
	v_mfma_f32_16x16x32_bf16 v[0:3], v[4:7], v[146:149], v[0:3]
	v_mfma_f32_16x16x32_bf16 v[12:15], v[102:105], v[138:141], v[8:11]
	v_mfma_f32_16x16x32_bf16 v[8:11], v[126:129], v[134:137], v[94:97]
	v_mfma_f32_16x16x32_bf16 v[4:7], v[102:105], v[150:153], v[0:3]
	v_mfma_f32_16x16x32_bf16 v[0:3], v[126:129], v[146:149], v[98:101]
	v_mfma_f32_16x16x32_bf16 v[8:11], v[130:133], v[138:141], v[8:11]
	v_mfma_f32_16x16x32_bf16 v[0:3], v[130:133], v[150:153], v[0:3]
	s_setprio 0
	s_barrier
	s_and_b64 vcc, exec, s[4:5]
	s_cbranch_vccnz .LBB0_401
	s_barrier

.LBB0_424:
	ds_read_b128 v[32:35], v165
	ds_read_b128 v[36:39], v165 offset:1024
	ds_read_b128 v[48:51], v165 offset:2048
	ds_read_b128 v[52:55], v165 offset:3072
	ds_read_b128 v[156:159], v166
	ds_read_b128 v[168:171], v166 offset:1024
	ds_read_b128 v[172:175], v166 offset:2048
	ds_read_b128 v[176:179], v166 offset:3072
	s_add_u32 s40, s38, 0xfff80080
	s_addc_u32 s41, s39, -1
	s_cmp_eq_u32 s64, 60
	s_cselect_b32 s43, s2, s41
	s_cselect_b32 s42, s3, s40
	s_cselect_b32 s41, s29, s63
	s_cselect_b32 s40, s31, s33
	v_lshl_add_u64 v[160:161], s[38:39], 0, v[152:153]
	s_add_i32 m0, s47, 0xc000
	ds_read_b128 v[180:183], v167
	ds_read_b128 v[184:187], v167 offset:1024
	ds_read_b128 v[188:191], v167 offset:2048
	ds_read_b128 v[192:195], v167 offset:3072
	ds_read_b128 v[196:199], v167 offset:4096
	ds_read_b128 v[200:203], v167 offset:5120
	ds_read_b128 v[204:207], v167 offset:6144
	ds_read_b128 v[210:213], v167 offset:7168
	global_load_lds_dwordx4 v[160:161], off
	v_lshl_add_u64 v[160:161], s[38:39], 0, v[154:155]
	s_add_i32 m0, s47, 0xe000
	s_nop 0
	global_load_lds_dwordx4 v[160:161], off
	s_waitcnt vmcnt(8)
	s_waitcnt lgkmcnt(0)
	s_barrier
	s_setprio 1
	v_mfma_f32_16x16x32_bf16 v[140:143], v[32:35], v[180:183], v[140:143]
	v_mfma_f32_16x16x32_bf16 v[136:139], v[48:51], v[180:183], v[136:139]
	v_mfma_f32_16x16x32_bf16 v[124:127], v[32:35], v[188:191], v[124:127]
	v_mfma_f32_16x16x32_bf16 v[120:123], v[48:51], v[188:191], v[120:123]
	v_mfma_f32_16x16x32_bf16 v[108:111], v[32:35], v[196:199], v[108:111]
	v_mfma_f32_16x16x32_bf16 v[104:107], v[48:51], v[196:199], v[104:107]
	v_mfma_f32_16x16x32_bf16 v[92:95], v[32:35], v[204:207], v[92:95]
	v_mfma_f32_16x16x32_bf16 v[88:91], v[48:51], v[204:207], v[88:91]
	v_mfma_f32_16x16x32_bf16 v[140:143], v[36:39], v[184:187], v[140:143]
	v_mfma_f32_16x16x32_bf16 v[136:139], v[52:55], v[184:187], v[136:139]
	v_mfma_f32_16x16x32_bf16 v[124:127], v[36:39], v[192:195], v[124:127]
	v_mfma_f32_16x16x32_bf16 v[120:123], v[52:55], v[192:195], v[120:123]
	v_mfma_f32_16x16x32_bf16 v[108:111], v[36:39], v[200:203], v[108:111]
	v_mfma_f32_16x16x32_bf16 v[104:107], v[52:55], v[200:203], v[104:107]
	v_mfma_f32_16x16x32_bf16 v[92:95], v[36:39], v[210:213], v[92:95]
	v_mfma_f32_16x16x32_bf16 v[88:91], v[52:55], v[210:213], v[88:91]
	v_mfma_f32_16x16x32_bf16 v[132:135], v[156:159], v[180:183], v[132:135]
	v_mfma_f32_16x16x32_bf16 v[128:131], v[172:175], v[180:183], v[128:131]
	v_mfma_f32_16x16x32_bf16 v[116:119], v[156:159], v[188:191], v[116:119]
	v_mfma_f32_16x16x32_bf16 v[112:115], v[172:175], v[188:191], v[112:115]
	v_mfma_f32_16x16x32_bf16 v[100:103], v[156:159], v[196:199], v[100:103]
	v_mfma_f32_16x16x32_bf16 v[96:99], v[172:175], v[196:199], v[96:99]
	v_mfma_f32_16x16x32_bf16 v[84:87], v[156:159], v[204:207], v[84:87]
	v_mfma_f32_16x16x32_bf16 v[80:83], v[172:175], v[204:207], v[80:83]
	v_mfma_f32_16x16x32_bf16 v[132:135], v[168:171], v[184:187], v[132:135]
	v_mfma_f32_16x16x32_bf16 v[128:131], v[176:179], v[184:187], v[128:131]
	v_mfma_f32_16x16x32_bf16 v[116:119], v[168:171], v[192:195], v[116:119]
	v_mfma_f32_16x16x32_bf16 v[112:115], v[176:179], v[192:195], v[112:115]
	v_mfma_f32_16x16x32_bf16 v[100:103], v[168:171], v[200:203], v[100:103]
	v_mfma_f32_16x16x32_bf16 v[96:99], v[176:179], v[200:203], v[96:99]
	v_mfma_f32_16x16x32_bf16 v[84:87], v[168:171], v[210:213], v[84:87]
	v_mfma_f32_16x16x32_bf16 v[80:83], v[176:179], v[210:213], v[80:83]
	s_setprio 0
	s_barrier
	s_add_i32 s65, s60, s93
	v_lshl_add_u64 v[160:161], s[40:41], 0, v[146:147]
	s_mov_b32 m0, s65
	ds_read_b128 v[180:183], v167 offset:16384
	ds_read_b128 v[184:187], v167 offset:17408
	ds_read_b128 v[188:191], v167 offset:18432
	ds_read_b128 v[192:195], v167 offset:19456
	ds_read_b128 v[196:199], v167 offset:20480
	ds_read_b128 v[200:203], v167 offset:21504
	ds_read_b128 v[204:207], v167 offset:22528
	ds_read_b128 v[210:213], v167 offset:23552
	global_load_lds_dwordx4 v[160:161], off
	s_add_i32 m0, s65, 0x2000
	s_add_u32 s66, s40, 0x100000
	v_lshl_add_u64 v[214:215], s[40:41], 0, v[150:151]
	s_addc_u32 s67, s41, 0
	s_add_i32 s65, s61, s93
	global_load_lds_dwordx4 v[214:215], off
	v_lshl_add_u64 v[216:217], s[66:67], 0, v[146:147]
	s_mov_b32 m0, s65
	v_lshl_add_u64 v[218:219], s[42:43], 0, v[148:149]
	global_load_lds_dwordx4 v[216:217], off
	v_lshl_add_u64 v[216:217], s[66:67], 0, v[150:151]
	s_add_i32 m0, s65, 0x2000
	s_nop 0
	global_load_lds_dwordx4 v[216:217], off
	v_lshl_add_u64 v[216:217], s[42:43], 0, v[144:145]
	s_mov_b32 m0, s47
	s_nop 0
	global_load_lds_dwordx4 v[216:217], off
	s_mov_b32 m0, s48
	s_nop 0
	global_load_lds_dwordx4 v[218:219], off
	s_waitcnt vmcnt(8)
	s_waitcnt lgkmcnt(0)
	s_barrier
	s_setprio 1
	v_mfma_f32_16x16x32_bf16 v[76:79], v[32:35], v[180:183], v[76:79]
	v_mfma_f32_16x16x32_bf16 v[72:75], v[48:51], v[180:183], v[72:75]
	v_mfma_f32_16x16x32_bf16 v[60:63], v[32:35], v[188:191], v[60:63]
	v_mfma_f32_16x16x32_bf16 v[56:59], v[48:51], v[188:191], v[56:59]
	v_mfma_f32_16x16x32_bf16 v[28:31], v[32:35], v[196:199], v[28:31]
	v_mfma_f32_16x16x32_bf16 v[24:27], v[48:51], v[196:199], v[24:27]
	v_mfma_f32_16x16x32_bf16 v[12:15], v[32:35], v[204:207], v[12:15]
	v_mfma_f32_16x16x32_bf16 v[8:11], v[48:51], v[204:207], v[8:11]
	v_mfma_f32_16x16x32_bf16 v[76:79], v[36:39], v[184:187], v[76:79]
	v_mfma_f32_16x16x32_bf16 v[72:75], v[52:55], v[184:187], v[72:75]
	v_mfma_f32_16x16x32_bf16 v[60:63], v[36:39], v[192:195], v[60:63]
	v_mfma_f32_16x16x32_bf16 v[56:59], v[52:55], v[192:195], v[56:59]
	v_mfma_f32_16x16x32_bf16 v[28:31], v[36:39], v[200:203], v[28:31]
	v_mfma_f32_16x16x32_bf16 v[24:27], v[52:55], v[200:203], v[24:27]
	v_mfma_f32_16x16x32_bf16 v[12:15], v[36:39], v[210:213], v[12:15]
	v_mfma_f32_16x16x32_bf16 v[8:11], v[52:55], v[210:213], v[8:11]
	v_mfma_f32_16x16x32_bf16 v[44:47], v[156:159], v[188:191], v[44:47]
	v_mfma_f32_16x16x32_bf16 v[40:43], v[172:175], v[188:191], v[40:43]
	v_mfma_f32_16x16x32_bf16 v[20:23], v[156:159], v[196:199], v[20:23]
	v_mfma_f32_16x16x32_bf16 v[16:19], v[172:175], v[196:199], v[16:19]
	v_mfma_f32_16x16x32_bf16 v[4:7], v[156:159], v[204:207], v[4:7]
	v_mfma_f32_16x16x32_bf16 v[0:3], v[172:175], v[204:207], v[0:3]
	v_mfma_f32_16x16x32_bf16 v[32:35], v[156:159], v[180:183], v[68:71]
	v_mfma_f32_16x16x32_bf16 v[36:39], v[172:175], v[180:183], v[64:67]
	v_mfma_f32_16x16x32_bf16 v[44:47], v[168:171], v[192:195], v[44:47]
	v_mfma_f32_16x16x32_bf16 v[40:43], v[176:179], v[192:195], v[40:43]
	v_mfma_f32_16x16x32_bf16 v[20:23], v[168:171], v[200:203], v[20:23]
	v_mfma_f32_16x16x32_bf16 v[16:19], v[176:179], v[200:203], v[16:19]
	v_mfma_f32_16x16x32_bf16 v[4:7], v[168:171], v[210:213], v[4:7]
	v_mfma_f32_16x16x32_bf16 v[0:3], v[176:179], v[210:213], v[0:3]
	v_mfma_f32_16x16x32_bf16 v[32:35], v[168:171], v[184:187], v[32:35]
	v_mfma_f32_16x16x32_bf16 v[36:39], v[176:179], v[184:187], v[36:39]
	s_setprio 0
	s_barrier
	s_add_i32 s65, 0, 0x18000
	s_add_i32 s66, 0, 0x1c000
	v_add_u32_e32 v68, s65, v163
	v_add_u32_e32 v176, s66, v163
	ds_read_b128 v[48:51], v68
	ds_read_b128 v[52:55], v68 offset:1024
	ds_read_b128 v[64:67], v68 offset:2048
	ds_read_b128 v[68:71], v68 offset:3072
	ds_read_b128 v[156:159], v176
	ds_read_b128 v[168:171], v176 offset:1024
	ds_read_b128 v[172:175], v176 offset:2048
	ds_read_b128 v[176:179], v176 offset:3072
	s_add_u32 s42, s42, 0x80000
	s_addc_u32 s43, s43, 0
	s_mov_b32 m0, s49
	v_lshl_add_u64 v[220:221], s[42:43], 0, v[144:145]
	ds_read_b128 v[180:183], v167 offset:32768
	ds_read_b128 v[184:187], v167 offset:33792
	ds_read_b128 v[188:191], v167 offset:34816
	ds_read_b128 v[192:195], v167 offset:35840
	ds_read_b128 v[196:199], v167 offset:36864
	ds_read_b128 v[200:203], v167 offset:37888
	ds_read_b128 v[204:207], v167 offset:38912
	ds_read_b128 v[210:213], v167 offset:39936
	global_load_lds_dwordx4 v[220:221], off
	v_lshl_add_u64 v[220:221], s[42:43], 0, v[148:149]
	s_mov_b32 m0, s50
	s_nop 0
	global_load_lds_dwordx4 v[220:221], off
	s_waitcnt vmcnt(8)
	s_waitcnt lgkmcnt(0)
	s_barrier
	s_setprio 1
	v_mfma_f32_16x16x32_bf16 v[140:143], v[48:51], v[180:183], v[140:143]
	v_mfma_f32_16x16x32_bf16 v[136:139], v[64:67], v[180:183], v[136:139]
	v_mfma_f32_16x16x32_bf16 v[124:127], v[48:51], v[188:191], v[124:127]
	v_mfma_f32_16x16x32_bf16 v[120:123], v[64:67], v[188:191], v[120:123]
	v_mfma_f32_16x16x32_bf16 v[108:111], v[48:51], v[196:199], v[108:111]
	v_mfma_f32_16x16x32_bf16 v[104:107], v[64:67], v[196:199], v[104:107]
	v_mfma_f32_16x16x32_bf16 v[92:95], v[48:51], v[204:207], v[92:95]
	v_mfma_f32_16x16x32_bf16 v[88:91], v[64:67], v[204:207], v[88:91]
	v_mfma_f32_16x16x32_bf16 v[140:143], v[52:55], v[184:187], v[140:143]
	v_mfma_f32_16x16x32_bf16 v[136:139], v[68:71], v[184:187], v[136:139]
	v_mfma_f32_16x16x32_bf16 v[124:127], v[52:55], v[192:195], v[124:127]
	v_mfma_f32_16x16x32_bf16 v[120:123], v[68:71], v[192:195], v[120:123]
	v_mfma_f32_16x16x32_bf16 v[108:111], v[52:55], v[200:203], v[108:111]
	v_mfma_f32_16x16x32_bf16 v[104:107], v[68:71], v[200:203], v[104:107]
	v_mfma_f32_16x16x32_bf16 v[92:95], v[52:55], v[210:213], v[92:95]
	v_mfma_f32_16x16x32_bf16 v[88:91], v[68:71], v[210:213], v[88:91]
	v_mfma_f32_16x16x32_bf16 v[132:135], v[156:159], v[180:183], v[132:135]
	v_mfma_f32_16x16x32_bf16 v[128:131], v[172:175], v[180:183], v[128:131]
	v_mfma_f32_16x16x32_bf16 v[116:119], v[156:159], v[188:191], v[116:119]
	v_mfma_f32_16x16x32_bf16 v[112:115], v[172:175], v[188:191], v[112:115]
	v_mfma_f32_16x16x32_bf16 v[100:103], v[156:159], v[196:199], v[100:103]
	v_mfma_f32_16x16x32_bf16 v[96:99], v[172:175], v[196:199], v[96:99]
	v_mfma_f32_16x16x32_bf16 v[84:87], v[156:159], v[204:207], v[84:87]
	v_mfma_f32_16x16x32_bf16 v[80:83], v[172:175], v[204:207], v[80:83]
	v_mfma_f32_16x16x32_bf16 v[132:135], v[168:171], v[184:187], v[132:135]
	v_mfma_f32_16x16x32_bf16 v[128:131], v[176:179], v[184:187], v[128:131]
	v_mfma_f32_16x16x32_bf16 v[116:119], v[168:171], v[192:195], v[116:119]
	v_mfma_f32_16x16x32_bf16 v[112:115], v[176:179], v[192:195], v[112:115]
	v_mfma_f32_16x16x32_bf16 v[100:103], v[168:171], v[200:203], v[100:103]
	v_mfma_f32_16x16x32_bf16 v[96:99], v[176:179], v[200:203], v[96:99]
	v_mfma_f32_16x16x32_bf16 v[84:87], v[168:171], v[210:213], v[84:87]
	v_mfma_f32_16x16x32_bf16 v[80:83], v[176:179], v[210:213], v[80:83]
	s_setprio 0
	s_barrier
	s_add_i32 s42, s65, s93
	v_lshl_add_u64 v[160:161], v[160:161], 0, s[22:23]
	s_mov_b32 m0, s42
	ds_read_b128 v[180:183], v167 offset:49152
	ds_read_b128 v[184:187], v167 offset:50176
	ds_read_b128 v[188:191], v167 offset:51200
	ds_read_b128 v[192:195], v167 offset:52224
	ds_read_b128 v[196:199], v167 offset:53248
	ds_read_b128 v[200:203], v167 offset:54272
	ds_read_b128 v[204:207], v167 offset:55296
	ds_read_b128 v[210:213], v167 offset:56320
	global_load_lds_dwordx4 v[160:161], off
	s_add_i32 m0, s42, 0x2000
	s_add_u32 s40, s40, 0x100080
	v_lshl_add_u64 v[160:161], v[214:215], 0, s[22:23]
	s_addc_u32 s41, s41, 0
	s_add_i32 s42, s66, s93
	global_load_lds_dwordx4 v[160:161], off
	v_lshl_add_u64 v[160:161], s[40:41], 0, v[146:147]
	s_mov_b32 m0, s42
	s_nop 0
	global_load_lds_dwordx4 v[160:161], off
	v_lshl_add_u64 v[160:161], s[40:41], 0, v[150:151]
	s_add_i32 m0, s42, 0x2000
	s_nop 0
	global_load_lds_dwordx4 v[160:161], off
	v_lshl_add_u64 v[160:161], v[216:217], 0, s[22:23]
	s_mov_b32 m0, s51
	s_nop 0
	global_load_lds_dwordx4 v[160:161], off
	v_lshl_add_u64 v[160:161], v[218:219], 0, s[22:23]
	s_mov_b32 m0, s58
	s_nop 0
	global_load_lds_dwordx4 v[160:161], off
	s_waitcnt vmcnt(8)
	s_waitcnt lgkmcnt(0)
	s_barrier
	s_setprio 1
	v_mfma_f32_16x16x32_bf16 v[76:79], v[48:51], v[180:183], v[76:79]
	v_mfma_f32_16x16x32_bf16 v[72:75], v[64:67], v[180:183], v[72:75]
	v_mfma_f32_16x16x32_bf16 v[60:63], v[48:51], v[188:191], v[60:63]
	v_mfma_f32_16x16x32_bf16 v[56:59], v[64:67], v[188:191], v[56:59]
	v_mfma_f32_16x16x32_bf16 v[28:31], v[48:51], v[196:199], v[28:31]
	v_mfma_f32_16x16x32_bf16 v[24:27], v[64:67], v[196:199], v[24:27]
	v_mfma_f32_16x16x32_bf16 v[12:15], v[48:51], v[204:207], v[12:15]
	v_mfma_f32_16x16x32_bf16 v[8:11], v[64:67], v[204:207], v[8:11]
	v_mfma_f32_16x16x32_bf16 v[76:79], v[52:55], v[184:187], v[76:79]
	v_mfma_f32_16x16x32_bf16 v[72:75], v[68:71], v[184:187], v[72:75]
	v_mfma_f32_16x16x32_bf16 v[60:63], v[52:55], v[192:195], v[60:63]
	v_mfma_f32_16x16x32_bf16 v[56:59], v[68:71], v[192:195], v[56:59]
	v_mfma_f32_16x16x32_bf16 v[28:31], v[52:55], v[200:203], v[28:31]
	v_mfma_f32_16x16x32_bf16 v[24:27], v[68:71], v[200:203], v[24:27]
	v_mfma_f32_16x16x32_bf16 v[12:15], v[52:55], v[210:213], v[12:15]
	v_mfma_f32_16x16x32_bf16 v[8:11], v[68:71], v[210:213], v[8:11]
	v_mfma_f32_16x16x32_bf16 v[32:35], v[156:159], v[180:183], v[32:35]
	v_mfma_f32_16x16x32_bf16 v[68:71], v[168:171], v[184:187], v[32:35]
	v_mfma_f32_16x16x32_bf16 v[32:35], v[172:175], v[180:183], v[36:39]
	v_mfma_f32_16x16x32_bf16 v[64:67], v[176:179], v[184:187], v[32:35]
	v_mfma_f32_16x16x32_bf16 v[32:35], v[156:159], v[188:191], v[44:47]
	v_mfma_f32_16x16x32_bf16 v[44:47], v[168:171], v[192:195], v[32:35]
	v_mfma_f32_16x16x32_bf16 v[32:35], v[172:175], v[188:191], v[40:43]
	v_mfma_f32_16x16x32_bf16 v[20:23], v[156:159], v[196:199], v[20:23]
	v_mfma_f32_16x16x32_bf16 v[16:19], v[172:175], v[196:199], v[16:19]
	v_mfma_f32_16x16x32_bf16 v[4:7], v[156:159], v[204:207], v[4:7]
	v_mfma_f32_16x16x32_bf16 v[0:3], v[172:175], v[204:207], v[0:3]
	v_mfma_f32_16x16x32_bf16 v[40:43], v[176:179], v[192:195], v[32:35]
	v_mfma_f32_16x16x32_bf16 v[20:23], v[168:171], v[200:203], v[20:23]
	v_mfma_f32_16x16x32_bf16 v[16:19], v[176:179], v[200:203], v[16:19]
	v_mfma_f32_16x16x32_bf16 v[4:7], v[168:171], v[210:213], v[4:7]
	v_mfma_f32_16x16x32_bf16 v[0:3], v[176:179], v[210:213], v[0:3]
	s_setprio 0
	s_barrier
	s_add_i32 s64, s64, 2
	s_add_u32 s38, s38, 0x100
	s_addc_u32 s39, s39, 0
	s_add_u32 s33, s33, 0x100
	s_addc_u32 s63, s63, 0
	s_cmp_gt_u32 s64, 61
	s_cbranch_scc0 .LBB0_424
	s_and_b64 vcc, exec, s[24:25]
	s_cbranch_vccz .LBB0_427
	s_barrier

.LBB0_562:
	s_ashr_i32 s31, s30, 31
	s_lshl_b64 s[2:3], s[30:31], 17
	s_add_u32 s34, s4, s2
	s_addc_u32 s35, s5, s3
	ds_read_b128 v[0:3], v75
	ds_read_b128 v[4:7], v75 offset:1024
	ds_read_b128 v[8:11], v75 offset:2048
	ds_read_b128 v[12:15], v75 offset:3072
	s_and_b64 s[2:3], s[26:27], exec
	s_cselect_b32 s43, s35, s39
	s_cselect_b32 s42, s34, s38
	s_ashr_i32 s29, s28, 31
	s_lshl_b64 s[2:3], s[28:29], 17
	s_add_u32 s36, s8, s2
	s_addc_u32 s37, s9, s3
	s_and_b64 s[2:3], s[26:27], exec
	s_cselect_b32 s41, s37, s45
	s_cselect_b32 s40, s36, s44
	s_add_u32 s2, s38, 0x10080
	s_addc_u32 s3, s39, 0
	s_mov_b32 m0, s57
	v_lshl_add_u64 v[48:49], s[2:3], 0, v[64:65]
	ds_read_b128 v[16:19], v76
	ds_read_b128 v[20:23], v76 offset:1024
	ds_read_b128 v[24:27], v76 offset:2048
	ds_read_b128 v[28:31], v76 offset:3072
	ds_read_b128 v[32:35], v76 offset:4096
	ds_read_b128 v[36:39], v76 offset:5120
	ds_read_b128 v[40:43], v76 offset:6144
	ds_read_b128 v[44:47], v76 offset:7168
	global_load_lds_dwordx4 v[48:49], off
	v_lshl_add_u64 v[48:49], s[2:3], 0, v[68:69]
	s_mov_b32 m0, s59
	s_nop 0
	global_load_lds_dwordx4 v[48:49], off
	s_waitcnt vmcnt(8)
	s_waitcnt lgkmcnt(0)
	s_barrier
	s_setprio 1
	v_mfma_f32_16x16x32_bf16 v[48:51], v[0:3], v[16:19], 0
	v_mfma_f32_16x16x32_bf16 v[16:19], v[8:11], v[16:19], 0
	v_mfma_f32_16x16x32_bf16 v[48:51], v[4:7], v[20:23], v[48:51]
	v_mfma_f32_16x16x32_bf16 v[16:19], v[12:15], v[20:23], v[16:19]
	v_mfma_f32_16x16x32_bf16 v[20:23], v[0:3], v[24:27], 0
	v_mfma_f32_16x16x32_bf16 v[24:27], v[8:11], v[24:27], 0
	v_mfma_f32_16x16x32_bf16 v[20:23], v[4:7], v[28:31], v[20:23]
	v_mfma_f32_16x16x32_bf16 v[24:27], v[12:15], v[28:31], v[24:27]
	v_mfma_f32_16x16x32_bf16 v[28:31], v[0:3], v[32:35], 0
	v_mfma_f32_16x16x32_bf16 v[32:35], v[8:11], v[32:35], 0
	v_mfma_f32_16x16x32_bf16 v[28:31], v[4:7], v[36:39], v[28:31]
	v_mfma_f32_16x16x32_bf16 v[32:35], v[12:15], v[36:39], v[32:35]
	v_mfma_f32_16x16x32_bf16 v[36:39], v[0:3], v[40:43], 0
	v_mfma_f32_16x16x32_bf16 v[40:43], v[8:11], v[40:43], 0
	v_mfma_f32_16x16x32_bf16 v[36:39], v[4:7], v[44:47], v[36:39]
	v_mfma_f32_16x16x32_bf16 v[40:43], v[12:15], v[44:47], v[40:43]
	s_setprio 0
	s_barrier
	v_lshl_add_u64 v[126:127], s[44:45], 0, v[66:67]
	s_mov_b32 m0, s60
	v_lshl_add_u64 v[94:95], v[126:127], 0, s[22:23]
	v_lshl_add_u64 v[128:129], s[44:45], 0, v[70:71]
	s_add_u32 s2, s44, 0x10100
	ds_read_b128 v[44:47], v76 offset:16384
	ds_read_b128 v[52:55], v76 offset:17408
	ds_read_b128 v[56:59], v76 offset:18432
	ds_read_b128 v[60:63], v76 offset:19456
	ds_read_b128 v[78:81], v76 offset:20480
	ds_read_b128 v[82:85], v76 offset:21504
	ds_read_b128 v[86:89], v76 offset:22528
	ds_read_b128 v[90:93], v76 offset:23552
	global_load_lds_dwordx4 v[94:95], off
	v_lshl_add_u64 v[94:95], v[128:129], 0, s[22:23]
	s_mov_b32 m0, s61
	s_addc_u32 s3, s45, 0
	global_load_lds_dwordx4 v[94:95], off
	v_lshl_add_u64 v[94:95], s[2:3], 0, v[66:67]
	s_mov_b32 m0, s33
	v_lshl_add_u64 v[130:131], s[38:39], 0, v[64:65]
	global_load_lds_dwordx4 v[94:95], off
	v_lshl_add_u64 v[94:95], s[2:3], 0, v[70:71]
	s_mov_b32 m0, s46
	v_lshl_add_u64 v[132:133], s[38:39], 0, v[68:69]
	global_load_lds_dwordx4 v[94:95], off
	v_lshl_add_u64 v[94:95], v[130:131], 0, s[22:23]
	s_mov_b32 m0, s11
	s_nop 0
	global_load_lds_dwordx4 v[94:95], off
	v_lshl_add_u64 v[94:95], v[132:133], 0, s[22:23]
	s_mov_b32 m0, s47
	s_nop 0
	global_load_lds_dwordx4 v[94:95], off
	s_waitcnt vmcnt(8)
	s_waitcnt lgkmcnt(0)
	s_barrier
	s_setprio 1
	v_mfma_f32_16x16x32_bf16 v[94:97], v[0:3], v[44:47], 0
	v_mfma_f32_16x16x32_bf16 v[44:47], v[8:11], v[44:47], 0
	v_mfma_f32_16x16x32_bf16 v[94:97], v[4:7], v[52:55], v[94:97]
	v_mfma_f32_16x16x32_bf16 v[44:47], v[12:15], v[52:55], v[44:47]
	v_mfma_f32_16x16x32_bf16 v[52:55], v[0:3], v[56:59], 0
	v_mfma_f32_16x16x32_bf16 v[56:59], v[8:11], v[56:59], 0
	v_mfma_f32_16x16x32_bf16 v[52:55], v[4:7], v[60:63], v[52:55]
	v_mfma_f32_16x16x32_bf16 v[56:59], v[12:15], v[60:63], v[56:59]
	v_mfma_f32_16x16x32_bf16 v[60:63], v[0:3], v[78:81], 0
	v_mfma_f32_16x16x32_bf16 v[0:3], v[0:3], v[86:89], 0
	v_mfma_f32_16x16x32_bf16 v[60:63], v[4:7], v[82:85], v[60:63]
	v_mfma_f32_16x16x32_bf16 v[0:3], v[4:7], v[90:93], v[0:3]
	v_mfma_f32_16x16x32_bf16 v[4:7], v[8:11], v[86:89], 0
	v_mfma_f32_16x16x32_bf16 v[78:81], v[8:11], v[78:81], 0
	v_mfma_f32_16x16x32_bf16 v[4:7], v[12:15], v[90:93], v[4:7]
	v_mfma_f32_16x16x32_bf16 v[78:81], v[12:15], v[82:85], v[78:81]
	s_setprio 0
	s_barrier
	ds_read_b128 v[8:11], v77
	ds_read_b128 v[12:15], v77 offset:1024
	ds_read_b128 v[82:85], v77 offset:2048
	ds_read_b128 v[86:89], v77 offset:3072
	s_add_u32 s2, s38, 0x10100
	s_addc_u32 s3, s39, 0
	s_mov_b32 m0, s48
	v_lshl_add_u64 v[134:135], s[2:3], 0, v[64:65]
	ds_read_b128 v[90:93], v76 offset:32768
	ds_read_b128 v[98:101], v76 offset:33792
	ds_read_b128 v[102:105], v76 offset:34816
	ds_read_b128 v[106:109], v76 offset:35840
	ds_read_b128 v[110:113], v76 offset:36864
	ds_read_b128 v[114:117], v76 offset:37888
	ds_read_b128 v[118:121], v76 offset:38912
	ds_read_b128 v[122:125], v76 offset:39936
	global_load_lds_dwordx4 v[134:135], off
	v_lshl_add_u64 v[134:135], s[2:3], 0, v[68:69]
	s_mov_b32 m0, s49
	s_nop 0
	global_load_lds_dwordx4 v[134:135], off
	s_waitcnt vmcnt(8)
	s_waitcnt lgkmcnt(0)
	s_barrier
	s_setprio 1
	v_mfma_f32_16x16x32_bf16 v[48:51], v[8:11], v[90:93], v[48:51]
	v_mfma_f32_16x16x32_bf16 v[16:19], v[82:85], v[90:93], v[16:19]
	v_mfma_f32_16x16x32_bf16 v[20:23], v[8:11], v[102:105], v[20:23]
	v_mfma_f32_16x16x32_bf16 v[24:27], v[82:85], v[102:105], v[24:27]
	v_mfma_f32_16x16x32_bf16 v[28:31], v[8:11], v[110:113], v[28:31]
	v_mfma_f32_16x16x32_bf16 v[32:35], v[82:85], v[110:113], v[32:35]
	v_mfma_f32_16x16x32_bf16 v[36:39], v[8:11], v[118:121], v[36:39]
	v_mfma_f32_16x16x32_bf16 v[40:43], v[82:85], v[118:121], v[40:43]
	v_mfma_f32_16x16x32_bf16 v[48:51], v[12:15], v[98:101], v[48:51]
	v_mfma_f32_16x16x32_bf16 v[16:19], v[86:89], v[98:101], v[16:19]
	v_mfma_f32_16x16x32_bf16 v[20:23], v[12:15], v[106:109], v[20:23]
	v_mfma_f32_16x16x32_bf16 v[24:27], v[86:89], v[106:109], v[24:27]
	v_mfma_f32_16x16x32_bf16 v[28:31], v[12:15], v[114:117], v[28:31]
	v_mfma_f32_16x16x32_bf16 v[32:35], v[86:89], v[114:117], v[32:35]
	v_mfma_f32_16x16x32_bf16 v[36:39], v[12:15], v[122:125], v[36:39]
	v_mfma_f32_16x16x32_bf16 v[40:43], v[86:89], v[122:125], v[40:43]
	s_setprio 0
	s_barrier
	s_mov_b32 m0, s62
	v_lshl_add_u64 v[126:127], v[126:127], 0, s[24:25]
	s_add_u32 s2, s44, 0x10180
	ds_read_b128 v[90:93], v76 offset:49152
	ds_read_b128 v[98:101], v76 offset:50176
	ds_read_b128 v[102:105], v76 offset:51200
	ds_read_b128 v[106:109], v76 offset:52224
	ds_read_b128 v[110:113], v76 offset:53248
	ds_read_b128 v[114:117], v76 offset:54272
	ds_read_b128 v[118:121], v76 offset:55296
	ds_read_b128 v[122:125], v76 offset:56320
	global_load_lds_dwordx4 v[126:127], off
	v_lshl_add_u64 v[126:127], v[128:129], 0, s[24:25]
	s_mov_b32 m0, s63
	s_addc_u32 s3, s45, 0
	global_load_lds_dwordx4 v[126:127], off
	v_lshl_add_u64 v[126:127], s[2:3], 0, v[66:67]
	s_mov_b32 m0, s54
	s_nop 0
	global_load_lds_dwordx4 v[126:127], off
	v_lshl_add_u64 v[126:127], s[2:3], 0, v[70:71]
	s_mov_b32 m0, s55
	s_nop 0
	global_load_lds_dwordx4 v[126:127], off
	v_lshl_add_u64 v[126:127], v[130:131], 0, s[24:25]
	s_mov_b32 m0, s50
	s_nop 0
	global_load_lds_dwordx4 v[126:127], off
	v_lshl_add_u64 v[126:127], v[132:133], 0, s[24:25]
	s_mov_b32 m0, s51
	s_nop 0
	global_load_lds_dwordx4 v[126:127], off
	s_waitcnt vmcnt(8)
	s_waitcnt lgkmcnt(0)
	s_barrier
	s_setprio 1
	v_mfma_f32_16x16x32_bf16 v[44:47], v[82:85], v[90:93], v[44:47]
	v_mfma_f32_16x16x32_bf16 v[52:55], v[8:11], v[102:105], v[52:55]
	v_mfma_f32_16x16x32_bf16 v[56:59], v[82:85], v[102:105], v[56:59]
	v_mfma_f32_16x16x32_bf16 v[60:63], v[8:11], v[110:113], v[60:63]
	v_mfma_f32_16x16x32_bf16 v[0:3], v[8:11], v[118:121], v[0:3]
	v_mfma_f32_16x16x32_bf16 v[4:7], v[82:85], v[118:121], v[4:7]
	v_mfma_f32_16x16x32_bf16 v[94:97], v[8:11], v[90:93], v[94:97]
	v_mfma_f32_16x16x32_bf16 v[44:47], v[86:89], v[98:101], v[44:47]
	v_mfma_f32_16x16x32_bf16 v[52:55], v[12:15], v[106:109], v[52:55]
	v_mfma_f32_16x16x32_bf16 v[56:59], v[86:89], v[106:109], v[56:59]
	v_mfma_f32_16x16x32_bf16 v[60:63], v[12:15], v[114:117], v[60:63]
	v_mfma_f32_16x16x32_bf16 v[78:81], v[82:85], v[110:113], v[78:81]
	v_mfma_f32_16x16x32_bf16 v[0:3], v[12:15], v[122:125], v[0:3]
	v_mfma_f32_16x16x32_bf16 v[4:7], v[86:89], v[122:125], v[4:7]
	v_mfma_f32_16x16x32_bf16 v[94:97], v[12:15], v[98:101], v[94:97]
	v_mfma_f32_16x16x32_bf16 v[78:81], v[86:89], v[114:117], v[78:81]
	s_setprio 0
	s_barrier
	ds_read_b128 v[8:11], v75
	ds_read_b128 v[12:15], v75 offset:1024
	ds_read_b128 v[82:85], v75 offset:2048
	ds_read_b128 v[86:89], v75 offset:3072
	s_add_u32 s2, s38, 0x10180
	s_addc_u32 s3, s39, 0
	s_mov_b32 m0, s57
	v_lshl_add_u64 v[126:127], s[2:3], 0, v[64:65]
	ds_read_b128 v[90:93], v76
	ds_read_b128 v[98:101], v76 offset:1024
	ds_read_b128 v[102:105], v76 offset:2048
	ds_read_b128 v[106:109], v76 offset:3072
	ds_read_b128 v[110:113], v76 offset:4096
	ds_read_b128 v[114:117], v76 offset:5120
	ds_read_b128 v[118:121], v76 offset:6144
	ds_read_b128 v[122:125], v76 offset:7168
	global_load_lds_dwordx4 v[126:127], off
	v_lshl_add_u64 v[126:127], s[2:3], 0, v[68:69]
	s_mov_b32 m0, s59
	s_nop 0
	global_load_lds_dwordx4 v[126:127], off
	s_waitcnt vmcnt(8)
	s_waitcnt lgkmcnt(0)
	s_barrier
	s_setprio 1
	v_mfma_f32_16x16x32_bf16 v[48:51], v[8:11], v[90:93], v[48:51]
	v_mfma_f32_16x16x32_bf16 v[16:19], v[82:85], v[90:93], v[16:19]
	v_mfma_f32_16x16x32_bf16 v[20:23], v[8:11], v[102:105], v[20:23]
	v_mfma_f32_16x16x32_bf16 v[24:27], v[82:85], v[102:105], v[24:27]
	v_mfma_f32_16x16x32_bf16 v[28:31], v[8:11], v[110:113], v[28:31]
	v_mfma_f32_16x16x32_bf16 v[32:35], v[82:85], v[110:113], v[32:35]
	v_mfma_f32_16x16x32_bf16 v[36:39], v[8:11], v[118:121], v[36:39]
	v_mfma_f32_16x16x32_bf16 v[48:51], v[12:15], v[98:101], v[48:51]
	v_mfma_f32_16x16x32_bf16 v[16:19], v[86:89], v[98:101], v[16:19]
	v_mfma_f32_16x16x32_bf16 v[20:23], v[12:15], v[106:109], v[20:23]
	v_mfma_f32_16x16x32_bf16 v[24:27], v[86:89], v[106:109], v[24:27]
	v_mfma_f32_16x16x32_bf16 v[28:31], v[12:15], v[114:117], v[28:31]
	v_mfma_f32_16x16x32_bf16 v[32:35], v[86:89], v[114:117], v[32:35]
	v_mfma_f32_16x16x32_bf16 v[36:39], v[12:15], v[122:125], v[36:39]
	v_mfma_f32_16x16x32_bf16 v[40:43], v[82:85], v[118:121], v[40:43]
	v_mfma_f32_16x16x32_bf16 v[90:93], v[86:89], v[122:125], v[40:43]
	s_setprio 0
	s_barrier
	s_mov_b32 m0, s60
	v_lshl_add_u64 v[138:139], s[40:41], 0, v[66:67]
	s_add_u32 s2, s40, 0x10000
	ds_read_b128 v[40:43], v76 offset:16384
	ds_read_b128 v[98:101], v76 offset:17408
	ds_read_b128 v[102:105], v76 offset:18432
	ds_read_b128 v[106:109], v76 offset:19456
	ds_read_b128 v[110:113], v76 offset:20480
	ds_read_b128 v[114:117], v76 offset:21504
	ds_read_b128 v[118:121], v76 offset:22528
	ds_read_b128 v[122:125], v76 offset:23552
	global_load_lds_dwordx4 v[138:139], off
	v_lshl_add_u64 v[140:141], s[40:41], 0, v[70:71]
	s_mov_b32 m0, s61
	s_addc_u32 s3, s41, 0
	global_load_lds_dwordx4 v[140:141], off
	v_lshl_add_u64 v[126:127], s[2:3], 0, v[66:67]
	s_mov_b32 m0, s33
	v_lshl_add_u64 v[142:143], s[42:43], 0, v[64:65]
	global_load_lds_dwordx4 v[126:127], off
	v_lshl_add_u64 v[126:127], s[2:3], 0, v[70:71]
	s_mov_b32 m0, s46
	v_lshl_add_u64 v[144:145], s[42:43], 0, v[68:69]
	global_load_lds_dwordx4 v[126:127], off
	s_mov_b32 m0, s11
	s_nop 0
	global_load_lds_dwordx4 v[142:143], off
	s_mov_b32 m0, s47
	s_nop 0
	global_load_lds_dwordx4 v[144:145], off
	s_waitcnt vmcnt(8)
	s_waitcnt lgkmcnt(0)
	s_barrier
	s_setprio 1
	v_mfma_f32_16x16x32_bf16 v[94:97], v[8:11], v[40:43], v[94:97]
	v_mfma_f32_16x16x32_bf16 v[40:43], v[82:85], v[40:43], v[44:47]
	v_mfma_f32_16x16x32_bf16 v[94:97], v[12:15], v[98:101], v[94:97]
	v_mfma_f32_16x16x32_bf16 v[98:101], v[86:89], v[98:101], v[40:43]
	v_mfma_f32_16x16x32_bf16 v[40:43], v[8:11], v[102:105], v[52:55]
	v_mfma_f32_16x16x32_bf16 v[126:129], v[12:15], v[106:109], v[40:43]
	v_mfma_f32_16x16x32_bf16 v[40:43], v[82:85], v[102:105], v[56:59]
	v_mfma_f32_16x16x32_bf16 v[102:105], v[86:89], v[106:109], v[40:43]
	v_mfma_f32_16x16x32_bf16 v[40:43], v[8:11], v[110:113], v[60:63]
	v_mfma_f32_16x16x32_bf16 v[0:3], v[8:11], v[118:121], v[0:3]
	v_mfma_f32_16x16x32_bf16 v[106:109], v[12:15], v[114:117], v[40:43]
	v_mfma_f32_16x16x32_bf16 v[40:43], v[82:85], v[110:113], v[78:81]
	v_mfma_f32_16x16x32_bf16 v[0:3], v[12:15], v[122:125], v[0:3]
	v_mfma_f32_16x16x32_bf16 v[4:7], v[82:85], v[118:121], v[4:7]
	v_mfma_f32_16x16x32_bf16 v[78:81], v[86:89], v[114:117], v[40:43]
	v_mfma_f32_16x16x32_bf16 v[82:85], v[86:89], v[122:125], v[4:7]
	s_setprio 0
	s_barrier
	s_nop 1
	ds_read_b128 v[4:7], v77
	ds_read_b128 v[86:89], v77 offset:1024
	ds_read_b128 v[110:113], v77 offset:2048
	ds_read_b128 v[114:117], v77 offset:3072
	s_add_u32 s2, s42, 0x10000
	s_addc_u32 s3, s43, 0
	s_mov_b32 m0, s48
	v_lshl_add_u64 v[52:53], s[2:3], 0, v[64:65]
	ds_read_b128 v[8:11], v76 offset:32768
	ds_read_b128 v[12:15], v76 offset:33792
	ds_read_b128 v[40:43], v76 offset:34816
	ds_read_b128 v[44:47], v76 offset:35840
	ds_read_b128 v[118:121], v76 offset:36864
	ds_read_b128 v[122:125], v76 offset:37888
	ds_read_b128 v[130:133], v76 offset:38912
	ds_read_b128 v[134:137], v76 offset:39936
	global_load_lds_dwordx4 v[52:53], off
	v_lshl_add_u64 v[52:53], s[2:3], 0, v[68:69]
	s_mov_b32 m0, s49
	s_nop 0
	global_load_lds_dwordx4 v[52:53], off
	s_waitcnt vmcnt(8)
	s_waitcnt lgkmcnt(0)
	s_barrier
	s_setprio 1
	v_mfma_f32_16x16x32_bf16 v[48:51], v[4:7], v[8:11], v[48:51]
	v_mfma_f32_16x16x32_bf16 v[8:11], v[110:113], v[8:11], v[16:19]
	v_mfma_f32_16x16x32_bf16 v[56:59], v[114:117], v[12:15], v[8:11]
	v_mfma_f32_16x16x32_bf16 v[8:11], v[4:7], v[40:43], v[20:23]
	v_mfma_f32_16x16x32_bf16 v[52:55], v[86:89], v[44:47], v[8:11]
	v_mfma_f32_16x16x32_bf16 v[8:11], v[110:113], v[40:43], v[24:27]
	v_mfma_f32_16x16x32_bf16 v[60:63], v[86:89], v[12:15], v[48:51]
	v_mfma_f32_16x16x32_bf16 v[48:51], v[114:117], v[44:47], v[8:11]
	v_mfma_f32_16x16x32_bf16 v[8:11], v[4:7], v[118:121], v[28:31]
	v_mfma_f32_16x16x32_bf16 v[40:43], v[86:89], v[122:125], v[8:11]
	v_mfma_f32_16x16x32_bf16 v[8:11], v[110:113], v[118:121], v[32:35]
	v_mfma_f32_16x16x32_bf16 v[32:35], v[114:117], v[122:125], v[8:11]
	v_mfma_f32_16x16x32_bf16 v[8:11], v[4:7], v[130:133], v[36:39]
	v_mfma_f32_16x16x32_bf16 v[20:23], v[86:89], v[134:137], v[8:11]
	v_mfma_f32_16x16x32_bf16 v[8:11], v[110:113], v[130:133], v[90:93]
	v_mfma_f32_16x16x32_bf16 v[16:19], v[114:117], v[134:137], v[8:11]
	s_setprio 0
	s_barrier
	s_mov_b32 m0, s62
	v_lshl_add_u64 v[28:29], v[138:139], 0, s[6:7]
	s_add_u32 s2, s40, 0x10080
	ds_read_b128 v[8:11], v76 offset:49152
	ds_read_b128 v[12:15], v76 offset:50176
	ds_read_b128 v[24:27], v76 offset:51200
	ds_read_b128 v[90:93], v76 offset:52224
	ds_read_b128 v[118:121], v76 offset:53248
	ds_read_b128 v[122:125], v76 offset:54272
	ds_read_b128 v[130:133], v76 offset:55296
	ds_read_b128 v[134:137], v76 offset:56320
	global_load_lds_dwordx4 v[28:29], off
	v_lshl_add_u64 v[28:29], v[140:141], 0, s[6:7]
	s_mov_b32 m0, s63
	s_addc_u32 s3, s41, 0
	global_load_lds_dwordx4 v[28:29], off
	v_lshl_add_u64 v[28:29], s[2:3], 0, v[66:67]
	s_mov_b32 m0, s54
	s_nop 0
	global_load_lds_dwordx4 v[28:29], off
	v_lshl_add_u64 v[28:29], s[2:3], 0, v[70:71]
	s_mov_b32 m0, s55
	s_nop 0
	global_load_lds_dwordx4 v[28:29], off
	v_lshl_add_u64 v[28:29], v[142:143], 0, s[6:7]
	s_mov_b32 m0, s50
	s_nop 0
	global_load_lds_dwordx4 v[28:29], off
	v_lshl_add_u64 v[28:29], v[144:145], 0, s[6:7]
	s_mov_b32 m0, s51
	s_nop 0
	global_load_lds_dwordx4 v[28:29], off
	s_waitcnt vmcnt(8)
	s_waitcnt lgkmcnt(0)
	s_barrier
	s_setprio 1
	v_mfma_f32_16x16x32_bf16 v[28:31], v[4:7], v[8:11], v[94:97]
	v_mfma_f32_16x16x32_bf16 v[8:11], v[110:113], v[8:11], v[98:101]
	v_mfma_f32_16x16x32_bf16 v[36:39], v[114:117], v[12:15], v[8:11]
	v_mfma_f32_16x16x32_bf16 v[8:11], v[4:7], v[24:27], v[126:129]
	v_mfma_f32_16x16x32_bf16 v[44:47], v[86:89], v[12:15], v[28:31]
	v_mfma_f32_16x16x32_bf16 v[28:31], v[86:89], v[90:93], v[8:11]
	v_mfma_f32_16x16x32_bf16 v[8:11], v[110:113], v[24:27], v[102:105]
	v_mfma_f32_16x16x32_bf16 v[24:27], v[114:117], v[90:93], v[8:11]
	v_mfma_f32_16x16x32_bf16 v[8:11], v[4:7], v[118:121], v[106:109]
	v_mfma_f32_16x16x32_bf16 v[0:3], v[4:7], v[130:133], v[0:3]
	v_mfma_f32_16x16x32_bf16 v[12:15], v[86:89], v[122:125], v[8:11]
	v_mfma_f32_16x16x32_bf16 v[8:11], v[110:113], v[118:121], v[78:81]
	v_mfma_f32_16x16x32_bf16 v[4:7], v[86:89], v[134:137], v[0:3]
	v_mfma_f32_16x16x32_bf16 v[0:3], v[110:113], v[130:133], v[82:85]
	v_mfma_f32_16x16x32_bf16 v[8:11], v[114:117], v[122:125], v[8:11]
	v_mfma_f32_16x16x32_bf16 v[0:3], v[114:117], v[134:137], v[0:3]
	s_setprio 0
	s_barrier
	s_andn2_b64 vcc, exec, s[18:19]
	s_cbranch_vccnz .LBB0_564
	s_barrier

.LBB0_842:
	ds_read_b128 v[144:147], v153
	ds_read_b128 v[156:159], v153 offset:1024
	ds_read_b128 v[160:163], v153 offset:2048
	ds_read_b128 v[164:167], v153 offset:3072
	ds_read_b128 v[168:171], v154
	ds_read_b128 v[172:175], v154 offset:1024
	ds_read_b128 v[176:179], v154 offset:2048
	ds_read_b128 v[184:187], v154 offset:3072
	s_add_u32 s2, s0, 0x100
	s_addc_u32 s3, s1, 0
	s_cmp_eq_u32 s47, 12
	s_cselect_b32 s25, s21, s3
	s_cselect_b32 s24, s20, s2
	s_cselect_b32 s7, s19, s46
	s_cselect_b32 s6, s44, s45
	v_lshl_add_u64 v[148:149], s[0:1], 0, v[136:137]
	s_add_i32 m0, s27, 0xc000
	ds_read_b128 v[188:191], v155
	ds_read_b128 v[192:195], v155 offset:1024
	ds_read_b128 v[196:199], v155 offset:2048
	ds_read_b128 v[200:203], v155 offset:3072
	ds_read_b128 v[204:207], v155 offset:4096
	ds_read_b128 v[208:211], v155 offset:5120
	ds_read_b128 v[212:215], v155 offset:6144
	ds_read_b128 v[216:219], v155 offset:7168
	global_load_lds_dwordx4 v[148:149], off
	v_lshl_add_u64 v[148:149], s[0:1], 0, v[138:139]
	s_add_i32 m0, s27, 0xe000
	s_nop 0
	global_load_lds_dwordx4 v[148:149], off
	s_waitcnt vmcnt(8)
	s_waitcnt lgkmcnt(0)
	s_barrier
	s_setprio 1
	v_mfma_f32_16x16x32_bf16 v[124:127], v[144:147], v[188:191], v[124:127]
	v_mfma_f32_16x16x32_bf16 v[120:123], v[160:163], v[188:191], v[120:123]
	v_mfma_f32_16x16x32_bf16 v[108:111], v[144:147], v[196:199], v[108:111]
	v_mfma_f32_16x16x32_bf16 v[104:107], v[160:163], v[196:199], v[104:107]
	v_mfma_f32_16x16x32_bf16 v[92:95], v[144:147], v[204:207], v[92:95]
	v_mfma_f32_16x16x32_bf16 v[88:91], v[160:163], v[204:207], v[88:91]
	v_mfma_f32_16x16x32_bf16 v[76:79], v[144:147], v[212:215], v[76:79]
	v_mfma_f32_16x16x32_bf16 v[72:75], v[160:163], v[212:215], v[72:75]
	v_mfma_f32_16x16x32_bf16 v[124:127], v[156:159], v[192:195], v[124:127]
	v_mfma_f32_16x16x32_bf16 v[120:123], v[164:167], v[192:195], v[120:123]
	v_mfma_f32_16x16x32_bf16 v[108:111], v[156:159], v[200:203], v[108:111]
	v_mfma_f32_16x16x32_bf16 v[104:107], v[164:167], v[200:203], v[104:107]
	v_mfma_f32_16x16x32_bf16 v[92:95], v[156:159], v[208:211], v[92:95]
	v_mfma_f32_16x16x32_bf16 v[88:91], v[164:167], v[208:211], v[88:91]
	v_mfma_f32_16x16x32_bf16 v[76:79], v[156:159], v[216:219], v[76:79]
	v_mfma_f32_16x16x32_bf16 v[72:75], v[164:167], v[216:219], v[72:75]
	v_mfma_f32_16x16x32_bf16 v[116:119], v[168:171], v[188:191], v[116:119]
	v_mfma_f32_16x16x32_bf16 v[112:115], v[176:179], v[188:191], v[112:115]
	v_mfma_f32_16x16x32_bf16 v[100:103], v[168:171], v[196:199], v[100:103]
	v_mfma_f32_16x16x32_bf16 v[96:99], v[176:179], v[196:199], v[96:99]
	v_mfma_f32_16x16x32_bf16 v[84:87], v[168:171], v[204:207], v[84:87]
	v_mfma_f32_16x16x32_bf16 v[80:83], v[176:179], v[204:207], v[80:83]
	v_mfma_f32_16x16x32_bf16 v[68:71], v[168:171], v[212:215], v[68:71]
	v_mfma_f32_16x16x32_bf16 v[64:67], v[176:179], v[212:215], v[64:67]
	v_mfma_f32_16x16x32_bf16 v[116:119], v[172:175], v[192:195], v[116:119]
	v_mfma_f32_16x16x32_bf16 v[112:115], v[184:187], v[192:195], v[112:115]
	v_mfma_f32_16x16x32_bf16 v[100:103], v[172:175], v[200:203], v[100:103]
	v_mfma_f32_16x16x32_bf16 v[96:99], v[184:187], v[200:203], v[96:99]
	v_mfma_f32_16x16x32_bf16 v[84:87], v[172:175], v[208:211], v[84:87]
	v_mfma_f32_16x16x32_bf16 v[80:83], v[184:187], v[208:211], v[80:83]
	v_mfma_f32_16x16x32_bf16 v[68:71], v[172:175], v[216:219], v[68:71]
	v_mfma_f32_16x16x32_bf16 v[64:67], v[184:187], v[216:219], v[64:67]
	s_setprio 0
	s_barrier
	s_add_i32 s0, s36, s93
	v_lshl_add_u64 v[148:149], s[6:7], 0, v[130:131]
	s_mov_b32 m0, s0
	ds_read_b128 v[188:191], v155 offset:16384
	ds_read_b128 v[192:195], v155 offset:17408
	ds_read_b128 v[196:199], v155 offset:18432
	ds_read_b128 v[200:203], v155 offset:19456
	ds_read_b128 v[204:207], v155 offset:20480
	ds_read_b128 v[208:211], v155 offset:21504
	ds_read_b128 v[212:215], v155 offset:22528
	ds_read_b128 v[216:219], v155 offset:23552
	global_load_lds_dwordx4 v[148:149], off
	s_add_i32 m0, s0, 0x2000
	s_add_u32 s0, s6, 0x40000
	v_lshl_add_u64 v[180:181], s[6:7], 0, v[134:135]
	s_addc_u32 s1, s7, 0
	s_add_i32 s48, s37, s93
	global_load_lds_dwordx4 v[180:181], off
	v_lshl_add_u64 v[220:221], s[0:1], 0, v[130:131]
	s_mov_b32 m0, s48
	v_lshl_add_u64 v[222:223], s[24:25], 0, v[132:133]
	global_load_lds_dwordx4 v[220:221], off
	v_lshl_add_u64 v[220:221], s[0:1], 0, v[134:135]
	s_add_i32 m0, s48, 0x2000
	s_nop 0
	global_load_lds_dwordx4 v[220:221], off
	v_lshl_add_u64 v[220:221], s[24:25], 0, v[128:129]
	s_mov_b32 m0, s27
	s_nop 0
	global_load_lds_dwordx4 v[220:221], off
	s_mov_b32 m0, s28
	s_nop 0
	global_load_lds_dwordx4 v[222:223], off
	s_waitcnt vmcnt(8)
	s_waitcnt lgkmcnt(0)
	s_barrier
	s_setprio 1
	v_mfma_f32_16x16x32_bf16 v[60:63], v[144:147], v[188:191], v[60:63]
	v_mfma_f32_16x16x32_bf16 v[56:59], v[160:163], v[188:191], v[56:59]
	v_mfma_f32_16x16x32_bf16 v[44:47], v[144:147], v[196:199], v[44:47]
	v_mfma_f32_16x16x32_bf16 v[40:43], v[160:163], v[196:199], v[40:43]
	v_mfma_f32_16x16x32_bf16 v[28:31], v[144:147], v[204:207], v[28:31]
	v_mfma_f32_16x16x32_bf16 v[24:27], v[160:163], v[204:207], v[24:27]
	v_mfma_f32_16x16x32_bf16 v[12:15], v[144:147], v[212:215], v[12:15]
	v_mfma_f32_16x16x32_bf16 v[8:11], v[160:163], v[212:215], v[8:11]
	v_mfma_f32_16x16x32_bf16 v[60:63], v[156:159], v[192:195], v[60:63]
	v_mfma_f32_16x16x32_bf16 v[56:59], v[164:167], v[192:195], v[56:59]
	v_mfma_f32_16x16x32_bf16 v[44:47], v[156:159], v[200:203], v[44:47]
	v_mfma_f32_16x16x32_bf16 v[40:43], v[164:167], v[200:203], v[40:43]
	v_mfma_f32_16x16x32_bf16 v[28:31], v[156:159], v[208:211], v[28:31]
	v_mfma_f32_16x16x32_bf16 v[24:27], v[164:167], v[208:211], v[24:27]
	v_mfma_f32_16x16x32_bf16 v[12:15], v[156:159], v[216:219], v[12:15]
	v_mfma_f32_16x16x32_bf16 v[8:11], v[164:167], v[216:219], v[8:11]
	v_mfma_f32_16x16x32_bf16 v[52:55], v[168:171], v[188:191], v[52:55]
	v_mfma_f32_16x16x32_bf16 v[48:51], v[176:179], v[188:191], v[48:51]
	v_mfma_f32_16x16x32_bf16 v[36:39], v[168:171], v[196:199], v[36:39]
	v_mfma_f32_16x16x32_bf16 v[32:35], v[176:179], v[196:199], v[32:35]
	v_mfma_f32_16x16x32_bf16 v[20:23], v[168:171], v[204:207], v[20:23]
	v_mfma_f32_16x16x32_bf16 v[16:19], v[176:179], v[204:207], v[16:19]
	v_mfma_f32_16x16x32_bf16 v[4:7], v[168:171], v[212:215], v[4:7]
	v_mfma_f32_16x16x32_bf16 v[0:3], v[176:179], v[212:215], v[0:3]
	v_mfma_f32_16x16x32_bf16 v[52:55], v[172:175], v[192:195], v[52:55]
	v_mfma_f32_16x16x32_bf16 v[48:51], v[184:187], v[192:195], v[48:51]
	v_mfma_f32_16x16x32_bf16 v[36:39], v[172:175], v[200:203], v[36:39]
	v_mfma_f32_16x16x32_bf16 v[32:35], v[184:187], v[200:203], v[32:35]
	v_mfma_f32_16x16x32_bf16 v[20:23], v[172:175], v[208:211], v[20:23]
	v_mfma_f32_16x16x32_bf16 v[16:19], v[184:187], v[208:211], v[16:19]
	v_mfma_f32_16x16x32_bf16 v[4:7], v[172:175], v[216:219], v[4:7]
	v_mfma_f32_16x16x32_bf16 v[0:3], v[184:187], v[216:219], v[0:3]
	s_setprio 0
	s_barrier
	s_add_i32 s48, 0, 0x18000
	s_add_i32 s49, 0, 0x1c000
	v_add_u32_e32 v164, s48, v151
	v_add_u32_e32 v183, s49, v151
	ds_read_b128 v[144:147], v164
	ds_read_b128 v[156:159], v164 offset:1024
	ds_read_b128 v[160:163], v164 offset:2048
	ds_read_b128 v[164:167], v164 offset:3072
	ds_read_b128 v[168:171], v183
	ds_read_b128 v[172:175], v183 offset:1024
	ds_read_b128 v[176:179], v183 offset:2048
	ds_read_b128 v[184:187], v183 offset:3072
	s_add_u32 s0, s24, 0x270000
	s_addc_u32 s1, s25, 0
	s_mov_b32 m0, s29
	v_lshl_add_u64 v[224:225], s[0:1], 0, v[128:129]
	ds_read_b128 v[188:191], v155 offset:32768
	ds_read_b128 v[192:195], v155 offset:33792
	ds_read_b128 v[196:199], v155 offset:34816
	ds_read_b128 v[200:203], v155 offset:35840
	ds_read_b128 v[204:207], v155 offset:36864
	ds_read_b128 v[208:211], v155 offset:37888
	ds_read_b128 v[212:215], v155 offset:38912
	ds_read_b128 v[216:219], v155 offset:39936
	global_load_lds_dwordx4 v[224:225], off
	v_lshl_add_u64 v[224:225], s[0:1], 0, v[132:133]
	s_mov_b32 m0, s30
	s_nop 0
	global_load_lds_dwordx4 v[224:225], off
	s_waitcnt vmcnt(8)
	s_waitcnt lgkmcnt(0)
	s_barrier
	s_setprio 1
	v_mfma_f32_16x16x32_bf16 v[124:127], v[144:147], v[188:191], v[124:127]
	v_mfma_f32_16x16x32_bf16 v[120:123], v[160:163], v[188:191], v[120:123]
	v_mfma_f32_16x16x32_bf16 v[108:111], v[144:147], v[196:199], v[108:111]
	v_mfma_f32_16x16x32_bf16 v[104:107], v[160:163], v[196:199], v[104:107]
	v_mfma_f32_16x16x32_bf16 v[92:95], v[144:147], v[204:207], v[92:95]
	v_mfma_f32_16x16x32_bf16 v[88:91], v[160:163], v[204:207], v[88:91]
	v_mfma_f32_16x16x32_bf16 v[76:79], v[144:147], v[212:215], v[76:79]
	v_mfma_f32_16x16x32_bf16 v[72:75], v[160:163], v[212:215], v[72:75]
	v_mfma_f32_16x16x32_bf16 v[124:127], v[156:159], v[192:195], v[124:127]
	v_mfma_f32_16x16x32_bf16 v[120:123], v[164:167], v[192:195], v[120:123]
	v_mfma_f32_16x16x32_bf16 v[108:111], v[156:159], v[200:203], v[108:111]
	v_mfma_f32_16x16x32_bf16 v[104:107], v[164:167], v[200:203], v[104:107]
	v_mfma_f32_16x16x32_bf16 v[92:95], v[156:159], v[208:211], v[92:95]
	v_mfma_f32_16x16x32_bf16 v[88:91], v[164:167], v[208:211], v[88:91]
	v_mfma_f32_16x16x32_bf16 v[76:79], v[156:159], v[216:219], v[76:79]
	v_mfma_f32_16x16x32_bf16 v[72:75], v[164:167], v[216:219], v[72:75]
	v_mfma_f32_16x16x32_bf16 v[116:119], v[168:171], v[188:191], v[116:119]
	v_mfma_f32_16x16x32_bf16 v[112:115], v[176:179], v[188:191], v[112:115]
	v_mfma_f32_16x16x32_bf16 v[100:103], v[168:171], v[196:199], v[100:103]
	v_mfma_f32_16x16x32_bf16 v[96:99], v[176:179], v[196:199], v[96:99]
	v_mfma_f32_16x16x32_bf16 v[84:87], v[168:171], v[204:207], v[84:87]
	v_mfma_f32_16x16x32_bf16 v[80:83], v[176:179], v[204:207], v[80:83]
	v_mfma_f32_16x16x32_bf16 v[68:71], v[168:171], v[212:215], v[68:71]
	v_mfma_f32_16x16x32_bf16 v[64:67], v[176:179], v[212:215], v[64:67]
	v_mfma_f32_16x16x32_bf16 v[116:119], v[172:175], v[192:195], v[116:119]
	v_mfma_f32_16x16x32_bf16 v[112:115], v[184:187], v[192:195], v[112:115]
	v_mfma_f32_16x16x32_bf16 v[100:103], v[172:175], v[200:203], v[100:103]
	v_mfma_f32_16x16x32_bf16 v[96:99], v[184:187], v[200:203], v[96:99]
	v_mfma_f32_16x16x32_bf16 v[84:87], v[172:175], v[208:211], v[84:87]
	v_mfma_f32_16x16x32_bf16 v[80:83], v[184:187], v[208:211], v[80:83]
	v_mfma_f32_16x16x32_bf16 v[68:71], v[172:175], v[216:219], v[68:71]
	v_mfma_f32_16x16x32_bf16 v[64:67], v[184:187], v[216:219], v[64:67]
	s_setprio 0
	s_barrier
	s_add_i32 s0, s48, s93
	v_lshl_add_u64 v[148:149], v[148:149], 0, s[14:15]
	s_mov_b32 m0, s0
	ds_read_b128 v[188:191], v155 offset:49152
	ds_read_b128 v[192:195], v155 offset:50176
	ds_read_b128 v[196:199], v155 offset:51200
	ds_read_b128 v[200:203], v155 offset:52224
	ds_read_b128 v[204:207], v155 offset:53248
	ds_read_b128 v[208:211], v155 offset:54272
	ds_read_b128 v[212:215], v155 offset:55296
	ds_read_b128 v[216:219], v155 offset:56320
	global_load_lds_dwordx4 v[148:149], off
	s_add_i32 m0, s0, 0x2000
	s_add_u32 s0, s6, 0x40080
	v_lshl_add_u64 v[148:149], v[180:181], 0, s[14:15]
	s_addc_u32 s1, s7, 0
	s_add_i32 s6, s49, s93
	global_load_lds_dwordx4 v[148:149], off
	v_lshl_add_u64 v[148:149], s[0:1], 0, v[130:131]
	s_mov_b32 m0, s6
	s_nop 0
	global_load_lds_dwordx4 v[148:149], off
	v_lshl_add_u64 v[148:149], s[0:1], 0, v[134:135]
	s_add_i32 m0, s6, 0x2000
	s_nop 0
	global_load_lds_dwordx4 v[148:149], off
	v_lshl_add_u64 v[148:149], v[220:221], 0, s[14:15]
	s_mov_b32 m0, s33
	s_nop 0
	global_load_lds_dwordx4 v[148:149], off
	v_lshl_add_u64 v[148:149], v[222:223], 0, s[14:15]
	s_mov_b32 m0, s34
	s_nop 0
	global_load_lds_dwordx4 v[148:149], off
	s_waitcnt vmcnt(8)
	s_waitcnt lgkmcnt(0)
	s_barrier
	s_setprio 1
	v_mfma_f32_16x16x32_bf16 v[60:63], v[144:147], v[188:191], v[60:63]
	v_mfma_f32_16x16x32_bf16 v[56:59], v[160:163], v[188:191], v[56:59]
	v_mfma_f32_16x16x32_bf16 v[44:47], v[144:147], v[196:199], v[44:47]
	v_mfma_f32_16x16x32_bf16 v[40:43], v[160:163], v[196:199], v[40:43]
	v_mfma_f32_16x16x32_bf16 v[28:31], v[144:147], v[204:207], v[28:31]
	v_mfma_f32_16x16x32_bf16 v[24:27], v[160:163], v[204:207], v[24:27]
	v_mfma_f32_16x16x32_bf16 v[12:15], v[144:147], v[212:215], v[12:15]
	v_mfma_f32_16x16x32_bf16 v[8:11], v[160:163], v[212:215], v[8:11]
	v_mfma_f32_16x16x32_bf16 v[60:63], v[156:159], v[192:195], v[60:63]
	v_mfma_f32_16x16x32_bf16 v[56:59], v[164:167], v[192:195], v[56:59]
	v_mfma_f32_16x16x32_bf16 v[44:47], v[156:159], v[200:203], v[44:47]
	v_mfma_f32_16x16x32_bf16 v[40:43], v[164:167], v[200:203], v[40:43]
	v_mfma_f32_16x16x32_bf16 v[28:31], v[156:159], v[208:211], v[28:31]
	v_mfma_f32_16x16x32_bf16 v[24:27], v[164:167], v[208:211], v[24:27]
	v_mfma_f32_16x16x32_bf16 v[12:15], v[156:159], v[216:219], v[12:15]
	v_mfma_f32_16x16x32_bf16 v[8:11], v[164:167], v[216:219], v[8:11]
	v_mfma_f32_16x16x32_bf16 v[52:55], v[168:171], v[188:191], v[52:55]
	v_mfma_f32_16x16x32_bf16 v[48:51], v[176:179], v[188:191], v[48:51]
	v_mfma_f32_16x16x32_bf16 v[36:39], v[168:171], v[196:199], v[36:39]
	v_mfma_f32_16x16x32_bf16 v[32:35], v[176:179], v[196:199], v[32:35]
	v_mfma_f32_16x16x32_bf16 v[20:23], v[168:171], v[204:207], v[20:23]
	v_mfma_f32_16x16x32_bf16 v[16:19], v[176:179], v[204:207], v[16:19]
	v_mfma_f32_16x16x32_bf16 v[4:7], v[168:171], v[212:215], v[4:7]
	v_mfma_f32_16x16x32_bf16 v[0:3], v[176:179], v[212:215], v[0:3]
	v_mfma_f32_16x16x32_bf16 v[52:55], v[172:175], v[192:195], v[52:55]
	v_mfma_f32_16x16x32_bf16 v[48:51], v[184:187], v[192:195], v[48:51]
	v_mfma_f32_16x16x32_bf16 v[36:39], v[172:175], v[200:203], v[36:39]
	v_mfma_f32_16x16x32_bf16 v[32:35], v[184:187], v[200:203], v[32:35]
	v_mfma_f32_16x16x32_bf16 v[20:23], v[172:175], v[208:211], v[20:23]
	v_mfma_f32_16x16x32_bf16 v[16:19], v[184:187], v[208:211], v[16:19]
	v_mfma_f32_16x16x32_bf16 v[4:7], v[172:175], v[216:219], v[4:7]
	v_mfma_f32_16x16x32_bf16 v[0:3], v[184:187], v[216:219], v[0:3]
	s_setprio 0
	s_barrier
	s_add_i32 s47, s47, 2
	s_add_u32 s45, s45, 0x100
	s_addc_u32 s46, s46, 0
	s_cmp_gt_u32 s47, 13
	s_mov_b64 s[0:1], s[2:3]
	s_cbranch_scc0 .LBB0_842
	s_and_b64 vcc, exec, s[16:17]
	s_cbranch_vccz .LBB0_845
	s_barrier

.LBB0_868:
	ds_read_b128 v[128:131], v159
	ds_read_b128 v[148:151], v159 offset:1024
	ds_read_b128 v[152:155], v159 offset:2048
	ds_read_b128 v[162:165], v159 offset:3072
	ds_read_b128 v[166:169], v160
	ds_read_b128 v[170:173], v160 offset:1024
	ds_read_b128 v[174:177], v160 offset:2048
	ds_read_b128 v[178:181], v160 offset:3072
	s_add_u32 s2, s0, 0x100
	s_addc_u32 s3, s1, 0
	s_cmp_eq_u32 s49, 12
	s_cselect_b32 s25, s21, s3
	s_cselect_b32 s24, s20, s2
	s_cselect_b32 s9, s19, s48
	s_cselect_b32 s8, s46, s47
	v_lshl_add_u64 v[216:217], s[0:1], 0, v[140:141]
	s_add_i32 m0, s29, 0xc000
	ds_read_b128 v[184:187], v161
	ds_read_b128 v[188:191], v161 offset:1024
	ds_read_b128 v[192:195], v161 offset:2048
	ds_read_b128 v[196:199], v161 offset:3072
	ds_read_b128 v[200:203], v161 offset:4096
	ds_read_b128 v[204:207], v161 offset:5120
	ds_read_b128 v[208:211], v161 offset:6144
	ds_read_b128 v[212:215], v161 offset:7168
	global_load_lds_dwordx4 v[216:217], off
	v_lshl_add_u64 v[216:217], s[0:1], 0, v[142:143]
	s_add_i32 m0, s29, 0xe000
	s_nop 0
	global_load_lds_dwordx4 v[216:217], off
	s_waitcnt vmcnt(8)
	s_waitcnt lgkmcnt(0)
	s_barrier
	s_setprio 1
	v_mfma_f32_16x16x32_bf16 v[124:127], v[128:131], v[184:187], v[124:127]
	v_mfma_f32_16x16x32_bf16 v[120:123], v[152:155], v[184:187], v[120:123]
	v_mfma_f32_16x16x32_bf16 v[108:111], v[128:131], v[192:195], v[108:111]
	v_mfma_f32_16x16x32_bf16 v[104:107], v[152:155], v[192:195], v[104:107]
	v_mfma_f32_16x16x32_bf16 v[92:95], v[128:131], v[200:203], v[92:95]
	v_mfma_f32_16x16x32_bf16 v[88:91], v[152:155], v[200:203], v[88:91]
	v_mfma_f32_16x16x32_bf16 v[76:79], v[128:131], v[208:211], v[76:79]
	v_mfma_f32_16x16x32_bf16 v[72:75], v[152:155], v[208:211], v[72:75]
	v_mfma_f32_16x16x32_bf16 v[124:127], v[148:151], v[188:191], v[124:127]
	v_mfma_f32_16x16x32_bf16 v[120:123], v[162:165], v[188:191], v[120:123]
	v_mfma_f32_16x16x32_bf16 v[108:111], v[148:151], v[196:199], v[108:111]
	v_mfma_f32_16x16x32_bf16 v[104:107], v[162:165], v[196:199], v[104:107]
	v_mfma_f32_16x16x32_bf16 v[92:95], v[148:151], v[204:207], v[92:95]
	v_mfma_f32_16x16x32_bf16 v[88:91], v[162:165], v[204:207], v[88:91]
	v_mfma_f32_16x16x32_bf16 v[76:79], v[148:151], v[212:215], v[76:79]
	v_mfma_f32_16x16x32_bf16 v[72:75], v[162:165], v[212:215], v[72:75]
	v_mfma_f32_16x16x32_bf16 v[116:119], v[166:169], v[184:187], v[116:119]
	v_mfma_f32_16x16x32_bf16 v[112:115], v[174:177], v[184:187], v[112:115]
	v_mfma_f32_16x16x32_bf16 v[100:103], v[166:169], v[192:195], v[100:103]
	v_mfma_f32_16x16x32_bf16 v[96:99], v[174:177], v[192:195], v[96:99]
	v_mfma_f32_16x16x32_bf16 v[84:87], v[166:169], v[200:203], v[84:87]
	v_mfma_f32_16x16x32_bf16 v[80:83], v[174:177], v[200:203], v[80:83]
	v_mfma_f32_16x16x32_bf16 v[68:71], v[166:169], v[208:211], v[68:71]
	v_mfma_f32_16x16x32_bf16 v[64:67], v[174:177], v[208:211], v[64:67]
	v_mfma_f32_16x16x32_bf16 v[116:119], v[170:173], v[188:191], v[116:119]
	v_mfma_f32_16x16x32_bf16 v[112:115], v[178:181], v[188:191], v[112:115]
	v_mfma_f32_16x16x32_bf16 v[100:103], v[170:173], v[196:199], v[100:103]
	v_mfma_f32_16x16x32_bf16 v[96:99], v[178:181], v[196:199], v[96:99]
	v_mfma_f32_16x16x32_bf16 v[84:87], v[170:173], v[204:207], v[84:87]
	v_mfma_f32_16x16x32_bf16 v[80:83], v[178:181], v[204:207], v[80:83]
	v_mfma_f32_16x16x32_bf16 v[68:71], v[170:173], v[212:215], v[68:71]
	v_mfma_f32_16x16x32_bf16 v[64:67], v[178:181], v[212:215], v[64:67]
	s_setprio 0
	s_barrier
	s_add_i32 s0, s38, s93
	v_lshl_add_u64 v[216:217], s[8:9], 0, v[134:135]
	s_mov_b32 m0, s0
	ds_read_b128 v[184:187], v161 offset:16384
	ds_read_b128 v[188:191], v161 offset:17408
	ds_read_b128 v[192:195], v161 offset:18432
	ds_read_b128 v[196:199], v161 offset:19456
	ds_read_b128 v[200:203], v161 offset:20480
	ds_read_b128 v[204:207], v161 offset:21504
	ds_read_b128 v[208:211], v161 offset:22528
	ds_read_b128 v[212:215], v161 offset:23552
	global_load_lds_dwordx4 v[216:217], off
	s_add_i32 m0, s0, 0x2000
	s_add_u32 s0, s8, 0x40000
	v_lshl_add_u64 v[218:219], s[8:9], 0, v[138:139]
	s_addc_u32 s1, s9, 0
	s_add_i32 s50, s39, s93
	global_load_lds_dwordx4 v[218:219], off
	v_lshl_add_u64 v[220:221], s[0:1], 0, v[134:135]
	s_mov_b32 m0, s50
	v_lshl_add_u64 v[222:223], s[24:25], 0, v[136:137]
	global_load_lds_dwordx4 v[220:221], off
	v_lshl_add_u64 v[220:221], s[0:1], 0, v[138:139]
	s_add_i32 m0, s50, 0x2000
	s_nop 0
	global_load_lds_dwordx4 v[220:221], off
	v_lshl_add_u64 v[220:221], s[24:25], 0, v[132:133]
	s_mov_b32 m0, s29
	s_nop 0
	global_load_lds_dwordx4 v[220:221], off
	s_mov_b32 m0, s30
	s_nop 0
	global_load_lds_dwordx4 v[222:223], off
	s_waitcnt vmcnt(8)
	s_waitcnt lgkmcnt(0)
	s_barrier
	s_setprio 1
	v_mfma_f32_16x16x32_bf16 v[60:63], v[128:131], v[184:187], v[60:63]
	v_mfma_f32_16x16x32_bf16 v[56:59], v[152:155], v[184:187], v[56:59]
	v_mfma_f32_16x16x32_bf16 v[44:47], v[128:131], v[192:195], v[44:47]
	v_mfma_f32_16x16x32_bf16 v[40:43], v[152:155], v[192:195], v[40:43]
	v_mfma_f32_16x16x32_bf16 v[28:31], v[128:131], v[200:203], v[28:31]
	v_mfma_f32_16x16x32_bf16 v[24:27], v[152:155], v[200:203], v[24:27]
	v_mfma_f32_16x16x32_bf16 v[12:15], v[128:131], v[208:211], v[12:15]
	v_mfma_f32_16x16x32_bf16 v[8:11], v[152:155], v[208:211], v[8:11]
	v_mfma_f32_16x16x32_bf16 v[60:63], v[148:151], v[188:191], v[60:63]
	v_mfma_f32_16x16x32_bf16 v[56:59], v[162:165], v[188:191], v[56:59]
	v_mfma_f32_16x16x32_bf16 v[44:47], v[148:151], v[196:199], v[44:47]
	v_mfma_f32_16x16x32_bf16 v[40:43], v[162:165], v[196:199], v[40:43]
	v_mfma_f32_16x16x32_bf16 v[28:31], v[148:151], v[204:207], v[28:31]
	v_mfma_f32_16x16x32_bf16 v[24:27], v[162:165], v[204:207], v[24:27]
	v_mfma_f32_16x16x32_bf16 v[12:15], v[148:151], v[212:215], v[12:15]
	v_mfma_f32_16x16x32_bf16 v[8:11], v[162:165], v[212:215], v[8:11]
	v_mfma_f32_16x16x32_bf16 v[52:55], v[166:169], v[184:187], v[52:55]
	v_mfma_f32_16x16x32_bf16 v[48:51], v[174:177], v[184:187], v[48:51]
	v_mfma_f32_16x16x32_bf16 v[36:39], v[166:169], v[192:195], v[36:39]
	v_mfma_f32_16x16x32_bf16 v[32:35], v[174:177], v[192:195], v[32:35]
	v_mfma_f32_16x16x32_bf16 v[20:23], v[166:169], v[200:203], v[20:23]
	v_mfma_f32_16x16x32_bf16 v[16:19], v[174:177], v[200:203], v[16:19]
	v_mfma_f32_16x16x32_bf16 v[4:7], v[166:169], v[208:211], v[4:7]
	v_mfma_f32_16x16x32_bf16 v[0:3], v[174:177], v[208:211], v[0:3]
	v_mfma_f32_16x16x32_bf16 v[52:55], v[170:173], v[188:191], v[52:55]
	v_mfma_f32_16x16x32_bf16 v[48:51], v[178:181], v[188:191], v[48:51]
	v_mfma_f32_16x16x32_bf16 v[36:39], v[170:173], v[196:199], v[36:39]
	v_mfma_f32_16x16x32_bf16 v[32:35], v[178:181], v[196:199], v[32:35]
	v_mfma_f32_16x16x32_bf16 v[20:23], v[170:173], v[204:207], v[20:23]
	v_mfma_f32_16x16x32_bf16 v[16:19], v[178:181], v[204:207], v[16:19]
	v_mfma_f32_16x16x32_bf16 v[4:7], v[170:173], v[212:215], v[4:7]
	v_mfma_f32_16x16x32_bf16 v[0:3], v[178:181], v[212:215], v[0:3]
	s_setprio 0
	s_barrier
	s_add_i32 s50, 0, 0x18000
	s_add_i32 s51, 0, 0x1c000
	v_add_u32_e32 v162, s50, v157
	v_add_u32_e32 v178, s51, v157
	ds_read_b128 v[128:131], v162
	ds_read_b128 v[148:151], v162 offset:1024
	ds_read_b128 v[152:155], v162 offset:2048
	ds_read_b128 v[162:165], v162 offset:3072
	ds_read_b128 v[166:169], v178
	ds_read_b128 v[170:173], v178 offset:1024
	ds_read_b128 v[174:177], v178 offset:2048
	ds_read_b128 v[178:181], v178 offset:3072
	s_add_u32 s0, s24, 0x270000
	s_addc_u32 s1, s25, 0
	s_mov_b32 m0, s31
	v_lshl_add_u64 v[224:225], s[0:1], 0, v[132:133]
	ds_read_b128 v[184:187], v161 offset:32768
	ds_read_b128 v[188:191], v161 offset:33792
	ds_read_b128 v[192:195], v161 offset:34816
	ds_read_b128 v[196:199], v161 offset:35840
	ds_read_b128 v[200:203], v161 offset:36864
	ds_read_b128 v[204:207], v161 offset:37888
	ds_read_b128 v[208:211], v161 offset:38912
	ds_read_b128 v[212:215], v161 offset:39936
	global_load_lds_dwordx4 v[224:225], off
	v_lshl_add_u64 v[224:225], s[0:1], 0, v[136:137]
	s_mov_b32 m0, s33
	s_nop 0
	global_load_lds_dwordx4 v[224:225], off
	s_waitcnt vmcnt(8)
	s_waitcnt lgkmcnt(0)
	s_barrier
	s_setprio 1
	v_mfma_f32_16x16x32_bf16 v[124:127], v[128:131], v[184:187], v[124:127]
	v_mfma_f32_16x16x32_bf16 v[120:123], v[152:155], v[184:187], v[120:123]
	v_mfma_f32_16x16x32_bf16 v[108:111], v[128:131], v[192:195], v[108:111]
	v_mfma_f32_16x16x32_bf16 v[104:107], v[152:155], v[192:195], v[104:107]
	v_mfma_f32_16x16x32_bf16 v[92:95], v[128:131], v[200:203], v[92:95]
	v_mfma_f32_16x16x32_bf16 v[88:91], v[152:155], v[200:203], v[88:91]
	v_mfma_f32_16x16x32_bf16 v[76:79], v[128:131], v[208:211], v[76:79]
	v_mfma_f32_16x16x32_bf16 v[72:75], v[152:155], v[208:211], v[72:75]
	v_mfma_f32_16x16x32_bf16 v[124:127], v[148:151], v[188:191], v[124:127]
	v_mfma_f32_16x16x32_bf16 v[120:123], v[162:165], v[188:191], v[120:123]
	v_mfma_f32_16x16x32_bf16 v[108:111], v[148:151], v[196:199], v[108:111]
	v_mfma_f32_16x16x32_bf16 v[104:107], v[162:165], v[196:199], v[104:107]
	v_mfma_f32_16x16x32_bf16 v[92:95], v[148:151], v[204:207], v[92:95]
	v_mfma_f32_16x16x32_bf16 v[88:91], v[162:165], v[204:207], v[88:91]
	v_mfma_f32_16x16x32_bf16 v[76:79], v[148:151], v[212:215], v[76:79]
	v_mfma_f32_16x16x32_bf16 v[72:75], v[162:165], v[212:215], v[72:75]
	v_mfma_f32_16x16x32_bf16 v[116:119], v[166:169], v[184:187], v[116:119]
	v_mfma_f32_16x16x32_bf16 v[112:115], v[174:177], v[184:187], v[112:115]
	v_mfma_f32_16x16x32_bf16 v[100:103], v[166:169], v[192:195], v[100:103]
	v_mfma_f32_16x16x32_bf16 v[96:99], v[174:177], v[192:195], v[96:99]
	v_mfma_f32_16x16x32_bf16 v[84:87], v[166:169], v[200:203], v[84:87]
	v_mfma_f32_16x16x32_bf16 v[80:83], v[174:177], v[200:203], v[80:83]
	v_mfma_f32_16x16x32_bf16 v[68:71], v[166:169], v[208:211], v[68:71]
	v_mfma_f32_16x16x32_bf16 v[64:67], v[174:177], v[208:211], v[64:67]
	v_mfma_f32_16x16x32_bf16 v[116:119], v[170:173], v[188:191], v[116:119]
	v_mfma_f32_16x16x32_bf16 v[112:115], v[178:181], v[188:191], v[112:115]
	v_mfma_f32_16x16x32_bf16 v[100:103], v[170:173], v[196:199], v[100:103]
	v_mfma_f32_16x16x32_bf16 v[96:99], v[178:181], v[196:199], v[96:99]
	v_mfma_f32_16x16x32_bf16 v[84:87], v[170:173], v[204:207], v[84:87]
	v_mfma_f32_16x16x32_bf16 v[80:83], v[178:181], v[204:207], v[80:83]
	v_mfma_f32_16x16x32_bf16 v[68:71], v[170:173], v[212:215], v[68:71]
	v_mfma_f32_16x16x32_bf16 v[64:67], v[178:181], v[212:215], v[64:67]
	s_setprio 0
	s_barrier
	s_add_i32 s0, s50, s93
	v_lshl_add_u64 v[216:217], v[216:217], 0, s[14:15]
	s_mov_b32 m0, s0
	ds_read_b128 v[184:187], v161 offset:49152
	ds_read_b128 v[188:191], v161 offset:50176
	ds_read_b128 v[192:195], v161 offset:51200
	ds_read_b128 v[196:199], v161 offset:52224
	ds_read_b128 v[200:203], v161 offset:53248
	ds_read_b128 v[204:207], v161 offset:54272
	ds_read_b128 v[208:211], v161 offset:55296
	ds_read_b128 v[212:215], v161 offset:56320
	global_load_lds_dwordx4 v[216:217], off
	s_add_i32 m0, s0, 0x2000
	s_add_u32 s0, s8, 0x40080
	v_lshl_add_u64 v[216:217], v[218:219], 0, s[14:15]
	s_addc_u32 s1, s9, 0
	s_add_i32 s8, s51, s93
	global_load_lds_dwordx4 v[216:217], off
	v_lshl_add_u64 v[216:217], s[0:1], 0, v[134:135]
	s_mov_b32 m0, s8
	s_nop 0
	global_load_lds_dwordx4 v[216:217], off
	v_lshl_add_u64 v[216:217], s[0:1], 0, v[138:139]
	s_add_i32 m0, s8, 0x2000
	s_nop 0
	global_load_lds_dwordx4 v[216:217], off
	v_lshl_add_u64 v[216:217], v[220:221], 0, s[14:15]
	s_mov_b32 m0, s35
	s_nop 0
	global_load_lds_dwordx4 v[216:217], off
	v_lshl_add_u64 v[216:217], v[222:223], 0, s[14:15]
	s_mov_b32 m0, s36
	s_nop 0
	global_load_lds_dwordx4 v[216:217], off
	s_waitcnt vmcnt(8)
	s_waitcnt lgkmcnt(0)
	s_barrier
	s_setprio 1
	v_mfma_f32_16x16x32_bf16 v[60:63], v[128:131], v[184:187], v[60:63]
	v_mfma_f32_16x16x32_bf16 v[56:59], v[152:155], v[184:187], v[56:59]
	v_mfma_f32_16x16x32_bf16 v[44:47], v[128:131], v[192:195], v[44:47]
	v_mfma_f32_16x16x32_bf16 v[40:43], v[152:155], v[192:195], v[40:43]
	v_mfma_f32_16x16x32_bf16 v[28:31], v[128:131], v[200:203], v[28:31]
	v_mfma_f32_16x16x32_bf16 v[24:27], v[152:155], v[200:203], v[24:27]
	v_mfma_f32_16x16x32_bf16 v[12:15], v[128:131], v[208:211], v[12:15]
	v_mfma_f32_16x16x32_bf16 v[8:11], v[152:155], v[208:211], v[8:11]
	v_mfma_f32_16x16x32_bf16 v[60:63], v[148:151], v[188:191], v[60:63]
	v_mfma_f32_16x16x32_bf16 v[56:59], v[162:165], v[188:191], v[56:59]
	v_mfma_f32_16x16x32_bf16 v[44:47], v[148:151], v[196:199], v[44:47]
	v_mfma_f32_16x16x32_bf16 v[40:43], v[162:165], v[196:199], v[40:43]
	v_mfma_f32_16x16x32_bf16 v[28:31], v[148:151], v[204:207], v[28:31]
	v_mfma_f32_16x16x32_bf16 v[24:27], v[162:165], v[204:207], v[24:27]
	v_mfma_f32_16x16x32_bf16 v[12:15], v[148:151], v[212:215], v[12:15]
	v_mfma_f32_16x16x32_bf16 v[8:11], v[162:165], v[212:215], v[8:11]
	v_mfma_f32_16x16x32_bf16 v[52:55], v[166:169], v[184:187], v[52:55]
	v_mfma_f32_16x16x32_bf16 v[48:51], v[174:177], v[184:187], v[48:51]
	v_mfma_f32_16x16x32_bf16 v[36:39], v[166:169], v[192:195], v[36:39]
	v_mfma_f32_16x16x32_bf16 v[32:35], v[174:177], v[192:195], v[32:35]
	v_mfma_f32_16x16x32_bf16 v[20:23], v[166:169], v[200:203], v[20:23]
	v_mfma_f32_16x16x32_bf16 v[16:19], v[174:177], v[200:203], v[16:19]
	v_mfma_f32_16x16x32_bf16 v[4:7], v[166:169], v[208:211], v[4:7]
	v_mfma_f32_16x16x32_bf16 v[0:3], v[174:177], v[208:211], v[0:3]
	v_mfma_f32_16x16x32_bf16 v[52:55], v[170:173], v[188:191], v[52:55]
	v_mfma_f32_16x16x32_bf16 v[48:51], v[178:181], v[188:191], v[48:51]
	v_mfma_f32_16x16x32_bf16 v[36:39], v[170:173], v[196:199], v[36:39]
	v_mfma_f32_16x16x32_bf16 v[32:35], v[178:181], v[196:199], v[32:35]
	v_mfma_f32_16x16x32_bf16 v[20:23], v[170:173], v[204:207], v[20:23]
	v_mfma_f32_16x16x32_bf16 v[16:19], v[178:181], v[204:207], v[16:19]
	v_mfma_f32_16x16x32_bf16 v[4:7], v[170:173], v[212:215], v[4:7]
	v_mfma_f32_16x16x32_bf16 v[0:3], v[178:181], v[212:215], v[0:3]
	s_setprio 0
	s_barrier
	s_add_i32 s49, s49, 2
	s_add_u32 s47, s47, 0x100
	s_addc_u32 s48, s48, 0
	s_cmp_gt_u32 s49, 13
	s_mov_b64 s[0:1], s[2:3]
	s_cbranch_scc0 .LBB0_868
	s_and_b64 vcc, exec, s[16:17]
	s_cbranch_vccz .LBB0_871
	s_barrier

.LBB0_902:
	ds_read_b128 v[128:131], v168
	ds_read_b128 v[144:147], v168 offset:1024
	ds_read_b128 v[148:151], v168 offset:2048
	ds_read_b128 v[152:155], v168 offset:3072
	ds_read_b128 v[156:159], v169
	ds_read_b128 v[174:177], v169 offset:1024
	ds_read_b128 v[178:181], v169 offset:2048
	ds_read_b128 v[184:187], v169 offset:3072
	s_add_u32 s16, s2, 0xfff80080
	s_addc_u32 s17, s3, -1
	s_cmp_eq_u32 s56, 28
	s_cselect_b32 s37, s1, s17
	s_cselect_b32 s36, s15, s16
	s_cselect_b32 s17, s27, s55
	s_cselect_b32 s16, s29, s54
	v_lshl_add_u64 v[160:161], s[2:3], 0, v[136:137]
	s_add_i32 m0, s33, 0xc000
	ds_read_b128 v[188:191], v170
	ds_read_b128 v[192:195], v170 offset:1024
	ds_read_b128 v[196:199], v170 offset:2048
	ds_read_b128 v[200:203], v170 offset:3072
	ds_read_b128 v[204:207], v170 offset:4096
	ds_read_b128 v[208:211], v170 offset:5120
	ds_read_b128 v[212:215], v170 offset:6144
	ds_read_b128 v[216:219], v170 offset:7168
	global_load_lds_dwordx4 v[160:161], off
	v_lshl_add_u64 v[160:161], s[2:3], 0, v[138:139]
	s_add_i32 m0, s33, 0xe000
	s_nop 0
	global_load_lds_dwordx4 v[160:161], off
	s_waitcnt vmcnt(8)
	s_waitcnt lgkmcnt(0)
	s_barrier
	s_setprio 1
	v_mfma_f32_16x16x32_bf16 v[124:127], v[128:131], v[188:191], v[124:127]
	v_mfma_f32_16x16x32_bf16 v[120:123], v[148:151], v[188:191], v[120:123]
	v_mfma_f32_16x16x32_bf16 v[112:115], v[128:131], v[196:199], v[112:115]
	v_mfma_f32_16x16x32_bf16 v[108:111], v[148:151], v[196:199], v[108:111]
	v_mfma_f32_16x16x32_bf16 v[96:99], v[128:131], v[204:207], v[96:99]
	v_mfma_f32_16x16x32_bf16 v[92:95], v[148:151], v[204:207], v[92:95]
	v_mfma_f32_16x16x32_bf16 v[80:83], v[128:131], v[212:215], v[80:83]
	v_mfma_f32_16x16x32_bf16 v[76:79], v[148:151], v[212:215], v[76:79]
	v_mfma_f32_16x16x32_bf16 v[124:127], v[144:147], v[192:195], v[124:127]
	v_mfma_f32_16x16x32_bf16 v[120:123], v[152:155], v[192:195], v[120:123]
	v_mfma_f32_16x16x32_bf16 v[112:115], v[144:147], v[200:203], v[112:115]
	v_mfma_f32_16x16x32_bf16 v[108:111], v[152:155], v[200:203], v[108:111]
	v_mfma_f32_16x16x32_bf16 v[96:99], v[144:147], v[208:211], v[96:99]
	v_mfma_f32_16x16x32_bf16 v[92:95], v[152:155], v[208:211], v[92:95]
	v_mfma_f32_16x16x32_bf16 v[80:83], v[144:147], v[216:219], v[80:83]
	v_mfma_f32_16x16x32_bf16 v[76:79], v[152:155], v[216:219], v[76:79]
	v_mfma_f32_16x16x32_bf16 v[116:119], v[156:159], v[188:191], v[116:119]
	v_mfma_f32_16x16x32_bf16 v[104:107], v[178:181], v[188:191], v[104:107]
	v_mfma_f32_16x16x32_bf16 v[100:103], v[156:159], v[196:199], v[100:103]
	v_mfma_f32_16x16x32_bf16 v[88:91], v[178:181], v[196:199], v[88:91]
	v_mfma_f32_16x16x32_bf16 v[84:87], v[156:159], v[204:207], v[84:87]
	v_mfma_f32_16x16x32_bf16 v[72:75], v[178:181], v[204:207], v[72:75]
	v_mfma_f32_16x16x32_bf16 v[68:71], v[156:159], v[212:215], v[68:71]
	v_mfma_f32_16x16x32_bf16 v[64:67], v[178:181], v[212:215], v[64:67]
	v_mfma_f32_16x16x32_bf16 v[116:119], v[174:177], v[192:195], v[116:119]
	v_mfma_f32_16x16x32_bf16 v[104:107], v[184:187], v[192:195], v[104:107]
	v_mfma_f32_16x16x32_bf16 v[100:103], v[174:177], v[200:203], v[100:103]
	v_mfma_f32_16x16x32_bf16 v[88:91], v[184:187], v[200:203], v[88:91]
	v_mfma_f32_16x16x32_bf16 v[84:87], v[174:177], v[208:211], v[84:87]
	v_mfma_f32_16x16x32_bf16 v[72:75], v[184:187], v[208:211], v[72:75]
	v_mfma_f32_16x16x32_bf16 v[68:71], v[174:177], v[216:219], v[68:71]
	v_mfma_f32_16x16x32_bf16 v[64:67], v[184:187], v[216:219], v[64:67]
	s_setprio 0
	s_barrier
	s_add_i32 s57, s50, s93
	v_lshl_add_u64 v[160:161], s[16:17], 0, v[132:133]
	s_mov_b32 m0, s57
	ds_read_b128 v[188:191], v170 offset:16384
	ds_read_b128 v[192:195], v170 offset:17408
	ds_read_b128 v[196:199], v170 offset:18432
	ds_read_b128 v[200:203], v170 offset:19456
	ds_read_b128 v[204:207], v170 offset:20480
	ds_read_b128 v[208:211], v170 offset:21504
	ds_read_b128 v[212:215], v170 offset:22528
	ds_read_b128 v[216:219], v170 offset:23552
	global_load_lds_dwordx4 v[160:161], off
	s_add_i32 m0, s57, 0x2000
	s_add_u32 s58, s16, 0x80000
	v_lshl_add_u64 v[220:221], s[16:17], 0, v[134:135]
	s_addc_u32 s59, s17, 0
	s_add_i32 s57, s51, s93
	global_load_lds_dwordx4 v[220:221], off
	v_lshl_add_u64 v[222:223], s[58:59], 0, v[132:133]
	s_mov_b32 m0, s57
	v_lshl_add_u64 v[224:225], s[36:37], 0, v[134:135]
	global_load_lds_dwordx4 v[222:223], off
	v_lshl_add_u64 v[222:223], s[58:59], 0, v[134:135]
	s_add_i32 m0, s57, 0x2000
	s_nop 0
	global_load_lds_dwordx4 v[222:223], off
	v_lshl_add_u64 v[222:223], s[36:37], 0, v[132:133]
	s_mov_b32 m0, s33
	s_nop 0
	global_load_lds_dwordx4 v[222:223], off
	s_mov_b32 m0, s38
	s_nop 0
	global_load_lds_dwordx4 v[224:225], off
	s_waitcnt vmcnt(8)
	s_waitcnt lgkmcnt(0)
	s_barrier
	s_setprio 1
	v_mfma_f32_16x16x32_bf16 v[60:63], v[128:131], v[188:191], v[60:63]
	v_mfma_f32_16x16x32_bf16 v[56:59], v[148:151], v[188:191], v[56:59]
	v_mfma_f32_16x16x32_bf16 v[48:51], v[128:131], v[196:199], v[48:51]
	v_mfma_f32_16x16x32_bf16 v[44:47], v[148:151], v[196:199], v[44:47]
	v_mfma_f32_16x16x32_bf16 v[32:35], v[128:131], v[204:207], v[32:35]
	v_mfma_f32_16x16x32_bf16 v[28:31], v[148:151], v[204:207], v[28:31]
	v_mfma_f32_16x16x32_bf16 v[16:19], v[128:131], v[212:215], v[16:19]
	v_mfma_f32_16x16x32_bf16 v[12:15], v[148:151], v[212:215], v[12:15]
	v_mfma_f32_16x16x32_bf16 v[60:63], v[144:147], v[192:195], v[60:63]
	v_mfma_f32_16x16x32_bf16 v[56:59], v[152:155], v[192:195], v[56:59]
	v_mfma_f32_16x16x32_bf16 v[48:51], v[144:147], v[200:203], v[48:51]
	v_mfma_f32_16x16x32_bf16 v[44:47], v[152:155], v[200:203], v[44:47]
	v_mfma_f32_16x16x32_bf16 v[32:35], v[144:147], v[208:211], v[32:35]
	v_mfma_f32_16x16x32_bf16 v[28:31], v[152:155], v[208:211], v[28:31]
	v_mfma_f32_16x16x32_bf16 v[16:19], v[144:147], v[216:219], v[16:19]
	v_mfma_f32_16x16x32_bf16 v[12:15], v[152:155], v[216:219], v[12:15]
	v_mfma_f32_16x16x32_bf16 v[52:55], v[156:159], v[188:191], v[52:55]
	v_mfma_f32_16x16x32_bf16 v[40:43], v[178:181], v[188:191], v[40:43]
	v_mfma_f32_16x16x32_bf16 v[36:39], v[156:159], v[196:199], v[36:39]
	v_mfma_f32_16x16x32_bf16 v[24:27], v[178:181], v[196:199], v[24:27]
	v_mfma_f32_16x16x32_bf16 v[20:23], v[156:159], v[204:207], v[20:23]
	v_mfma_f32_16x16x32_bf16 v[8:11], v[178:181], v[204:207], v[8:11]
	v_mfma_f32_16x16x32_bf16 v[4:7], v[156:159], v[212:215], v[4:7]
	v_mfma_f32_16x16x32_bf16 v[0:3], v[178:181], v[212:215], v[0:3]
	v_mfma_f32_16x16x32_bf16 v[52:55], v[174:177], v[192:195], v[52:55]
	v_mfma_f32_16x16x32_bf16 v[40:43], v[184:187], v[192:195], v[40:43]
	v_mfma_f32_16x16x32_bf16 v[36:39], v[174:177], v[200:203], v[36:39]
	v_mfma_f32_16x16x32_bf16 v[24:27], v[184:187], v[200:203], v[24:27]
	v_mfma_f32_16x16x32_bf16 v[20:23], v[174:177], v[208:211], v[20:23]
	v_mfma_f32_16x16x32_bf16 v[8:11], v[184:187], v[208:211], v[8:11]
	v_mfma_f32_16x16x32_bf16 v[4:7], v[174:177], v[216:219], v[4:7]
	v_mfma_f32_16x16x32_bf16 v[0:3], v[184:187], v[216:219], v[0:3]
	s_setprio 0
	s_barrier
	s_add_i32 s57, 0, 0x18000
	s_add_i32 s58, 0, 0x1c000
	v_add_u32_e32 v152, s57, v163
	v_add_u32_e32 v183, s58, v163
	ds_read_b128 v[128:131], v152
	ds_read_b128 v[144:147], v152 offset:1024
	ds_read_b128 v[148:151], v152 offset:2048
	ds_read_b128 v[152:155], v152 offset:3072
	ds_read_b128 v[156:159], v183
	ds_read_b128 v[174:177], v183 offset:1024
	ds_read_b128 v[178:181], v183 offset:2048
	ds_read_b128 v[184:187], v183 offset:3072
	s_add_u32 s36, s36, 0x80000
	s_addc_u32 s37, s37, 0
	s_mov_b32 m0, s39
	v_lshl_add_u64 v[226:227], s[36:37], 0, v[132:133]
	ds_read_b128 v[188:191], v170 offset:32768
	ds_read_b128 v[192:195], v170 offset:33792
	ds_read_b128 v[196:199], v170 offset:34816
	ds_read_b128 v[200:203], v170 offset:35840
	ds_read_b128 v[204:207], v170 offset:36864
	ds_read_b128 v[208:211], v170 offset:37888
	ds_read_b128 v[212:215], v170 offset:38912
	ds_read_b128 v[216:219], v170 offset:39936
	global_load_lds_dwordx4 v[226:227], off
	v_lshl_add_u64 v[226:227], s[36:37], 0, v[134:135]
	s_mov_b32 m0, s40
	s_nop 0
	global_load_lds_dwordx4 v[226:227], off
	s_waitcnt vmcnt(8)
	s_waitcnt lgkmcnt(0)
	s_barrier
	s_setprio 1
	v_mfma_f32_16x16x32_bf16 v[124:127], v[128:131], v[188:191], v[124:127]
	v_mfma_f32_16x16x32_bf16 v[120:123], v[148:151], v[188:191], v[120:123]
	v_mfma_f32_16x16x32_bf16 v[112:115], v[128:131], v[196:199], v[112:115]
	v_mfma_f32_16x16x32_bf16 v[108:111], v[148:151], v[196:199], v[108:111]
	v_mfma_f32_16x16x32_bf16 v[96:99], v[128:131], v[204:207], v[96:99]
	v_mfma_f32_16x16x32_bf16 v[92:95], v[148:151], v[204:207], v[92:95]
	v_mfma_f32_16x16x32_bf16 v[80:83], v[128:131], v[212:215], v[80:83]
	v_mfma_f32_16x16x32_bf16 v[76:79], v[148:151], v[212:215], v[76:79]
	v_mfma_f32_16x16x32_bf16 v[124:127], v[144:147], v[192:195], v[124:127]
	v_mfma_f32_16x16x32_bf16 v[120:123], v[152:155], v[192:195], v[120:123]
	v_mfma_f32_16x16x32_bf16 v[112:115], v[144:147], v[200:203], v[112:115]
	v_mfma_f32_16x16x32_bf16 v[108:111], v[152:155], v[200:203], v[108:111]
	v_mfma_f32_16x16x32_bf16 v[96:99], v[144:147], v[208:211], v[96:99]
	v_mfma_f32_16x16x32_bf16 v[92:95], v[152:155], v[208:211], v[92:95]
	v_mfma_f32_16x16x32_bf16 v[80:83], v[144:147], v[216:219], v[80:83]
	v_mfma_f32_16x16x32_bf16 v[76:79], v[152:155], v[216:219], v[76:79]
	v_mfma_f32_16x16x32_bf16 v[116:119], v[156:159], v[188:191], v[116:119]
	v_mfma_f32_16x16x32_bf16 v[104:107], v[178:181], v[188:191], v[104:107]
	v_mfma_f32_16x16x32_bf16 v[100:103], v[156:159], v[196:199], v[100:103]
	v_mfma_f32_16x16x32_bf16 v[88:91], v[178:181], v[196:199], v[88:91]
	v_mfma_f32_16x16x32_bf16 v[84:87], v[156:159], v[204:207], v[84:87]
	v_mfma_f32_16x16x32_bf16 v[72:75], v[178:181], v[204:207], v[72:75]
	v_mfma_f32_16x16x32_bf16 v[68:71], v[156:159], v[212:215], v[68:71]
	v_mfma_f32_16x16x32_bf16 v[64:67], v[178:181], v[212:215], v[64:67]
	v_mfma_f32_16x16x32_bf16 v[116:119], v[174:177], v[192:195], v[116:119]
	v_mfma_f32_16x16x32_bf16 v[104:107], v[184:187], v[192:195], v[104:107]
	v_mfma_f32_16x16x32_bf16 v[100:103], v[174:177], v[200:203], v[100:103]
	v_mfma_f32_16x16x32_bf16 v[88:91], v[184:187], v[200:203], v[88:91]
	v_mfma_f32_16x16x32_bf16 v[84:87], v[174:177], v[208:211], v[84:87]
	v_mfma_f32_16x16x32_bf16 v[72:75], v[184:187], v[208:211], v[72:75]
	v_mfma_f32_16x16x32_bf16 v[68:71], v[174:177], v[216:219], v[68:71]
	v_mfma_f32_16x16x32_bf16 v[64:67], v[184:187], v[216:219], v[64:67]
	s_setprio 0
	s_barrier
	s_add_i32 s36, s57, s93
	v_lshl_add_u64 v[160:161], v[160:161], 0, s[22:23]
	s_mov_b32 m0, s36
	ds_read_b128 v[188:191], v170 offset:49152
	ds_read_b128 v[192:195], v170 offset:50176
	ds_read_b128 v[196:199], v170 offset:51200
	ds_read_b128 v[200:203], v170 offset:52224
	ds_read_b128 v[204:207], v170 offset:53248
	ds_read_b128 v[208:211], v170 offset:54272
	ds_read_b128 v[212:215], v170 offset:55296
	ds_read_b128 v[216:219], v170 offset:56320
	global_load_lds_dwordx4 v[160:161], off
	s_add_i32 m0, s36, 0x2000
	s_add_u32 s16, s16, 0x80080
	v_lshl_add_u64 v[160:161], v[220:221], 0, s[22:23]
	s_addc_u32 s17, s17, 0
	s_add_i32 s36, s58, s93
	global_load_lds_dwordx4 v[160:161], off
	v_lshl_add_u64 v[160:161], s[16:17], 0, v[132:133]
	s_mov_b32 m0, s36
	s_nop 0
	global_load_lds_dwordx4 v[160:161], off
	v_lshl_add_u64 v[160:161], s[16:17], 0, v[134:135]
	s_add_i32 m0, s36, 0x2000
	s_nop 0
	global_load_lds_dwordx4 v[160:161], off
	v_lshl_add_u64 v[160:161], v[222:223], 0, s[22:23]
	s_mov_b32 m0, s46
	s_nop 0
	global_load_lds_dwordx4 v[160:161], off
	v_lshl_add_u64 v[160:161], v[224:225], 0, s[22:23]
	s_mov_b32 m0, s47
	s_nop 0
	global_load_lds_dwordx4 v[160:161], off
	s_waitcnt vmcnt(8)
	s_waitcnt lgkmcnt(0)
	s_barrier
	s_setprio 1
	v_mfma_f32_16x16x32_bf16 v[60:63], v[128:131], v[188:191], v[60:63]
	v_mfma_f32_16x16x32_bf16 v[56:59], v[148:151], v[188:191], v[56:59]
	v_mfma_f32_16x16x32_bf16 v[48:51], v[128:131], v[196:199], v[48:51]
	v_mfma_f32_16x16x32_bf16 v[44:47], v[148:151], v[196:199], v[44:47]
	v_mfma_f32_16x16x32_bf16 v[32:35], v[128:131], v[204:207], v[32:35]
	v_mfma_f32_16x16x32_bf16 v[28:31], v[148:151], v[204:207], v[28:31]
	v_mfma_f32_16x16x32_bf16 v[16:19], v[128:131], v[212:215], v[16:19]
	v_mfma_f32_16x16x32_bf16 v[12:15], v[148:151], v[212:215], v[12:15]
	v_mfma_f32_16x16x32_bf16 v[60:63], v[144:147], v[192:195], v[60:63]
	v_mfma_f32_16x16x32_bf16 v[56:59], v[152:155], v[192:195], v[56:59]
	v_mfma_f32_16x16x32_bf16 v[48:51], v[144:147], v[200:203], v[48:51]
	v_mfma_f32_16x16x32_bf16 v[44:47], v[152:155], v[200:203], v[44:47]
	v_mfma_f32_16x16x32_bf16 v[32:35], v[144:147], v[208:211], v[32:35]
	v_mfma_f32_16x16x32_bf16 v[28:31], v[152:155], v[208:211], v[28:31]
	v_mfma_f32_16x16x32_bf16 v[16:19], v[144:147], v[216:219], v[16:19]
	v_mfma_f32_16x16x32_bf16 v[12:15], v[152:155], v[216:219], v[12:15]
	v_mfma_f32_16x16x32_bf16 v[52:55], v[156:159], v[188:191], v[52:55]
	v_mfma_f32_16x16x32_bf16 v[40:43], v[178:181], v[188:191], v[40:43]
	v_mfma_f32_16x16x32_bf16 v[36:39], v[156:159], v[196:199], v[36:39]
	v_mfma_f32_16x16x32_bf16 v[24:27], v[178:181], v[196:199], v[24:27]
	v_mfma_f32_16x16x32_bf16 v[20:23], v[156:159], v[204:207], v[20:23]
	v_mfma_f32_16x16x32_bf16 v[8:11], v[178:181], v[204:207], v[8:11]
	v_mfma_f32_16x16x32_bf16 v[4:7], v[156:159], v[212:215], v[4:7]
	v_mfma_f32_16x16x32_bf16 v[0:3], v[178:181], v[212:215], v[0:3]
	v_mfma_f32_16x16x32_bf16 v[52:55], v[174:177], v[192:195], v[52:55]
	v_mfma_f32_16x16x32_bf16 v[40:43], v[184:187], v[192:195], v[40:43]
	v_mfma_f32_16x16x32_bf16 v[36:39], v[174:177], v[200:203], v[36:39]
	v_mfma_f32_16x16x32_bf16 v[24:27], v[184:187], v[200:203], v[24:27]
	v_mfma_f32_16x16x32_bf16 v[20:23], v[174:177], v[208:211], v[20:23]
	v_mfma_f32_16x16x32_bf16 v[8:11], v[184:187], v[208:211], v[8:11]
	v_mfma_f32_16x16x32_bf16 v[4:7], v[174:177], v[216:219], v[4:7]
	v_mfma_f32_16x16x32_bf16 v[0:3], v[184:187], v[216:219], v[0:3]
	s_setprio 0
	s_barrier
	s_add_i32 s56, s56, 2
	s_add_u32 s2, s2, 0x100
	s_addc_u32 s3, s3, 0
	s_add_u32 s54, s54, 0x100
	s_addc_u32 s55, s55, 0
	s_cmp_gt_u32 s56, 29
	s_cbranch_scc0 .LBB0_902
	s_and_b64 vcc, exec, s[24:25]
	s_cbranch_vccz .LBB0_905
	s_barrier

.LBB0_975:
	ds_read_b128 v[116:119], v185
	ds_read_b128 v[120:123], v185 offset:1024
	ds_read_b128 v[124:127], v185 offset:2048
	ds_read_b128 v[132:135], v185 offset:3072
	ds_read_b128 v[166:169], v186
	ds_read_b128 v[170:173], v186 offset:1024
	ds_read_b128 v[174:177], v186 offset:2048
	ds_read_b128 v[178:181], v186 offset:3072
	s_add_u32 s40, s38, 0xfff80080
	s_addc_u32 s41, s39, -1
	s_cmp_eq_u32 s59, 28
	s_cselect_b32 s43, s1, s41
	s_cselect_b32 s42, s3, s40
	s_cselect_b32 s41, s29, s58
	s_cselect_b32 s40, s31, s57
	v_lshl_add_u64 v[224:225], s[38:39], 0, v[156:157]
	s_add_i32 m0, s33, 0xc000
	ds_read_b128 v[192:195], v187
	ds_read_b128 v[196:199], v187 offset:1024
	ds_read_b128 v[200:203], v187 offset:2048
	ds_read_b128 v[204:207], v187 offset:3072
	ds_read_b128 v[208:211], v187 offset:4096
	ds_read_b128 v[212:215], v187 offset:5120
	ds_read_b128 v[216:219], v187 offset:6144
	ds_read_b128 v[220:223], v187 offset:7168
	global_load_lds_dwordx4 v[224:225], off
	v_lshl_add_u64 v[224:225], s[38:39], 0, v[158:159]
	s_add_i32 m0, s33, 0xe000
	s_nop 0
	global_load_lds_dwordx4 v[224:225], off
	s_waitcnt vmcnt(8)
	s_waitcnt lgkmcnt(0)
	s_barrier
	s_setprio 1
	v_mfma_f32_16x16x32_bf16 v[136:139], v[116:119], v[192:195], v[136:139]
	v_mfma_f32_16x16x32_bf16 v[56:59], v[124:127], v[192:195], v[56:59]
	v_mfma_f32_16x16x32_bf16 v[112:115], v[116:119], v[200:203], v[112:115]
	v_mfma_f32_16x16x32_bf16 v[48:51], v[124:127], v[200:203], v[48:51]
	v_mfma_f32_16x16x32_bf16 v[104:107], v[116:119], v[208:211], v[104:107]
	v_mfma_f32_16x16x32_bf16 v[40:43], v[124:127], v[208:211], v[40:43]
	v_mfma_f32_16x16x32_bf16 v[100:103], v[116:119], v[216:219], v[100:103]
	v_mfma_f32_16x16x32_bf16 v[36:39], v[124:127], v[216:219], v[36:39]
	v_mfma_f32_16x16x32_bf16 v[136:139], v[120:123], v[196:199], v[136:139]
	v_mfma_f32_16x16x32_bf16 v[56:59], v[132:135], v[196:199], v[56:59]
	v_mfma_f32_16x16x32_bf16 v[112:115], v[120:123], v[204:207], v[112:115]
	v_mfma_f32_16x16x32_bf16 v[48:51], v[132:135], v[204:207], v[48:51]
	v_mfma_f32_16x16x32_bf16 v[104:107], v[120:123], v[212:215], v[104:107]
	v_mfma_f32_16x16x32_bf16 v[40:43], v[132:135], v[212:215], v[40:43]
	v_mfma_f32_16x16x32_bf16 v[100:103], v[120:123], v[220:223], v[100:103]
	v_mfma_f32_16x16x32_bf16 v[36:39], v[132:135], v[220:223], v[36:39]
	v_mfma_f32_16x16x32_bf16 v[140:143], v[166:169], v[192:195], v[140:143]
	v_mfma_f32_16x16x32_bf16 v[60:63], v[174:177], v[192:195], v[60:63]
	v_mfma_f32_16x16x32_bf16 v[128:131], v[166:169], v[200:203], v[128:131]
	v_mfma_f32_16x16x32_bf16 v[52:55], v[174:177], v[200:203], v[52:55]
	v_mfma_f32_16x16x32_bf16 v[108:111], v[166:169], v[208:211], v[108:111]
	v_mfma_f32_16x16x32_bf16 v[44:47], v[174:177], v[208:211], v[44:47]
	v_mfma_f32_16x16x32_bf16 v[96:99], v[166:169], v[216:219], v[96:99]
	v_mfma_f32_16x16x32_bf16 v[32:35], v[174:177], v[216:219], v[32:35]
	v_mfma_f32_16x16x32_bf16 v[140:143], v[170:173], v[196:199], v[140:143]
	v_mfma_f32_16x16x32_bf16 v[60:63], v[178:181], v[196:199], v[60:63]
	v_mfma_f32_16x16x32_bf16 v[128:131], v[170:173], v[204:207], v[128:131]
	v_mfma_f32_16x16x32_bf16 v[52:55], v[178:181], v[204:207], v[52:55]
	v_mfma_f32_16x16x32_bf16 v[108:111], v[170:173], v[212:215], v[108:111]
	v_mfma_f32_16x16x32_bf16 v[44:47], v[178:181], v[212:215], v[44:47]
	v_mfma_f32_16x16x32_bf16 v[96:99], v[170:173], v[220:223], v[96:99]
	v_mfma_f32_16x16x32_bf16 v[32:35], v[178:181], v[220:223], v[32:35]
	s_setprio 0
	s_barrier
	s_add_i32 s60, s53, s93
	v_lshl_add_u64 v[224:225], s[40:41], 0, v[146:147]
	s_mov_b32 m0, s60
	ds_read_b128 v[192:195], v187 offset:16384
	ds_read_b128 v[196:199], v187 offset:17408
	ds_read_b128 v[200:203], v187 offset:18432
	ds_read_b128 v[204:207], v187 offset:19456
	ds_read_b128 v[208:211], v187 offset:20480
	ds_read_b128 v[212:215], v187 offset:21504
	ds_read_b128 v[216:219], v187 offset:22528
	ds_read_b128 v[220:223], v187 offset:23552
	global_load_lds_dwordx4 v[224:225], off
	s_add_i32 m0, s60, 0x2000
	s_add_u32 s60, s40, 0x80000
	v_lshl_add_u64 v[226:227], s[40:41], 0, v[150:151]
	s_addc_u32 s61, s41, 0
	s_add_i32 s62, s54, s93
	global_load_lds_dwordx4 v[226:227], off
	v_lshl_add_u64 v[228:229], s[60:61], 0, v[146:147]
	s_mov_b32 m0, s62
	v_lshl_add_u64 v[230:231], s[42:43], 0, v[148:149]
	global_load_lds_dwordx4 v[228:229], off
	v_lshl_add_u64 v[228:229], s[60:61], 0, v[150:151]
	s_add_i32 m0, s62, 0x2000
	s_nop 0
	global_load_lds_dwordx4 v[228:229], off
	v_lshl_add_u64 v[228:229], s[42:43], 0, v[144:145]
	s_mov_b32 m0, s33
	s_nop 0
	global_load_lds_dwordx4 v[228:229], off
	s_mov_b32 m0, s44
	s_nop 0
	global_load_lds_dwordx4 v[230:231], off
	s_waitcnt vmcnt(8)
	s_waitcnt lgkmcnt(0)
	s_barrier
	s_setprio 1
	v_mfma_f32_16x16x32_bf16 v[88:91], v[116:119], v[192:195], v[88:91]
	v_mfma_f32_16x16x32_bf16 v[24:27], v[124:127], v[192:195], v[24:27]
	v_mfma_f32_16x16x32_bf16 v[80:83], v[116:119], v[200:203], v[80:83]
	v_mfma_f32_16x16x32_bf16 v[16:19], v[124:127], v[200:203], v[16:19]
	v_mfma_f32_16x16x32_bf16 v[72:75], v[116:119], v[208:211], v[72:75]
	v_mfma_f32_16x16x32_bf16 v[8:11], v[124:127], v[208:211], v[8:11]
	v_mfma_f32_16x16x32_bf16 v[68:71], v[116:119], v[216:219], v[68:71]
	v_mfma_f32_16x16x32_bf16 v[4:7], v[124:127], v[216:219], v[4:7]
	v_mfma_f32_16x16x32_bf16 v[88:91], v[120:123], v[196:199], v[88:91]
	v_mfma_f32_16x16x32_bf16 v[24:27], v[132:135], v[196:199], v[24:27]
	v_mfma_f32_16x16x32_bf16 v[80:83], v[120:123], v[204:207], v[80:83]
	v_mfma_f32_16x16x32_bf16 v[16:19], v[132:135], v[204:207], v[16:19]
	v_mfma_f32_16x16x32_bf16 v[72:75], v[120:123], v[212:215], v[72:75]
	v_mfma_f32_16x16x32_bf16 v[8:11], v[132:135], v[212:215], v[8:11]
	v_mfma_f32_16x16x32_bf16 v[68:71], v[120:123], v[220:223], v[68:71]
	v_mfma_f32_16x16x32_bf16 v[4:7], v[132:135], v[220:223], v[4:7]
	v_mfma_f32_16x16x32_bf16 v[92:95], v[166:169], v[192:195], v[92:95]
	v_mfma_f32_16x16x32_bf16 v[28:31], v[174:177], v[192:195], v[28:31]
	v_mfma_f32_16x16x32_bf16 v[84:87], v[166:169], v[200:203], v[84:87]
	v_mfma_f32_16x16x32_bf16 v[20:23], v[174:177], v[200:203], v[20:23]
	v_mfma_f32_16x16x32_bf16 v[76:79], v[166:169], v[208:211], v[76:79]
	v_mfma_f32_16x16x32_bf16 v[12:15], v[174:177], v[208:211], v[12:15]
	v_mfma_f32_16x16x32_bf16 v[64:67], v[166:169], v[216:219], v[64:67]
	v_mfma_f32_16x16x32_bf16 v[0:3], v[174:177], v[216:219], v[0:3]
	v_mfma_f32_16x16x32_bf16 v[92:95], v[170:173], v[196:199], v[92:95]
	v_mfma_f32_16x16x32_bf16 v[28:31], v[178:181], v[196:199], v[28:31]
	v_mfma_f32_16x16x32_bf16 v[84:87], v[170:173], v[204:207], v[84:87]
	v_mfma_f32_16x16x32_bf16 v[20:23], v[178:181], v[204:207], v[20:23]
	v_mfma_f32_16x16x32_bf16 v[76:79], v[170:173], v[212:215], v[76:79]
	v_mfma_f32_16x16x32_bf16 v[12:15], v[178:181], v[212:215], v[12:15]
	v_mfma_f32_16x16x32_bf16 v[64:67], v[170:173], v[220:223], v[64:67]
	v_mfma_f32_16x16x32_bf16 v[0:3], v[178:181], v[220:223], v[0:3]
	s_setprio 0
	s_barrier
	s_add_i32 s60, 0, 0x18000
	s_add_i32 s61, 0, 0x1c000
	v_add_u32_e32 v132, s60, v183
	v_add_u32_e32 v178, s61, v183
	ds_read_b128 v[116:119], v132
	ds_read_b128 v[120:123], v132 offset:1024
	ds_read_b128 v[124:127], v132 offset:2048
	ds_read_b128 v[132:135], v132 offset:3072
	ds_read_b128 v[166:169], v178
	ds_read_b128 v[170:173], v178 offset:1024
	ds_read_b128 v[174:177], v178 offset:2048
	ds_read_b128 v[178:181], v178 offset:3072
	s_add_u32 s42, s42, 0x80000
	s_addc_u32 s43, s43, 0
	s_mov_b32 m0, s45
	v_lshl_add_u64 v[232:233], s[42:43], 0, v[144:145]
	ds_read_b128 v[192:195], v187 offset:32768
	ds_read_b128 v[196:199], v187 offset:33792
	ds_read_b128 v[200:203], v187 offset:34816
	ds_read_b128 v[204:207], v187 offset:35840
	ds_read_b128 v[208:211], v187 offset:36864
	ds_read_b128 v[212:215], v187 offset:37888
	ds_read_b128 v[216:219], v187 offset:38912
	ds_read_b128 v[220:223], v187 offset:39936
	global_load_lds_dwordx4 v[232:233], off
	v_lshl_add_u64 v[232:233], s[42:43], 0, v[148:149]
	s_mov_b32 m0, s46
	s_nop 0
	global_load_lds_dwordx4 v[232:233], off
	s_waitcnt vmcnt(8)
	s_waitcnt lgkmcnt(0)
	s_barrier
	s_setprio 1
	v_mfma_f32_16x16x32_bf16 v[136:139], v[116:119], v[192:195], v[136:139]
	v_mfma_f32_16x16x32_bf16 v[56:59], v[124:127], v[192:195], v[56:59]
	v_mfma_f32_16x16x32_bf16 v[112:115], v[116:119], v[200:203], v[112:115]
	v_mfma_f32_16x16x32_bf16 v[48:51], v[124:127], v[200:203], v[48:51]
	v_mfma_f32_16x16x32_bf16 v[104:107], v[116:119], v[208:211], v[104:107]
	v_mfma_f32_16x16x32_bf16 v[40:43], v[124:127], v[208:211], v[40:43]
	v_mfma_f32_16x16x32_bf16 v[100:103], v[116:119], v[216:219], v[100:103]
	v_mfma_f32_16x16x32_bf16 v[36:39], v[124:127], v[216:219], v[36:39]
	v_mfma_f32_16x16x32_bf16 v[136:139], v[120:123], v[196:199], v[136:139]
	v_mfma_f32_16x16x32_bf16 v[56:59], v[132:135], v[196:199], v[56:59]
	v_mfma_f32_16x16x32_bf16 v[112:115], v[120:123], v[204:207], v[112:115]
	v_mfma_f32_16x16x32_bf16 v[48:51], v[132:135], v[204:207], v[48:51]
	v_mfma_f32_16x16x32_bf16 v[104:107], v[120:123], v[212:215], v[104:107]
	v_mfma_f32_16x16x32_bf16 v[40:43], v[132:135], v[212:215], v[40:43]
	v_mfma_f32_16x16x32_bf16 v[100:103], v[120:123], v[220:223], v[100:103]
	v_mfma_f32_16x16x32_bf16 v[36:39], v[132:135], v[220:223], v[36:39]
	v_mfma_f32_16x16x32_bf16 v[140:143], v[166:169], v[192:195], v[140:143]
	v_mfma_f32_16x16x32_bf16 v[60:63], v[174:177], v[192:195], v[60:63]
	v_mfma_f32_16x16x32_bf16 v[128:131], v[166:169], v[200:203], v[128:131]
	v_mfma_f32_16x16x32_bf16 v[52:55], v[174:177], v[200:203], v[52:55]
	v_mfma_f32_16x16x32_bf16 v[108:111], v[166:169], v[208:211], v[108:111]
	v_mfma_f32_16x16x32_bf16 v[44:47], v[174:177], v[208:211], v[44:47]
	v_mfma_f32_16x16x32_bf16 v[96:99], v[166:169], v[216:219], v[96:99]
	v_mfma_f32_16x16x32_bf16 v[32:35], v[174:177], v[216:219], v[32:35]
	v_mfma_f32_16x16x32_bf16 v[140:143], v[170:173], v[196:199], v[140:143]
	v_mfma_f32_16x16x32_bf16 v[60:63], v[178:181], v[196:199], v[60:63]
	v_mfma_f32_16x16x32_bf16 v[128:131], v[170:173], v[204:207], v[128:131]
	v_mfma_f32_16x16x32_bf16 v[52:55], v[178:181], v[204:207], v[52:55]
	v_mfma_f32_16x16x32_bf16 v[108:111], v[170:173], v[212:215], v[108:111]
	v_mfma_f32_16x16x32_bf16 v[44:47], v[178:181], v[212:215], v[44:47]
	v_mfma_f32_16x16x32_bf16 v[96:99], v[170:173], v[220:223], v[96:99]
	v_mfma_f32_16x16x32_bf16 v[32:35], v[178:181], v[220:223], v[32:35]
	s_setprio 0
	s_barrier
	s_add_i32 s42, s60, s93
	v_lshl_add_u64 v[224:225], v[224:225], 0, s[20:21]
	s_mov_b32 m0, s42
	ds_read_b128 v[192:195], v187 offset:49152
	ds_read_b128 v[196:199], v187 offset:50176
	ds_read_b128 v[200:203], v187 offset:51200
	ds_read_b128 v[204:207], v187 offset:52224
	ds_read_b128 v[208:211], v187 offset:53248
	ds_read_b128 v[212:215], v187 offset:54272
	ds_read_b128 v[216:219], v187 offset:55296
	ds_read_b128 v[220:223], v187 offset:56320
	global_load_lds_dwordx4 v[224:225], off
	s_add_i32 m0, s42, 0x2000
	s_add_u32 s40, s40, 0x80080
	v_lshl_add_u64 v[224:225], v[226:227], 0, s[20:21]
	s_addc_u32 s41, s41, 0
	s_add_i32 s42, s61, s93
	global_load_lds_dwordx4 v[224:225], off
	v_lshl_add_u64 v[224:225], s[40:41], 0, v[146:147]
	s_mov_b32 m0, s42
	s_nop 0
	global_load_lds_dwordx4 v[224:225], off
	v_lshl_add_u64 v[224:225], s[40:41], 0, v[150:151]
	s_add_i32 m0, s42, 0x2000
	s_nop 0
	global_load_lds_dwordx4 v[224:225], off
	v_lshl_add_u64 v[224:225], v[228:229], 0, s[20:21]
	s_mov_b32 m0, s48
	s_nop 0
	global_load_lds_dwordx4 v[224:225], off
	v_lshl_add_u64 v[224:225], v[230:231], 0, s[20:21]
	s_mov_b32 m0, s49
	s_nop 0
	global_load_lds_dwordx4 v[224:225], off
	s_waitcnt vmcnt(8)
	s_waitcnt lgkmcnt(0)
	s_barrier
	s_setprio 1
	v_mfma_f32_16x16x32_bf16 v[88:91], v[116:119], v[192:195], v[88:91]
	v_mfma_f32_16x16x32_bf16 v[24:27], v[124:127], v[192:195], v[24:27]
	v_mfma_f32_16x16x32_bf16 v[80:83], v[116:119], v[200:203], v[80:83]
	v_mfma_f32_16x16x32_bf16 v[16:19], v[124:127], v[200:203], v[16:19]
	v_mfma_f32_16x16x32_bf16 v[72:75], v[116:119], v[208:211], v[72:75]
	v_mfma_f32_16x16x32_bf16 v[8:11], v[124:127], v[208:211], v[8:11]
	v_mfma_f32_16x16x32_bf16 v[68:71], v[116:119], v[216:219], v[68:71]
	v_mfma_f32_16x16x32_bf16 v[4:7], v[124:127], v[216:219], v[4:7]
	v_mfma_f32_16x16x32_bf16 v[88:91], v[120:123], v[196:199], v[88:91]
	v_mfma_f32_16x16x32_bf16 v[24:27], v[132:135], v[196:199], v[24:27]
	v_mfma_f32_16x16x32_bf16 v[80:83], v[120:123], v[204:207], v[80:83]
	v_mfma_f32_16x16x32_bf16 v[16:19], v[132:135], v[204:207], v[16:19]
	v_mfma_f32_16x16x32_bf16 v[72:75], v[120:123], v[212:215], v[72:75]
	v_mfma_f32_16x16x32_bf16 v[8:11], v[132:135], v[212:215], v[8:11]
	v_mfma_f32_16x16x32_bf16 v[68:71], v[120:123], v[220:223], v[68:71]
	v_mfma_f32_16x16x32_bf16 v[4:7], v[132:135], v[220:223], v[4:7]
	v_mfma_f32_16x16x32_bf16 v[92:95], v[166:169], v[192:195], v[92:95]
	v_mfma_f32_16x16x32_bf16 v[28:31], v[174:177], v[192:195], v[28:31]
	v_mfma_f32_16x16x32_bf16 v[84:87], v[166:169], v[200:203], v[84:87]
	v_mfma_f32_16x16x32_bf16 v[20:23], v[174:177], v[200:203], v[20:23]
	v_mfma_f32_16x16x32_bf16 v[76:79], v[166:169], v[208:211], v[76:79]
	v_mfma_f32_16x16x32_bf16 v[12:15], v[174:177], v[208:211], v[12:15]
	v_mfma_f32_16x16x32_bf16 v[64:67], v[166:169], v[216:219], v[64:67]
	v_mfma_f32_16x16x32_bf16 v[0:3], v[174:177], v[216:219], v[0:3]
	v_mfma_f32_16x16x32_bf16 v[92:95], v[170:173], v[196:199], v[92:95]
	v_mfma_f32_16x16x32_bf16 v[28:31], v[178:181], v[196:199], v[28:31]
	v_mfma_f32_16x16x32_bf16 v[84:87], v[170:173], v[204:207], v[84:87]
	v_mfma_f32_16x16x32_bf16 v[20:23], v[178:181], v[204:207], v[20:23]
	v_mfma_f32_16x16x32_bf16 v[76:79], v[170:173], v[212:215], v[76:79]
	v_mfma_f32_16x16x32_bf16 v[12:15], v[178:181], v[212:215], v[12:15]
	v_mfma_f32_16x16x32_bf16 v[64:67], v[170:173], v[220:223], v[64:67]
	v_mfma_f32_16x16x32_bf16 v[0:3], v[178:181], v[220:223], v[0:3]
	s_setprio 0
	s_barrier
	s_add_i32 s59, s59, 2
	s_add_u32 s38, s38, 0x100
	s_addc_u32 s39, s39, 0
	s_add_u32 s57, s57, 0x100
	s_addc_u32 s58, s58, 0
	s_cmp_gt_u32 s59, 29
	s_cbranch_scc0 .LBB0_975
	s_and_b64 vcc, exec, s[22:23]
	s_cbranch_vccz .LBB0_978
	s_barrier

.LBB0_1051:
	ds_read_b128 v[140:143], v167
	ds_read_b128 v[144:147], v167 offset:1024
	ds_read_b128 v[148:151], v167 offset:2048
	ds_read_b128 v[152:155], v167 offset:3072
	ds_read_b128 v[156:159], v168
	ds_read_b128 v[174:177], v168 offset:1024
	ds_read_b128 v[178:181], v168 offset:2048
	ds_read_b128 v[184:187], v168 offset:3072
	s_add_u32 s12, s2, 0x100
	s_addc_u32 s13, s3, 0
	s_cmpk_eq_i32 s62, 0x54
	s_cselect_b32 s39, s35, s13
	s_cselect_b32 s38, s34, s12
	s_cselect_b32 s15, s37, s61
	s_cselect_b32 s14, s36, s1
	v_lshl_add_u64 v[220:221], s[2:3], 0, v[132:133]
	s_add_i32 m0, s33, 0xc000
	ds_read_b128 v[188:191], v169
	ds_read_b128 v[192:195], v169 offset:1024
	ds_read_b128 v[196:199], v169 offset:2048
	ds_read_b128 v[200:203], v169 offset:3072
	ds_read_b128 v[204:207], v169 offset:4096
	ds_read_b128 v[208:211], v169 offset:5120
	ds_read_b128 v[212:215], v169 offset:6144
	ds_read_b128 v[216:219], v169 offset:7168
	global_load_lds_dwordx4 v[220:221], off
	v_lshl_add_u64 v[220:221], s[2:3], 0, v[134:135]
	s_add_i32 m0, s33, 0xe000
	s_nop 0
	global_load_lds_dwordx4 v[220:221], off
	s_waitcnt vmcnt(8)
	s_waitcnt lgkmcnt(0)
	s_barrier
	s_setprio 1
	v_mfma_f32_16x16x32_bf16 v[124:127], v[140:143], v[188:191], v[124:127]
	v_mfma_f32_16x16x32_bf16 v[120:123], v[148:151], v[188:191], v[120:123]
	v_mfma_f32_16x16x32_bf16 v[116:119], v[140:143], v[196:199], v[116:119]
	v_mfma_f32_16x16x32_bf16 v[104:107], v[148:151], v[196:199], v[104:107]
	v_mfma_f32_16x16x32_bf16 v[112:115], v[140:143], v[204:207], v[112:115]
	v_mfma_f32_16x16x32_bf16 v[100:103], v[148:151], v[204:207], v[100:103]
	v_mfma_f32_16x16x32_bf16 v[96:99], v[140:143], v[212:215], v[96:99]
	v_mfma_f32_16x16x32_bf16 v[76:79], v[148:151], v[212:215], v[76:79]
	v_mfma_f32_16x16x32_bf16 v[124:127], v[144:147], v[192:195], v[124:127]
	v_mfma_f32_16x16x32_bf16 v[120:123], v[152:155], v[192:195], v[120:123]
	v_mfma_f32_16x16x32_bf16 v[116:119], v[144:147], v[200:203], v[116:119]
	v_mfma_f32_16x16x32_bf16 v[104:107], v[152:155], v[200:203], v[104:107]
	v_mfma_f32_16x16x32_bf16 v[112:115], v[144:147], v[208:211], v[112:115]
	v_mfma_f32_16x16x32_bf16 v[100:103], v[152:155], v[208:211], v[100:103]
	v_mfma_f32_16x16x32_bf16 v[96:99], v[144:147], v[216:219], v[96:99]
	v_mfma_f32_16x16x32_bf16 v[76:79], v[152:155], v[216:219], v[76:79]
	v_mfma_f32_16x16x32_bf16 v[108:111], v[156:159], v[188:191], v[108:111]
	v_mfma_f32_16x16x32_bf16 v[92:95], v[178:181], v[188:191], v[92:95]
	v_mfma_f32_16x16x32_bf16 v[88:91], v[156:159], v[196:199], v[88:91]
	v_mfma_f32_16x16x32_bf16 v[72:75], v[178:181], v[196:199], v[72:75]
	v_mfma_f32_16x16x32_bf16 v[80:83], v[156:159], v[204:207], v[80:83]
	v_mfma_f32_16x16x32_bf16 v[64:67], v[178:181], v[204:207], v[64:67]
	v_mfma_f32_16x16x32_bf16 v[60:63], v[156:159], v[212:215], v[60:63]
	v_mfma_f32_16x16x32_bf16 v[56:59], v[178:181], v[212:215], v[56:59]
	v_mfma_f32_16x16x32_bf16 v[108:111], v[174:177], v[192:195], v[108:111]
	v_mfma_f32_16x16x32_bf16 v[92:95], v[184:187], v[192:195], v[92:95]
	v_mfma_f32_16x16x32_bf16 v[88:91], v[174:177], v[200:203], v[88:91]
	v_mfma_f32_16x16x32_bf16 v[72:75], v[184:187], v[200:203], v[72:75]
	v_mfma_f32_16x16x32_bf16 v[80:83], v[174:177], v[208:211], v[80:83]
	v_mfma_f32_16x16x32_bf16 v[64:67], v[184:187], v[208:211], v[64:67]
	v_mfma_f32_16x16x32_bf16 v[60:63], v[174:177], v[216:219], v[60:63]
	v_mfma_f32_16x16x32_bf16 v[56:59], v[184:187], v[216:219], v[56:59]
	s_setprio 0
	s_barrier
	s_add_i32 s2, s50, s93
	v_lshl_add_u64 v[220:221], s[14:15], 0, v[128:129]
	s_mov_b32 m0, s2
	ds_read_b128 v[188:191], v169 offset:16384
	ds_read_b128 v[192:195], v169 offset:17408
	ds_read_b128 v[196:199], v169 offset:18432
	ds_read_b128 v[200:203], v169 offset:19456
	ds_read_b128 v[204:207], v169 offset:20480
	ds_read_b128 v[208:211], v169 offset:21504
	ds_read_b128 v[212:215], v169 offset:22528
	ds_read_b128 v[216:219], v169 offset:23552
	global_load_lds_dwordx4 v[220:221], off
	s_add_i32 m0, s2, 0x2000
	s_add_u32 s2, s14, 0x160000
	v_lshl_add_u64 v[222:223], s[14:15], 0, v[130:131]
	s_addc_u32 s3, s15, 0
	s_add_i32 s63, s51, s93
	global_load_lds_dwordx4 v[222:223], off
	v_lshl_add_u64 v[224:225], s[2:3], 0, v[128:129]
	s_mov_b32 m0, s63
	v_lshl_add_u64 v[226:227], s[38:39], 0, v[130:131]
	global_load_lds_dwordx4 v[224:225], off
	v_lshl_add_u64 v[224:225], s[2:3], 0, v[130:131]
	s_add_i32 m0, s63, 0x2000
	s_nop 0
	global_load_lds_dwordx4 v[224:225], off
	v_lshl_add_u64 v[224:225], s[38:39], 0, v[128:129]
	s_mov_b32 m0, s33
	s_nop 0
	global_load_lds_dwordx4 v[224:225], off
	s_mov_b32 m0, s40
	s_nop 0
	global_load_lds_dwordx4 v[226:227], off
	s_waitcnt vmcnt(8)
	s_waitcnt lgkmcnt(0)
	s_barrier
	s_setprio 1
	v_mfma_f32_16x16x32_bf16 v[84:87], v[140:143], v[188:191], v[84:87]
	v_mfma_f32_16x16x32_bf16 v[68:71], v[148:151], v[188:191], v[68:71]
	v_mfma_f32_16x16x32_bf16 v[44:47], v[140:143], v[196:199], v[44:47]
	v_mfma_f32_16x16x32_bf16 v[40:43], v[148:151], v[196:199], v[40:43]
	v_mfma_f32_16x16x32_bf16 v[28:31], v[140:143], v[204:207], v[28:31]
	v_mfma_f32_16x16x32_bf16 v[24:27], v[148:151], v[204:207], v[24:27]
	v_mfma_f32_16x16x32_bf16 v[12:15], v[140:143], v[212:215], v[12:15]
	v_mfma_f32_16x16x32_bf16 v[8:11], v[148:151], v[212:215], v[8:11]
	v_mfma_f32_16x16x32_bf16 v[84:87], v[144:147], v[192:195], v[84:87]
	v_mfma_f32_16x16x32_bf16 v[68:71], v[152:155], v[192:195], v[68:71]
	v_mfma_f32_16x16x32_bf16 v[44:47], v[144:147], v[200:203], v[44:47]
	v_mfma_f32_16x16x32_bf16 v[40:43], v[152:155], v[200:203], v[40:43]
	v_mfma_f32_16x16x32_bf16 v[28:31], v[144:147], v[208:211], v[28:31]
	v_mfma_f32_16x16x32_bf16 v[24:27], v[152:155], v[208:211], v[24:27]
	v_mfma_f32_16x16x32_bf16 v[12:15], v[144:147], v[216:219], v[12:15]
	v_mfma_f32_16x16x32_bf16 v[8:11], v[152:155], v[216:219], v[8:11]
	v_mfma_f32_16x16x32_bf16 v[52:55], v[156:159], v[188:191], v[52:55]
	v_mfma_f32_16x16x32_bf16 v[48:51], v[178:181], v[188:191], v[48:51]
	v_mfma_f32_16x16x32_bf16 v[36:39], v[156:159], v[196:199], v[36:39]
	v_mfma_f32_16x16x32_bf16 v[32:35], v[178:181], v[196:199], v[32:35]
	v_mfma_f32_16x16x32_bf16 v[20:23], v[156:159], v[204:207], v[20:23]
	v_mfma_f32_16x16x32_bf16 v[16:19], v[178:181], v[204:207], v[16:19]
	v_mfma_f32_16x16x32_bf16 v[4:7], v[156:159], v[212:215], v[4:7]
	v_mfma_f32_16x16x32_bf16 v[0:3], v[178:181], v[212:215], v[0:3]
	v_mfma_f32_16x16x32_bf16 v[52:55], v[174:177], v[192:195], v[52:55]
	v_mfma_f32_16x16x32_bf16 v[48:51], v[184:187], v[192:195], v[48:51]
	v_mfma_f32_16x16x32_bf16 v[36:39], v[174:177], v[200:203], v[36:39]
	v_mfma_f32_16x16x32_bf16 v[32:35], v[184:187], v[200:203], v[32:35]
	v_mfma_f32_16x16x32_bf16 v[20:23], v[174:177], v[208:211], v[20:23]
	v_mfma_f32_16x16x32_bf16 v[16:19], v[184:187], v[208:211], v[16:19]
	v_mfma_f32_16x16x32_bf16 v[4:7], v[174:177], v[216:219], v[4:7]
	v_mfma_f32_16x16x32_bf16 v[0:3], v[184:187], v[216:219], v[0:3]
	s_setprio 0
	s_barrier
	s_add_i32 s63, 0, 0x18000
	s_add_i32 s64, 0, 0x1c000
	v_add_u32_e32 v152, s63, v162
	v_add_u32_e32 v160, s64, v162
	ds_read_b128 v[140:143], v152
	ds_read_b128 v[144:147], v152 offset:1024
	ds_read_b128 v[148:151], v152 offset:2048
	ds_read_b128 v[152:155], v152 offset:3072
	ds_read_b128 v[156:159], v160
	ds_read_b128 v[174:177], v160 offset:1024
	ds_read_b128 v[178:181], v160 offset:2048
	ds_read_b128 v[184:187], v160 offset:3072
	s_add_u32 s2, s38, 0x160000
	s_addc_u32 s3, s39, 0
	s_mov_b32 m0, s41
	v_lshl_add_u64 v[228:229], s[2:3], 0, v[128:129]
	ds_read_b128 v[188:191], v169 offset:32768
	ds_read_b128 v[192:195], v169 offset:33792
	ds_read_b128 v[196:199], v169 offset:34816
	ds_read_b128 v[200:203], v169 offset:35840
	ds_read_b128 v[204:207], v169 offset:36864
	ds_read_b128 v[208:211], v169 offset:37888
	ds_read_b128 v[212:215], v169 offset:38912
	ds_read_b128 v[216:219], v169 offset:39936
	global_load_lds_dwordx4 v[228:229], off
	v_lshl_add_u64 v[228:229], s[2:3], 0, v[130:131]
	s_mov_b32 m0, s42
	s_nop 0
	global_load_lds_dwordx4 v[228:229], off
	s_waitcnt vmcnt(8)
	s_waitcnt lgkmcnt(0)
	s_barrier
	s_setprio 1
	v_mfma_f32_16x16x32_bf16 v[124:127], v[140:143], v[188:191], v[124:127]
	v_mfma_f32_16x16x32_bf16 v[120:123], v[148:151], v[188:191], v[120:123]
	v_mfma_f32_16x16x32_bf16 v[116:119], v[140:143], v[196:199], v[116:119]
	v_mfma_f32_16x16x32_bf16 v[104:107], v[148:151], v[196:199], v[104:107]
	v_mfma_f32_16x16x32_bf16 v[112:115], v[140:143], v[204:207], v[112:115]
	v_mfma_f32_16x16x32_bf16 v[100:103], v[148:151], v[204:207], v[100:103]
	v_mfma_f32_16x16x32_bf16 v[96:99], v[140:143], v[212:215], v[96:99]
	v_mfma_f32_16x16x32_bf16 v[76:79], v[148:151], v[212:215], v[76:79]
	v_mfma_f32_16x16x32_bf16 v[124:127], v[144:147], v[192:195], v[124:127]
	v_mfma_f32_16x16x32_bf16 v[120:123], v[152:155], v[192:195], v[120:123]
	v_mfma_f32_16x16x32_bf16 v[116:119], v[144:147], v[200:203], v[116:119]
	v_mfma_f32_16x16x32_bf16 v[104:107], v[152:155], v[200:203], v[104:107]
	v_mfma_f32_16x16x32_bf16 v[112:115], v[144:147], v[208:211], v[112:115]
	v_mfma_f32_16x16x32_bf16 v[100:103], v[152:155], v[208:211], v[100:103]
	v_mfma_f32_16x16x32_bf16 v[96:99], v[144:147], v[216:219], v[96:99]
	v_mfma_f32_16x16x32_bf16 v[76:79], v[152:155], v[216:219], v[76:79]
	v_mfma_f32_16x16x32_bf16 v[108:111], v[156:159], v[188:191], v[108:111]
	v_mfma_f32_16x16x32_bf16 v[92:95], v[178:181], v[188:191], v[92:95]
	v_mfma_f32_16x16x32_bf16 v[88:91], v[156:159], v[196:199], v[88:91]
	v_mfma_f32_16x16x32_bf16 v[72:75], v[178:181], v[196:199], v[72:75]
	v_mfma_f32_16x16x32_bf16 v[80:83], v[156:159], v[204:207], v[80:83]
	v_mfma_f32_16x16x32_bf16 v[64:67], v[178:181], v[204:207], v[64:67]
	v_mfma_f32_16x16x32_bf16 v[60:63], v[156:159], v[212:215], v[60:63]
	v_mfma_f32_16x16x32_bf16 v[56:59], v[178:181], v[212:215], v[56:59]
	v_mfma_f32_16x16x32_bf16 v[108:111], v[174:177], v[192:195], v[108:111]
	v_mfma_f32_16x16x32_bf16 v[92:95], v[184:187], v[192:195], v[92:95]
	v_mfma_f32_16x16x32_bf16 v[88:91], v[174:177], v[200:203], v[88:91]
	v_mfma_f32_16x16x32_bf16 v[72:75], v[184:187], v[200:203], v[72:75]
	v_mfma_f32_16x16x32_bf16 v[80:83], v[174:177], v[208:211], v[80:83]
	v_mfma_f32_16x16x32_bf16 v[64:67], v[184:187], v[208:211], v[64:67]
	v_mfma_f32_16x16x32_bf16 v[60:63], v[174:177], v[216:219], v[60:63]
	v_mfma_f32_16x16x32_bf16 v[56:59], v[184:187], v[216:219], v[56:59]
	s_setprio 0
	s_barrier
	s_add_i32 s2, s63, s93
	v_lshl_add_u64 v[220:221], v[220:221], 0, s[22:23]
	s_mov_b32 m0, s2
	ds_read_b128 v[188:191], v169 offset:49152
	ds_read_b128 v[192:195], v169 offset:50176
	ds_read_b128 v[196:199], v169 offset:51200
	ds_read_b128 v[200:203], v169 offset:52224
	ds_read_b128 v[204:207], v169 offset:53248
	ds_read_b128 v[208:211], v169 offset:54272
	ds_read_b128 v[212:215], v169 offset:55296
	ds_read_b128 v[216:219], v169 offset:56320
	global_load_lds_dwordx4 v[220:221], off
	s_add_i32 m0, s2, 0x2000
	s_add_u32 s2, s14, 0x160080
	v_lshl_add_u64 v[220:221], v[222:223], 0, s[22:23]
	s_addc_u32 s3, s15, 0
	s_add_i32 s14, s64, s93
	global_load_lds_dwordx4 v[220:221], off
	v_lshl_add_u64 v[220:221], s[2:3], 0, v[128:129]
	s_mov_b32 m0, s14
	s_nop 0
	global_load_lds_dwordx4 v[220:221], off
	v_lshl_add_u64 v[220:221], s[2:3], 0, v[130:131]
	s_add_i32 m0, s14, 0x2000
	s_nop 0
	global_load_lds_dwordx4 v[220:221], off
	v_lshl_add_u64 v[220:221], v[224:225], 0, s[22:23]
	s_mov_b32 m0, s46
	s_nop 0
	global_load_lds_dwordx4 v[220:221], off
	v_lshl_add_u64 v[220:221], v[226:227], 0, s[22:23]
	s_mov_b32 m0, s47
	s_nop 0
	global_load_lds_dwordx4 v[220:221], off
	s_waitcnt vmcnt(8)
	s_waitcnt lgkmcnt(0)
	s_barrier
	s_setprio 1
	v_mfma_f32_16x16x32_bf16 v[84:87], v[140:143], v[188:191], v[84:87]
	v_mfma_f32_16x16x32_bf16 v[68:71], v[148:151], v[188:191], v[68:71]
	v_mfma_f32_16x16x32_bf16 v[44:47], v[140:143], v[196:199], v[44:47]
	v_mfma_f32_16x16x32_bf16 v[40:43], v[148:151], v[196:199], v[40:43]
	v_mfma_f32_16x16x32_bf16 v[28:31], v[140:143], v[204:207], v[28:31]
	v_mfma_f32_16x16x32_bf16 v[24:27], v[148:151], v[204:207], v[24:27]
	v_mfma_f32_16x16x32_bf16 v[12:15], v[140:143], v[212:215], v[12:15]
	v_mfma_f32_16x16x32_bf16 v[8:11], v[148:151], v[212:215], v[8:11]
	v_mfma_f32_16x16x32_bf16 v[84:87], v[144:147], v[192:195], v[84:87]
	v_mfma_f32_16x16x32_bf16 v[68:71], v[152:155], v[192:195], v[68:71]
	v_mfma_f32_16x16x32_bf16 v[44:47], v[144:147], v[200:203], v[44:47]
	v_mfma_f32_16x16x32_bf16 v[40:43], v[152:155], v[200:203], v[40:43]
	v_mfma_f32_16x16x32_bf16 v[28:31], v[144:147], v[208:211], v[28:31]
	v_mfma_f32_16x16x32_bf16 v[24:27], v[152:155], v[208:211], v[24:27]
	v_mfma_f32_16x16x32_bf16 v[12:15], v[144:147], v[216:219], v[12:15]
	v_mfma_f32_16x16x32_bf16 v[8:11], v[152:155], v[216:219], v[8:11]
	v_mfma_f32_16x16x32_bf16 v[52:55], v[156:159], v[188:191], v[52:55]
	v_mfma_f32_16x16x32_bf16 v[48:51], v[178:181], v[188:191], v[48:51]
	v_mfma_f32_16x16x32_bf16 v[36:39], v[156:159], v[196:199], v[36:39]
	v_mfma_f32_16x16x32_bf16 v[32:35], v[178:181], v[196:199], v[32:35]
	v_mfma_f32_16x16x32_bf16 v[20:23], v[156:159], v[204:207], v[20:23]
	v_mfma_f32_16x16x32_bf16 v[16:19], v[178:181], v[204:207], v[16:19]
	v_mfma_f32_16x16x32_bf16 v[4:7], v[156:159], v[212:215], v[4:7]
	v_mfma_f32_16x16x32_bf16 v[0:3], v[178:181], v[212:215], v[0:3]
	v_mfma_f32_16x16x32_bf16 v[52:55], v[174:177], v[192:195], v[52:55]
	v_mfma_f32_16x16x32_bf16 v[48:51], v[184:187], v[192:195], v[48:51]
	v_mfma_f32_16x16x32_bf16 v[36:39], v[174:177], v[200:203], v[36:39]
	v_mfma_f32_16x16x32_bf16 v[32:35], v[184:187], v[200:203], v[32:35]
	v_mfma_f32_16x16x32_bf16 v[20:23], v[174:177], v[208:211], v[20:23]
	v_mfma_f32_16x16x32_bf16 v[16:19], v[184:187], v[208:211], v[16:19]
	v_mfma_f32_16x16x32_bf16 v[4:7], v[174:177], v[216:219], v[4:7]
	v_mfma_f32_16x16x32_bf16 v[0:3], v[184:187], v[216:219], v[0:3]
	s_setprio 0
	s_barrier
	s_add_i32 s62, s62, 2
	s_add_u32 s1, s1, 0x100
	s_addc_u32 s61, s61, 0
	s_cmpk_gt_u32 s62, 0x55
	s_mov_b64 s[2:3], s[12:13]
	s_cbranch_scc0 .LBB0_1051
	s_and_b64 vcc, exec, s[24:25]
	s_cbranch_vccz .LBB0_1054
	s_barrier
